# removed mid-phase s_setprio 0/1 pairs between the two 16-MFMA groups in all GEMM K-loops
# speedup vs baseline: 1.0105x; 1.0061x over previous
.LBB0_111:
	s_add_u32 s28, s26, 0xfffc0080
	s_addc_u32 s29, s27, -1
	s_add_i32 s57, 0, 0x10000
	s_cmp_eq_u32 s56, 12
	s_cselect_b32 s31, s19, s29
	s_cselect_b32 s30, s52, s28
	v_add_u32_e32 v150, s57, v1
	s_cselect_b32 s29, s17, s55
	s_cselect_b32 s28, s53, s54
	s_add_i32 s60, 0, 0x14000
	ds_read_b128 v[142:145], v150
	ds_read_b128 v[146:149], v150 offset:1024
	ds_read_b128 v[154:157], v150 offset:2048
	ds_read_b128 v[158:161], v150 offset:3072
	v_add_u32_e32 v150, s60, v1
	s_nop 0
	ds_read_b128 v[162:165], v150
	ds_read_b128 v[166:169], v150 offset:1024
	ds_read_b128 v[170:173], v150 offset:2048
	ds_read_b128 v[174:177], v150 offset:3072
	v_lshl_add_u64 v[150:151], s[26:27], 0, v[138:139]
	s_add_i32 m0, s43, 0xc000
	ds_read_b128 v[178:181], v152
	ds_read_b128 v[182:185], v152 offset:1024
	ds_read_b128 v[186:189], v152 offset:2048
	ds_read_b128 v[190:193], v152 offset:3072
	ds_read_b128 v[204:207], v152 offset:4096
	ds_read_b128 v[208:211], v152 offset:5120
	ds_read_b128 v[212:215], v152 offset:6144
	ds_read_b128 v[228:231], v152 offset:7168
	global_load_lds_dwordx4 v[150:151], off
	v_lshl_add_u64 v[150:151], s[26:27], 0, v[140:141]
	s_add_i32 m0, s43, 0xe000
	s_nop 0
	global_load_lds_dwordx4 v[150:151], off
	s_waitcnt vmcnt(8)
	s_waitcnt lgkmcnt(0)
	s_barrier
	s_setprio 1
	s_waitcnt lgkmcnt(0)
	v_mfma_f32_16x16x32_bf16 v[126:129], v[142:145], v[178:181], v[126:129]
	v_mfma_f32_16x16x32_bf16 v[122:125], v[154:157], v[178:181], v[122:125]
	v_mfma_f32_16x16x32_bf16 v[110:113], v[142:145], v[186:189], v[110:113]
	v_mfma_f32_16x16x32_bf16 v[106:109], v[154:157], v[186:189], v[106:109]
	v_mfma_f32_16x16x32_bf16 v[94:97], v[142:145], v[204:207], v[94:97]
	v_mfma_f32_16x16x32_bf16 v[90:93], v[154:157], v[204:207], v[90:93]
	v_mfma_f32_16x16x32_bf16 v[78:81], v[142:145], v[212:215], v[78:81]
	v_mfma_f32_16x16x32_bf16 v[74:77], v[154:157], v[212:215], v[74:77]
	v_mfma_f32_16x16x32_bf16 v[126:129], v[146:149], v[182:185], v[126:129]
	v_mfma_f32_16x16x32_bf16 v[122:125], v[158:161], v[182:185], v[122:125]
	v_mfma_f32_16x16x32_bf16 v[110:113], v[146:149], v[190:193], v[110:113]
	v_mfma_f32_16x16x32_bf16 v[106:109], v[158:161], v[190:193], v[106:109]
	v_mfma_f32_16x16x32_bf16 v[94:97], v[146:149], v[208:211], v[94:97]
	v_mfma_f32_16x16x32_bf16 v[90:93], v[158:161], v[208:211], v[90:93]
	v_mfma_f32_16x16x32_bf16 v[78:81], v[146:149], v[228:231], v[78:81]
	v_mfma_f32_16x16x32_bf16 v[74:77], v[158:161], v[228:231], v[74:77]
	v_mfma_f32_16x16x32_bf16 v[118:121], v[162:165], v[178:181], v[118:121]
	v_mfma_f32_16x16x32_bf16 v[114:117], v[170:173], v[178:181], v[114:117]
	v_mfma_f32_16x16x32_bf16 v[102:105], v[162:165], v[186:189], v[102:105]
	v_mfma_f32_16x16x32_bf16 v[98:101], v[170:173], v[186:189], v[98:101]
	v_mfma_f32_16x16x32_bf16 v[86:89], v[162:165], v[204:207], v[86:89]
	v_mfma_f32_16x16x32_bf16 v[82:85], v[170:173], v[204:207], v[82:85]
	v_mfma_f32_16x16x32_bf16 v[70:73], v[162:165], v[212:215], v[70:73]
	v_mfma_f32_16x16x32_bf16 v[66:69], v[170:173], v[212:215], v[66:69]
	v_mfma_f32_16x16x32_bf16 v[118:121], v[166:169], v[182:185], v[118:121]
	v_mfma_f32_16x16x32_bf16 v[114:117], v[174:177], v[182:185], v[114:117]
	v_mfma_f32_16x16x32_bf16 v[102:105], v[166:169], v[190:193], v[102:105]
	v_mfma_f32_16x16x32_bf16 v[98:101], v[174:177], v[190:193], v[98:101]
	v_mfma_f32_16x16x32_bf16 v[86:89], v[166:169], v[208:211], v[86:89]
	v_mfma_f32_16x16x32_bf16 v[82:85], v[174:177], v[208:211], v[82:85]
	v_mfma_f32_16x16x32_bf16 v[70:73], v[166:169], v[228:231], v[70:73]
	v_mfma_f32_16x16x32_bf16 v[66:69], v[174:177], v[228:231], v[66:69]
	s_setprio 0
	s_barrier
	s_add_i32 s57, s57, s42
	v_lshl_add_u64 v[150:151], s[28:29], 0, v[134:135]
	s_mov_b32 m0, s57
	ds_read_b128 v[178:181], v152 offset:16384
	ds_read_b128 v[182:185], v152 offset:17408
	ds_read_b128 v[186:189], v152 offset:18432
	ds_read_b128 v[190:193], v152 offset:19456
	ds_read_b128 v[204:207], v152 offset:20480
	ds_read_b128 v[208:211], v152 offset:21504
	ds_read_b128 v[212:215], v152 offset:22528
	ds_read_b128 v[228:231], v152 offset:23552
	global_load_lds_dwordx4 v[150:151], off
	s_add_i32 m0, s57, 0x2000
	s_add_u32 s58, s28, 0x40000
	v_lshl_add_u64 v[194:195], s[28:29], 0, v[130:131]
	s_addc_u32 s59, s29, 0
	s_add_i32 s57, s60, s42
	global_load_lds_dwordx4 v[194:195], off
	v_lshl_add_u64 v[216:217], s[58:59], 0, v[134:135]
	s_mov_b32 m0, s57
	v_lshl_add_u64 v[232:233], s[30:31], 0, v[132:133]
	global_load_lds_dwordx4 v[216:217], off
	v_lshl_add_u64 v[216:217], s[58:59], 0, v[130:131]
	s_add_i32 m0, s57, 0x2000
	s_nop 0
	global_load_lds_dwordx4 v[216:217], off
	v_lshl_add_u64 v[216:217], s[30:31], 0, v[136:137]
	s_mov_b32 m0, s43
	s_nop 0
	global_load_lds_dwordx4 v[216:217], off
	s_mov_b32 m0, s44
	s_nop 0
	global_load_lds_dwordx4 v[232:233], off
	s_waitcnt vmcnt(8)
	s_waitcnt lgkmcnt(0)
	s_barrier
	s_setprio 1
	s_waitcnt lgkmcnt(0)
	v_mfma_f32_16x16x32_bf16 v[62:65], v[142:145], v[178:181], v[62:65]
	v_mfma_f32_16x16x32_bf16 v[58:61], v[154:157], v[178:181], v[58:61]
	v_mfma_f32_16x16x32_bf16 v[46:49], v[142:145], v[186:189], v[46:49]
	v_mfma_f32_16x16x32_bf16 v[42:45], v[154:157], v[186:189], v[42:45]
	v_mfma_f32_16x16x32_bf16 v[30:33], v[142:145], v[204:207], v[30:33]
	v_mfma_f32_16x16x32_bf16 v[26:29], v[154:157], v[204:207], v[26:29]
	v_mfma_f32_16x16x32_bf16 v[14:17], v[142:145], v[212:215], v[14:17]
	v_mfma_f32_16x16x32_bf16 v[10:13], v[154:157], v[212:215], v[10:13]
	v_mfma_f32_16x16x32_bf16 v[62:65], v[146:149], v[182:185], v[62:65]
	v_mfma_f32_16x16x32_bf16 v[58:61], v[158:161], v[182:185], v[58:61]
	v_mfma_f32_16x16x32_bf16 v[46:49], v[146:149], v[190:193], v[46:49]
	v_mfma_f32_16x16x32_bf16 v[42:45], v[158:161], v[190:193], v[42:45]
	v_mfma_f32_16x16x32_bf16 v[30:33], v[146:149], v[208:211], v[30:33]
	v_mfma_f32_16x16x32_bf16 v[26:29], v[158:161], v[208:211], v[26:29]
	v_mfma_f32_16x16x32_bf16 v[14:17], v[146:149], v[228:231], v[14:17]
	v_mfma_f32_16x16x32_bf16 v[10:13], v[158:161], v[228:231], v[10:13]
	v_mfma_f32_16x16x32_bf16 v[54:57], v[162:165], v[178:181], v[54:57]
	v_mfma_f32_16x16x32_bf16 v[50:53], v[170:173], v[178:181], v[50:53]
	v_mfma_f32_16x16x32_bf16 v[38:41], v[162:165], v[186:189], v[38:41]
	v_mfma_f32_16x16x32_bf16 v[34:37], v[170:173], v[186:189], v[34:37]
	v_mfma_f32_16x16x32_bf16 v[22:25], v[162:165], v[204:207], v[22:25]
	v_mfma_f32_16x16x32_bf16 v[18:21], v[170:173], v[204:207], v[18:21]
	v_mfma_f32_16x16x32_bf16 v[6:9], v[162:165], v[212:215], v[6:9]
	v_mfma_f32_16x16x32_bf16 v[2:5], v[170:173], v[212:215], v[2:5]
	v_mfma_f32_16x16x32_bf16 v[54:57], v[166:169], v[182:185], v[54:57]
	v_mfma_f32_16x16x32_bf16 v[50:53], v[174:177], v[182:185], v[50:53]
	v_mfma_f32_16x16x32_bf16 v[38:41], v[166:169], v[190:193], v[38:41]
	v_mfma_f32_16x16x32_bf16 v[34:37], v[174:177], v[190:193], v[34:37]
	v_mfma_f32_16x16x32_bf16 v[22:25], v[166:169], v[208:211], v[22:25]
	v_mfma_f32_16x16x32_bf16 v[18:21], v[174:177], v[208:211], v[18:21]
	v_mfma_f32_16x16x32_bf16 v[6:9], v[166:169], v[228:231], v[6:9]
	v_mfma_f32_16x16x32_bf16 v[2:5], v[174:177], v[228:231], v[2:5]
	s_setprio 0
	s_barrier
	s_add_i32 s57, 0, 0x18000
	v_add_u32_e32 v153, s57, v1
	s_add_i32 s58, 0, 0x1c000
	ds_read_b128 v[142:145], v153
	ds_read_b128 v[146:149], v153 offset:1024
	ds_read_b128 v[154:157], v153 offset:2048
	ds_read_b128 v[158:161], v153 offset:3072
	v_add_u32_e32 v153, s58, v1
	ds_read_b128 v[162:165], v153
	ds_read_b128 v[166:169], v153 offset:1024
	ds_read_b128 v[170:173], v153 offset:2048
	ds_read_b128 v[174:177], v153 offset:3072
	s_add_u32 s30, s30, 0x40000
	s_addc_u32 s31, s31, 0
	s_mov_b32 m0, s45
	v_lshl_add_u64 v[234:235], s[30:31], 0, v[136:137]
	ds_read_b128 v[178:181], v152 offset:32768
	ds_read_b128 v[182:185], v152 offset:33792
	ds_read_b128 v[186:189], v152 offset:34816
	ds_read_b128 v[190:193], v152 offset:35840
	ds_read_b128 v[204:207], v152 offset:36864
	ds_read_b128 v[208:211], v152 offset:37888
	ds_read_b128 v[212:215], v152 offset:38912
	ds_read_b128 v[228:231], v152 offset:39936
	global_load_lds_dwordx4 v[234:235], off
	v_lshl_add_u64 v[234:235], s[30:31], 0, v[132:133]
	s_mov_b32 m0, s46
	s_nop 0
	global_load_lds_dwordx4 v[234:235], off
	s_waitcnt vmcnt(8)
	s_waitcnt lgkmcnt(0)
	s_barrier
	s_setprio 1
	s_waitcnt lgkmcnt(0)
	v_mfma_f32_16x16x32_bf16 v[126:129], v[142:145], v[178:181], v[126:129]
	v_mfma_f32_16x16x32_bf16 v[122:125], v[154:157], v[178:181], v[122:125]
	v_mfma_f32_16x16x32_bf16 v[110:113], v[142:145], v[186:189], v[110:113]
	v_mfma_f32_16x16x32_bf16 v[106:109], v[154:157], v[186:189], v[106:109]
	v_mfma_f32_16x16x32_bf16 v[94:97], v[142:145], v[204:207], v[94:97]
	v_mfma_f32_16x16x32_bf16 v[90:93], v[154:157], v[204:207], v[90:93]
	v_mfma_f32_16x16x32_bf16 v[78:81], v[142:145], v[212:215], v[78:81]
	v_mfma_f32_16x16x32_bf16 v[74:77], v[154:157], v[212:215], v[74:77]
	v_mfma_f32_16x16x32_bf16 v[126:129], v[146:149], v[182:185], v[126:129]
	v_mfma_f32_16x16x32_bf16 v[122:125], v[158:161], v[182:185], v[122:125]
	v_mfma_f32_16x16x32_bf16 v[110:113], v[146:149], v[190:193], v[110:113]
	v_mfma_f32_16x16x32_bf16 v[106:109], v[158:161], v[190:193], v[106:109]
	v_mfma_f32_16x16x32_bf16 v[94:97], v[146:149], v[208:211], v[94:97]
	v_mfma_f32_16x16x32_bf16 v[90:93], v[158:161], v[208:211], v[90:93]
	v_mfma_f32_16x16x32_bf16 v[78:81], v[146:149], v[228:231], v[78:81]
	v_mfma_f32_16x16x32_bf16 v[74:77], v[158:161], v[228:231], v[74:77]
	v_mfma_f32_16x16x32_bf16 v[118:121], v[162:165], v[178:181], v[118:121]
	v_mfma_f32_16x16x32_bf16 v[114:117], v[170:173], v[178:181], v[114:117]
	v_mfma_f32_16x16x32_bf16 v[102:105], v[162:165], v[186:189], v[102:105]
	v_mfma_f32_16x16x32_bf16 v[98:101], v[170:173], v[186:189], v[98:101]
	v_mfma_f32_16x16x32_bf16 v[86:89], v[162:165], v[204:207], v[86:89]
	v_mfma_f32_16x16x32_bf16 v[82:85], v[170:173], v[204:207], v[82:85]
	v_mfma_f32_16x16x32_bf16 v[70:73], v[162:165], v[212:215], v[70:73]
	v_mfma_f32_16x16x32_bf16 v[66:69], v[170:173], v[212:215], v[66:69]
	v_mfma_f32_16x16x32_bf16 v[118:121], v[166:169], v[182:185], v[118:121]
	v_mfma_f32_16x16x32_bf16 v[114:117], v[174:177], v[182:185], v[114:117]
	v_mfma_f32_16x16x32_bf16 v[102:105], v[166:169], v[190:193], v[102:105]
	v_mfma_f32_16x16x32_bf16 v[98:101], v[174:177], v[190:193], v[98:101]
	v_mfma_f32_16x16x32_bf16 v[86:89], v[166:169], v[208:211], v[86:89]
	v_mfma_f32_16x16x32_bf16 v[82:85], v[174:177], v[208:211], v[82:85]
	v_mfma_f32_16x16x32_bf16 v[70:73], v[166:169], v[228:231], v[70:73]
	v_mfma_f32_16x16x32_bf16 v[66:69], v[174:177], v[228:231], v[66:69]
	s_setprio 0
	s_barrier
	s_add_i32 s30, s57, s42
	v_lshl_add_u64 v[150:151], v[150:151], 0, s[94:95]
	s_mov_b32 m0, s30
	ds_read_b128 v[178:181], v152 offset:49152
	ds_read_b128 v[182:185], v152 offset:50176
	ds_read_b128 v[186:189], v152 offset:51200
	ds_read_b128 v[190:193], v152 offset:52224
	ds_read_b128 v[204:207], v152 offset:53248
	ds_read_b128 v[208:211], v152 offset:54272
	ds_read_b128 v[212:215], v152 offset:55296
	ds_read_b128 v[228:231], v152 offset:56320
	global_load_lds_dwordx4 v[150:151], off
	s_add_i32 m0, s30, 0x2000
	s_add_u32 s28, s28, 0x40080
	v_lshl_add_u64 v[150:151], v[194:195], 0, s[94:95]
	s_addc_u32 s29, s29, 0
	s_add_i32 s30, s58, s42
	global_load_lds_dwordx4 v[150:151], off
	v_lshl_add_u64 v[150:151], s[28:29], 0, v[134:135]
	s_mov_b32 m0, s30
	s_nop 0
	global_load_lds_dwordx4 v[150:151], off
	v_lshl_add_u64 v[150:151], s[28:29], 0, v[130:131]
	s_add_i32 m0, s30, 0x2000
	s_nop 0
	global_load_lds_dwordx4 v[150:151], off
	v_lshl_add_u64 v[150:151], v[216:217], 0, s[94:95]
	s_mov_b32 m0, s49
	s_nop 0
	global_load_lds_dwordx4 v[150:151], off
	v_lshl_add_u64 v[150:151], v[232:233], 0, s[94:95]
	s_mov_b32 m0, s50
	s_nop 0
	global_load_lds_dwordx4 v[150:151], off
	s_waitcnt vmcnt(8)
	s_waitcnt lgkmcnt(0)
	s_barrier
	s_setprio 1
	s_waitcnt lgkmcnt(0)
	v_mfma_f32_16x16x32_bf16 v[62:65], v[142:145], v[178:181], v[62:65]
	v_mfma_f32_16x16x32_bf16 v[58:61], v[154:157], v[178:181], v[58:61]
	v_mfma_f32_16x16x32_bf16 v[46:49], v[142:145], v[186:189], v[46:49]
	v_mfma_f32_16x16x32_bf16 v[42:45], v[154:157], v[186:189], v[42:45]
	v_mfma_f32_16x16x32_bf16 v[30:33], v[142:145], v[204:207], v[30:33]
	v_mfma_f32_16x16x32_bf16 v[26:29], v[154:157], v[204:207], v[26:29]
	v_mfma_f32_16x16x32_bf16 v[14:17], v[142:145], v[212:215], v[14:17]
	v_mfma_f32_16x16x32_bf16 v[10:13], v[154:157], v[212:215], v[10:13]
	v_mfma_f32_16x16x32_bf16 v[62:65], v[146:149], v[182:185], v[62:65]
	v_mfma_f32_16x16x32_bf16 v[58:61], v[158:161], v[182:185], v[58:61]
	v_mfma_f32_16x16x32_bf16 v[46:49], v[146:149], v[190:193], v[46:49]
	v_mfma_f32_16x16x32_bf16 v[42:45], v[158:161], v[190:193], v[42:45]
	v_mfma_f32_16x16x32_bf16 v[30:33], v[146:149], v[208:211], v[30:33]
	v_mfma_f32_16x16x32_bf16 v[26:29], v[158:161], v[208:211], v[26:29]
	v_mfma_f32_16x16x32_bf16 v[14:17], v[146:149], v[228:231], v[14:17]
	v_mfma_f32_16x16x32_bf16 v[10:13], v[158:161], v[228:231], v[10:13]
	v_mfma_f32_16x16x32_bf16 v[54:57], v[162:165], v[178:181], v[54:57]
	v_mfma_f32_16x16x32_bf16 v[50:53], v[170:173], v[178:181], v[50:53]
	v_mfma_f32_16x16x32_bf16 v[38:41], v[162:165], v[186:189], v[38:41]
	v_mfma_f32_16x16x32_bf16 v[34:37], v[170:173], v[186:189], v[34:37]
	v_mfma_f32_16x16x32_bf16 v[22:25], v[162:165], v[204:207], v[22:25]
	v_mfma_f32_16x16x32_bf16 v[18:21], v[170:173], v[204:207], v[18:21]
	v_mfma_f32_16x16x32_bf16 v[6:9], v[162:165], v[212:215], v[6:9]
	v_mfma_f32_16x16x32_bf16 v[2:5], v[170:173], v[212:215], v[2:5]
	v_mfma_f32_16x16x32_bf16 v[54:57], v[166:169], v[182:185], v[54:57]
	v_mfma_f32_16x16x32_bf16 v[50:53], v[174:177], v[182:185], v[50:53]
	v_mfma_f32_16x16x32_bf16 v[38:41], v[166:169], v[190:193], v[38:41]
	v_mfma_f32_16x16x32_bf16 v[34:37], v[174:177], v[190:193], v[34:37]
	v_mfma_f32_16x16x32_bf16 v[22:25], v[166:169], v[208:211], v[22:25]
	v_mfma_f32_16x16x32_bf16 v[18:21], v[174:177], v[208:211], v[18:21]
	v_mfma_f32_16x16x32_bf16 v[6:9], v[166:169], v[228:231], v[6:9]
	v_mfma_f32_16x16x32_bf16 v[2:5], v[174:177], v[228:231], v[2:5]
	s_setprio 0
	s_barrier
	s_add_i32 s56, s56, 2
	s_add_u32 s26, s26, 0x100
	s_addc_u32 s27, s27, 0
	s_add_u32 s54, s54, 0x100
	s_addc_u32 s55, s55, 0
	s_cmp_gt_u32 s56, 13
	s_cbranch_scc0 .LBB0_111
	s_and_b64 vcc, exec, s[14:15]
	s_cbranch_vccz .LBB0_114
	s_barrier

.LBB0_139:
	s_add_u32 s28, s26, 0xfffc0080
	s_addc_u32 s29, s27, -1
	s_add_i32 s64, 0, 0x10000
	s_cmp_eq_u32 s63, 12
	s_cselect_b32 s31, s21, s29
	s_cselect_b32 s30, s59, s28
	v_add_u32_e32 v143, s64, v1
	s_cselect_b32 s29, s19, s62
	s_cselect_b32 s28, s60, s61
	s_add_i32 s66, 0, 0x14000
	ds_read_b128 v[144:147], v143
	ds_read_b128 v[148:151], v143 offset:1024
	ds_read_b128 v[152:155], v143 offset:2048
	ds_read_b128 v[156:159], v143 offset:3072
	v_add_u32_e32 v143, s66, v1
	ds_read_b128 v[160:163], v143
	ds_read_b128 v[164:167], v143 offset:1024
	ds_read_b128 v[168:171], v143 offset:2048
	ds_read_b128 v[172:175], v143 offset:3072
	v_lshl_add_u64 v[216:217], s[26:27], 0, v[138:139]
	s_add_i32 m0, s50, 0xc000
	ds_read_b128 v[176:179], v142
	ds_read_b128 v[180:183], v142 offset:1024
	ds_read_b128 v[184:187], v142 offset:2048
	ds_read_b128 v[188:191], v142 offset:3072
	ds_read_b128 v[192:195], v142 offset:4096
	ds_read_b128 v[204:207], v142 offset:5120
	ds_read_b128 v[208:211], v142 offset:6144
	ds_read_b128 v[212:215], v142 offset:7168
	global_load_lds_dwordx4 v[216:217], off
	v_lshl_add_u64 v[216:217], s[26:27], 0, v[140:141]
	s_add_i32 m0, s50, 0xe000
	s_nop 0
	global_load_lds_dwordx4 v[216:217], off
	s_waitcnt vmcnt(8)
	s_waitcnt lgkmcnt(0)
	s_barrier
	s_setprio 1
	s_waitcnt lgkmcnt(0)
	v_mfma_f32_16x16x32_bf16 v[126:129], v[144:147], v[176:179], v[126:129]
	v_mfma_f32_16x16x32_bf16 v[122:125], v[152:155], v[176:179], v[122:125]
	v_mfma_f32_16x16x32_bf16 v[118:121], v[144:147], v[184:187], v[118:121]
	v_mfma_f32_16x16x32_bf16 v[114:117], v[152:155], v[184:187], v[114:117]
	v_mfma_f32_16x16x32_bf16 v[102:105], v[144:147], v[192:195], v[102:105]
	v_mfma_f32_16x16x32_bf16 v[98:101], v[152:155], v[192:195], v[98:101]
	v_mfma_f32_16x16x32_bf16 v[86:89], v[144:147], v[208:211], v[86:89]
	v_mfma_f32_16x16x32_bf16 v[82:85], v[152:155], v[208:211], v[82:85]
	v_mfma_f32_16x16x32_bf16 v[126:129], v[148:151], v[180:183], v[126:129]
	v_mfma_f32_16x16x32_bf16 v[122:125], v[156:159], v[180:183], v[122:125]
	v_mfma_f32_16x16x32_bf16 v[118:121], v[148:151], v[188:191], v[118:121]
	v_mfma_f32_16x16x32_bf16 v[114:117], v[156:159], v[188:191], v[114:117]
	v_mfma_f32_16x16x32_bf16 v[102:105], v[148:151], v[204:207], v[102:105]
	v_mfma_f32_16x16x32_bf16 v[98:101], v[156:159], v[204:207], v[98:101]
	v_mfma_f32_16x16x32_bf16 v[86:89], v[148:151], v[212:215], v[86:89]
	v_mfma_f32_16x16x32_bf16 v[82:85], v[156:159], v[212:215], v[82:85]
	v_mfma_f32_16x16x32_bf16 v[110:113], v[160:163], v[176:179], v[110:113]
	v_mfma_f32_16x16x32_bf16 v[106:109], v[168:171], v[176:179], v[106:109]
	v_mfma_f32_16x16x32_bf16 v[94:97], v[160:163], v[184:187], v[94:97]
	v_mfma_f32_16x16x32_bf16 v[90:93], v[168:171], v[184:187], v[90:93]
	v_mfma_f32_16x16x32_bf16 v[78:81], v[160:163], v[192:195], v[78:81]
	v_mfma_f32_16x16x32_bf16 v[74:77], v[168:171], v[192:195], v[74:77]
	v_mfma_f32_16x16x32_bf16 v[70:73], v[160:163], v[208:211], v[70:73]
	v_mfma_f32_16x16x32_bf16 v[66:69], v[168:171], v[208:211], v[66:69]
	v_mfma_f32_16x16x32_bf16 v[110:113], v[164:167], v[180:183], v[110:113]
	v_mfma_f32_16x16x32_bf16 v[106:109], v[172:175], v[180:183], v[106:109]
	v_mfma_f32_16x16x32_bf16 v[94:97], v[164:167], v[188:191], v[94:97]
	v_mfma_f32_16x16x32_bf16 v[90:93], v[172:175], v[188:191], v[90:93]
	v_mfma_f32_16x16x32_bf16 v[78:81], v[164:167], v[204:207], v[78:81]
	v_mfma_f32_16x16x32_bf16 v[74:77], v[172:175], v[204:207], v[74:77]
	v_mfma_f32_16x16x32_bf16 v[70:73], v[164:167], v[212:215], v[70:73]
	v_mfma_f32_16x16x32_bf16 v[66:69], v[172:175], v[212:215], v[66:69]
	s_setprio 0
	s_barrier
	s_add_i32 s64, s64, s49
	v_lshl_add_u64 v[216:217], s[28:29], 0, v[132:133]
	s_mov_b32 m0, s64
	ds_read_b128 v[176:179], v142 offset:16384
	ds_read_b128 v[180:183], v142 offset:17408
	ds_read_b128 v[184:187], v142 offset:18432
	ds_read_b128 v[188:191], v142 offset:19456
	ds_read_b128 v[192:195], v142 offset:20480
	ds_read_b128 v[204:207], v142 offset:21504
	ds_read_b128 v[208:211], v142 offset:22528
	ds_read_b128 v[212:215], v142 offset:23552
	global_load_lds_dwordx4 v[216:217], off
	s_add_i32 m0, s64, 0x2000
	s_add_u32 s64, s28, 0x40000
	v_lshl_add_u64 v[228:229], s[28:29], 0, v[136:137]
	s_addc_u32 s65, s29, 0
	s_add_i32 s66, s66, s49
	global_load_lds_dwordx4 v[228:229], off
	v_lshl_add_u64 v[230:231], s[64:65], 0, v[132:133]
	s_mov_b32 m0, s66
	v_lshl_add_u64 v[232:233], s[30:31], 0, v[134:135]
	global_load_lds_dwordx4 v[230:231], off
	v_lshl_add_u64 v[230:231], s[64:65], 0, v[136:137]
	s_add_i32 m0, s66, 0x2000
	s_nop 0
	global_load_lds_dwordx4 v[230:231], off
	v_lshl_add_u64 v[230:231], s[30:31], 0, v[130:131]
	s_mov_b32 m0, s50
	s_nop 0
	global_load_lds_dwordx4 v[230:231], off
	s_mov_b32 m0, s51
	s_nop 0
	global_load_lds_dwordx4 v[232:233], off
	s_waitcnt vmcnt(8)
	s_waitcnt lgkmcnt(0)
	s_barrier
	s_setprio 1
	s_waitcnt lgkmcnt(0)
	v_mfma_f32_16x16x32_bf16 v[62:65], v[144:147], v[176:179], v[62:65]
	v_mfma_f32_16x16x32_bf16 v[58:61], v[152:155], v[176:179], v[58:61]
	v_mfma_f32_16x16x32_bf16 v[54:57], v[144:147], v[184:187], v[54:57]
	v_mfma_f32_16x16x32_bf16 v[50:53], v[152:155], v[184:187], v[50:53]
	v_mfma_f32_16x16x32_bf16 v[38:41], v[144:147], v[192:195], v[38:41]
	v_mfma_f32_16x16x32_bf16 v[34:37], v[152:155], v[192:195], v[34:37]
	v_mfma_f32_16x16x32_bf16 v[22:25], v[144:147], v[208:211], v[22:25]
	v_mfma_f32_16x16x32_bf16 v[18:21], v[152:155], v[208:211], v[18:21]
	v_mfma_f32_16x16x32_bf16 v[62:65], v[148:151], v[180:183], v[62:65]
	v_mfma_f32_16x16x32_bf16 v[58:61], v[156:159], v[180:183], v[58:61]
	v_mfma_f32_16x16x32_bf16 v[54:57], v[148:151], v[188:191], v[54:57]
	v_mfma_f32_16x16x32_bf16 v[50:53], v[156:159], v[188:191], v[50:53]
	v_mfma_f32_16x16x32_bf16 v[38:41], v[148:151], v[204:207], v[38:41]
	v_mfma_f32_16x16x32_bf16 v[34:37], v[156:159], v[204:207], v[34:37]
	v_mfma_f32_16x16x32_bf16 v[22:25], v[148:151], v[212:215], v[22:25]
	v_mfma_f32_16x16x32_bf16 v[18:21], v[156:159], v[212:215], v[18:21]
	v_mfma_f32_16x16x32_bf16 v[46:49], v[160:163], v[176:179], v[46:49]
	v_mfma_f32_16x16x32_bf16 v[42:45], v[168:171], v[176:179], v[42:45]
	v_mfma_f32_16x16x32_bf16 v[30:33], v[160:163], v[184:187], v[30:33]
	v_mfma_f32_16x16x32_bf16 v[26:29], v[168:171], v[184:187], v[26:29]
	v_mfma_f32_16x16x32_bf16 v[14:17], v[160:163], v[192:195], v[14:17]
	v_mfma_f32_16x16x32_bf16 v[10:13], v[168:171], v[192:195], v[10:13]
	v_mfma_f32_16x16x32_bf16 v[6:9], v[160:163], v[208:211], v[6:9]
	v_mfma_f32_16x16x32_bf16 v[2:5], v[168:171], v[208:211], v[2:5]
	v_mfma_f32_16x16x32_bf16 v[46:49], v[164:167], v[180:183], v[46:49]
	v_mfma_f32_16x16x32_bf16 v[42:45], v[172:175], v[180:183], v[42:45]
	v_mfma_f32_16x16x32_bf16 v[30:33], v[164:167], v[188:191], v[30:33]
	v_mfma_f32_16x16x32_bf16 v[26:29], v[172:175], v[188:191], v[26:29]
	v_mfma_f32_16x16x32_bf16 v[14:17], v[164:167], v[204:207], v[14:17]
	v_mfma_f32_16x16x32_bf16 v[10:13], v[172:175], v[204:207], v[10:13]
	v_mfma_f32_16x16x32_bf16 v[6:9], v[164:167], v[212:215], v[6:9]
	v_mfma_f32_16x16x32_bf16 v[2:5], v[172:175], v[212:215], v[2:5]
	s_setprio 0
	s_barrier
	s_add_i32 s64, 0, 0x18000
	v_add_u32_e32 v143, s64, v1
	s_add_i32 s65, 0, 0x1c000
	ds_read_b128 v[144:147], v143
	ds_read_b128 v[148:151], v143 offset:1024
	ds_read_b128 v[152:155], v143 offset:2048
	ds_read_b128 v[156:159], v143 offset:3072
	v_add_u32_e32 v143, s65, v1
	ds_read_b128 v[160:163], v143
	ds_read_b128 v[164:167], v143 offset:1024
	ds_read_b128 v[168:171], v143 offset:2048
	ds_read_b128 v[172:175], v143 offset:3072
	s_add_u32 s30, s30, 0x40000
	s_addc_u32 s31, s31, 0
	s_mov_b32 m0, s52
	v_lshl_add_u64 v[234:235], s[30:31], 0, v[130:131]
	ds_read_b128 v[176:179], v142 offset:32768
	ds_read_b128 v[180:183], v142 offset:33792
	ds_read_b128 v[184:187], v142 offset:34816
	ds_read_b128 v[188:191], v142 offset:35840
	ds_read_b128 v[192:195], v142 offset:36864
	ds_read_b128 v[204:207], v142 offset:37888
	ds_read_b128 v[208:211], v142 offset:38912
	ds_read_b128 v[212:215], v142 offset:39936
	global_load_lds_dwordx4 v[234:235], off
	v_lshl_add_u64 v[234:235], s[30:31], 0, v[134:135]
	s_mov_b32 m0, s53
	s_nop 0
	global_load_lds_dwordx4 v[234:235], off
	s_waitcnt vmcnt(8)
	s_waitcnt lgkmcnt(0)
	s_barrier
	s_setprio 1
	s_waitcnt lgkmcnt(0)
	v_mfma_f32_16x16x32_bf16 v[126:129], v[144:147], v[176:179], v[126:129]
	v_mfma_f32_16x16x32_bf16 v[122:125], v[152:155], v[176:179], v[122:125]
	v_mfma_f32_16x16x32_bf16 v[118:121], v[144:147], v[184:187], v[118:121]
	v_mfma_f32_16x16x32_bf16 v[114:117], v[152:155], v[184:187], v[114:117]
	v_mfma_f32_16x16x32_bf16 v[102:105], v[144:147], v[192:195], v[102:105]
	v_mfma_f32_16x16x32_bf16 v[98:101], v[152:155], v[192:195], v[98:101]
	v_mfma_f32_16x16x32_bf16 v[86:89], v[144:147], v[208:211], v[86:89]
	v_mfma_f32_16x16x32_bf16 v[82:85], v[152:155], v[208:211], v[82:85]
	v_mfma_f32_16x16x32_bf16 v[126:129], v[148:151], v[180:183], v[126:129]
	v_mfma_f32_16x16x32_bf16 v[122:125], v[156:159], v[180:183], v[122:125]
	v_mfma_f32_16x16x32_bf16 v[118:121], v[148:151], v[188:191], v[118:121]
	v_mfma_f32_16x16x32_bf16 v[114:117], v[156:159], v[188:191], v[114:117]
	v_mfma_f32_16x16x32_bf16 v[102:105], v[148:151], v[204:207], v[102:105]
	v_mfma_f32_16x16x32_bf16 v[98:101], v[156:159], v[204:207], v[98:101]
	v_mfma_f32_16x16x32_bf16 v[86:89], v[148:151], v[212:215], v[86:89]
	v_mfma_f32_16x16x32_bf16 v[82:85], v[156:159], v[212:215], v[82:85]
	v_mfma_f32_16x16x32_bf16 v[110:113], v[160:163], v[176:179], v[110:113]
	v_mfma_f32_16x16x32_bf16 v[106:109], v[168:171], v[176:179], v[106:109]
	v_mfma_f32_16x16x32_bf16 v[94:97], v[160:163], v[184:187], v[94:97]
	v_mfma_f32_16x16x32_bf16 v[90:93], v[168:171], v[184:187], v[90:93]
	v_mfma_f32_16x16x32_bf16 v[78:81], v[160:163], v[192:195], v[78:81]
	v_mfma_f32_16x16x32_bf16 v[74:77], v[168:171], v[192:195], v[74:77]
	v_mfma_f32_16x16x32_bf16 v[70:73], v[160:163], v[208:211], v[70:73]
	v_mfma_f32_16x16x32_bf16 v[66:69], v[168:171], v[208:211], v[66:69]
	v_mfma_f32_16x16x32_bf16 v[110:113], v[164:167], v[180:183], v[110:113]
	v_mfma_f32_16x16x32_bf16 v[106:109], v[172:175], v[180:183], v[106:109]
	v_mfma_f32_16x16x32_bf16 v[94:97], v[164:167], v[188:191], v[94:97]
	v_mfma_f32_16x16x32_bf16 v[90:93], v[172:175], v[188:191], v[90:93]
	v_mfma_f32_16x16x32_bf16 v[78:81], v[164:167], v[204:207], v[78:81]
	v_mfma_f32_16x16x32_bf16 v[74:77], v[172:175], v[204:207], v[74:77]
	v_mfma_f32_16x16x32_bf16 v[70:73], v[164:167], v[212:215], v[70:73]
	v_mfma_f32_16x16x32_bf16 v[66:69], v[172:175], v[212:215], v[66:69]
	s_setprio 0
	s_barrier
	s_add_i32 s30, s64, s49
	v_lshl_add_u64 v[216:217], v[216:217], 0, s[94:95]
	s_mov_b32 m0, s30
	ds_read_b128 v[176:179], v142 offset:49152
	ds_read_b128 v[180:183], v142 offset:50176
	ds_read_b128 v[184:187], v142 offset:51200
	ds_read_b128 v[188:191], v142 offset:52224
	ds_read_b128 v[192:195], v142 offset:53248
	ds_read_b128 v[204:207], v142 offset:54272
	ds_read_b128 v[208:211], v142 offset:55296
	ds_read_b128 v[212:215], v142 offset:56320
	global_load_lds_dwordx4 v[216:217], off
	s_add_i32 m0, s30, 0x2000
	s_add_u32 s28, s28, 0x40080
	v_lshl_add_u64 v[216:217], v[228:229], 0, s[94:95]
	s_addc_u32 s29, s29, 0
	s_add_i32 s30, s65, s49
	global_load_lds_dwordx4 v[216:217], off
	v_lshl_add_u64 v[216:217], s[28:29], 0, v[132:133]
	s_mov_b32 m0, s30
	s_nop 0
	global_load_lds_dwordx4 v[216:217], off
	v_lshl_add_u64 v[216:217], s[28:29], 0, v[136:137]
	s_add_i32 m0, s30, 0x2000
	s_nop 0
	global_load_lds_dwordx4 v[216:217], off
	v_lshl_add_u64 v[216:217], v[230:231], 0, s[94:95]
	s_mov_b32 m0, s56
	s_nop 0
	global_load_lds_dwordx4 v[216:217], off
	v_lshl_add_u64 v[216:217], v[232:233], 0, s[94:95]
	s_mov_b32 m0, s57
	s_nop 0
	global_load_lds_dwordx4 v[216:217], off
	s_waitcnt vmcnt(8)
	s_waitcnt lgkmcnt(0)
	s_barrier
	s_setprio 1
	s_waitcnt lgkmcnt(0)
	v_mfma_f32_16x16x32_bf16 v[62:65], v[144:147], v[176:179], v[62:65]
	v_mfma_f32_16x16x32_bf16 v[58:61], v[152:155], v[176:179], v[58:61]
	v_mfma_f32_16x16x32_bf16 v[54:57], v[144:147], v[184:187], v[54:57]
	v_mfma_f32_16x16x32_bf16 v[50:53], v[152:155], v[184:187], v[50:53]
	v_mfma_f32_16x16x32_bf16 v[38:41], v[144:147], v[192:195], v[38:41]
	v_mfma_f32_16x16x32_bf16 v[34:37], v[152:155], v[192:195], v[34:37]
	v_mfma_f32_16x16x32_bf16 v[22:25], v[144:147], v[208:211], v[22:25]
	v_mfma_f32_16x16x32_bf16 v[18:21], v[152:155], v[208:211], v[18:21]
	v_mfma_f32_16x16x32_bf16 v[62:65], v[148:151], v[180:183], v[62:65]
	v_mfma_f32_16x16x32_bf16 v[58:61], v[156:159], v[180:183], v[58:61]
	v_mfma_f32_16x16x32_bf16 v[54:57], v[148:151], v[188:191], v[54:57]
	v_mfma_f32_16x16x32_bf16 v[50:53], v[156:159], v[188:191], v[50:53]
	v_mfma_f32_16x16x32_bf16 v[38:41], v[148:151], v[204:207], v[38:41]
	v_mfma_f32_16x16x32_bf16 v[34:37], v[156:159], v[204:207], v[34:37]
	v_mfma_f32_16x16x32_bf16 v[22:25], v[148:151], v[212:215], v[22:25]
	v_mfma_f32_16x16x32_bf16 v[18:21], v[156:159], v[212:215], v[18:21]
	v_mfma_f32_16x16x32_bf16 v[46:49], v[160:163], v[176:179], v[46:49]
	v_mfma_f32_16x16x32_bf16 v[42:45], v[168:171], v[176:179], v[42:45]
	v_mfma_f32_16x16x32_bf16 v[30:33], v[160:163], v[184:187], v[30:33]
	v_mfma_f32_16x16x32_bf16 v[26:29], v[168:171], v[184:187], v[26:29]
	v_mfma_f32_16x16x32_bf16 v[14:17], v[160:163], v[192:195], v[14:17]
	v_mfma_f32_16x16x32_bf16 v[10:13], v[168:171], v[192:195], v[10:13]
	v_mfma_f32_16x16x32_bf16 v[6:9], v[160:163], v[208:211], v[6:9]
	v_mfma_f32_16x16x32_bf16 v[2:5], v[168:171], v[208:211], v[2:5]
	v_mfma_f32_16x16x32_bf16 v[46:49], v[164:167], v[180:183], v[46:49]
	v_mfma_f32_16x16x32_bf16 v[42:45], v[172:175], v[180:183], v[42:45]
	v_mfma_f32_16x16x32_bf16 v[30:33], v[164:167], v[188:191], v[30:33]
	v_mfma_f32_16x16x32_bf16 v[26:29], v[172:175], v[188:191], v[26:29]
	v_mfma_f32_16x16x32_bf16 v[14:17], v[164:167], v[204:207], v[14:17]
	v_mfma_f32_16x16x32_bf16 v[10:13], v[172:175], v[204:207], v[10:13]
	v_mfma_f32_16x16x32_bf16 v[6:9], v[164:167], v[212:215], v[6:9]
	v_mfma_f32_16x16x32_bf16 v[2:5], v[172:175], v[212:215], v[2:5]
	s_setprio 0
	s_barrier
	s_add_i32 s63, s63, 2
	s_add_u32 s26, s26, 0x100
	s_addc_u32 s27, s27, 0
	s_add_u32 s61, s61, 0x100
	s_addc_u32 s62, s62, 0
	s_cmp_gt_u32 s63, 13
	s_cbranch_scc0 .LBB0_139
	s_and_b64 vcc, exec, s[10:11]
	s_cbranch_vccz .LBB0_142
	s_barrier

.LBB0_220:
	s_add_u32 s26, s24, 0x100
	s_addc_u32 s27, s25, 0
	s_add_i32 s59, 0, 0x10000
	s_cmp_eq_u32 s58, 40
	s_cselect_b32 s31, s7, s27
	s_cselect_b32 s30, s6, s26
	s_cselect_b32 s29, s23, s57
	s_cselect_b32 s28, s22, s56
	s_add_i32 s60, 0, 0x14000
	v_add_u32_e32 v134, s59, v1
	v_add_u32_e32 v154, s60, v1
	ds_read_b128 v[110:113], v134
	ds_read_b128 v[118:121], v134 offset:1024
	ds_read_b128 v[122:125], v134 offset:2048
	ds_read_b128 v[134:137], v134 offset:3072
	ds_read_b128 v[138:141], v154
	ds_read_b128 v[142:145], v154 offset:1024
	ds_read_b128 v[146:149], v154 offset:2048
	ds_read_b128 v[154:157], v154 offset:3072
	v_lshl_add_u64 v[216:217], s[24:25], 0, v[206:207]
	s_add_i32 m0, s41, 0xc000
	ds_read_b128 v[162:165], v214
	ds_read_b128 v[166:169], v214 offset:1024
	ds_read_b128 v[170:173], v214 offset:2048
	ds_read_b128 v[174:177], v214 offset:3072
	ds_read_b128 v[178:181], v214 offset:4096
	ds_read_b128 v[182:185], v214 offset:5120
	ds_read_b128 v[186:189], v214 offset:6144
	ds_read_b128 v[210:213], v214 offset:7168
	global_load_lds_dwordx4 v[216:217], off
	v_lshl_add_u64 v[216:217], s[24:25], 0, v[208:209]
	s_add_i32 m0, s41, 0xe000
	s_nop 0
	global_load_lds_dwordx4 v[216:217], off
	s_waitcnt vmcnt(8)
	s_waitcnt lgkmcnt(0)
	s_barrier
	s_setprio 1
	s_waitcnt lgkmcnt(0)
	v_mfma_f32_16x16x32_bf16 v[158:161], v[110:113], v[162:165], v[158:161]
	v_mfma_f32_16x16x32_bf16 v[150:153], v[122:125], v[162:165], v[150:153]
	v_mfma_f32_16x16x32_bf16 v[114:117], v[110:113], v[170:173], v[114:117]
	v_mfma_f32_16x16x32_bf16 v[106:109], v[122:125], v[170:173], v[106:109]
	v_mfma_f32_16x16x32_bf16 v[94:97], v[110:113], v[178:181], v[94:97]
	v_mfma_f32_16x16x32_bf16 v[90:93], v[122:125], v[178:181], v[90:93]
	v_mfma_f32_16x16x32_bf16 v[78:81], v[110:113], v[186:189], v[78:81]
	v_mfma_f32_16x16x32_bf16 v[74:77], v[122:125], v[186:189], v[74:77]
	v_mfma_f32_16x16x32_bf16 v[158:161], v[118:121], v[166:169], v[158:161]
	v_mfma_f32_16x16x32_bf16 v[150:153], v[134:137], v[166:169], v[150:153]
	v_mfma_f32_16x16x32_bf16 v[114:117], v[118:121], v[174:177], v[114:117]
	v_mfma_f32_16x16x32_bf16 v[106:109], v[134:137], v[174:177], v[106:109]
	v_mfma_f32_16x16x32_bf16 v[94:97], v[118:121], v[182:185], v[94:97]
	v_mfma_f32_16x16x32_bf16 v[90:93], v[134:137], v[182:185], v[90:93]
	v_mfma_f32_16x16x32_bf16 v[78:81], v[118:121], v[210:213], v[78:81]
	v_mfma_f32_16x16x32_bf16 v[74:77], v[134:137], v[210:213], v[74:77]
	v_mfma_f32_16x16x32_bf16 v[130:133], v[138:141], v[162:165], v[130:133]
	v_mfma_f32_16x16x32_bf16 v[126:129], v[146:149], v[162:165], v[126:129]
	v_mfma_f32_16x16x32_bf16 v[102:105], v[138:141], v[170:173], v[102:105]
	v_mfma_f32_16x16x32_bf16 v[98:101], v[146:149], v[170:173], v[98:101]
	v_mfma_f32_16x16x32_bf16 v[86:89], v[138:141], v[178:181], v[86:89]
	v_mfma_f32_16x16x32_bf16 v[82:85], v[146:149], v[178:181], v[82:85]
	v_mfma_f32_16x16x32_bf16 v[70:73], v[138:141], v[186:189], v[70:73]
	v_mfma_f32_16x16x32_bf16 v[66:69], v[146:149], v[186:189], v[66:69]
	v_mfma_f32_16x16x32_bf16 v[130:133], v[142:145], v[166:169], v[130:133]
	v_mfma_f32_16x16x32_bf16 v[126:129], v[154:157], v[166:169], v[126:129]
	v_mfma_f32_16x16x32_bf16 v[102:105], v[142:145], v[174:177], v[102:105]
	v_mfma_f32_16x16x32_bf16 v[98:101], v[154:157], v[174:177], v[98:101]
	v_mfma_f32_16x16x32_bf16 v[86:89], v[142:145], v[182:185], v[86:89]
	v_mfma_f32_16x16x32_bf16 v[82:85], v[154:157], v[182:185], v[82:85]
	v_mfma_f32_16x16x32_bf16 v[70:73], v[142:145], v[210:213], v[70:73]
	v_mfma_f32_16x16x32_bf16 v[66:69], v[154:157], v[210:213], v[66:69]
	s_setprio 0
	s_barrier
	s_add_i32 s24, s59, s40
	v_lshl_add_u64 v[216:217], s[28:29], 0, v[192:193]
	s_mov_b32 m0, s24
	ds_read_b128 v[162:165], v214 offset:16384
	ds_read_b128 v[166:169], v214 offset:17408
	ds_read_b128 v[170:173], v214 offset:18432
	ds_read_b128 v[174:177], v214 offset:19456
	ds_read_b128 v[178:181], v214 offset:20480
	ds_read_b128 v[182:185], v214 offset:21504
	ds_read_b128 v[186:189], v214 offset:22528
	ds_read_b128 v[210:213], v214 offset:23552
	global_load_lds_dwordx4 v[216:217], off
	s_add_i32 m0, s24, 0x2000
	s_add_u32 s24, s28, 0xb0000
	v_lshl_add_u64 v[228:229], s[28:29], 0, v[204:205]
	s_addc_u32 s25, s29, 0
	s_add_i32 s59, s60, s40
	global_load_lds_dwordx4 v[228:229], off
	v_lshl_add_u64 v[230:231], s[24:25], 0, v[192:193]
	s_mov_b32 m0, s59
	v_lshl_add_u64 v[232:233], s[30:31], 0, v[194:195]
	global_load_lds_dwordx4 v[230:231], off
	v_lshl_add_u64 v[230:231], s[24:25], 0, v[204:205]
	s_add_i32 m0, s59, 0x2000
	s_nop 0
	global_load_lds_dwordx4 v[230:231], off
	v_lshl_add_u64 v[230:231], s[30:31], 0, v[190:191]
	s_mov_b32 m0, s41
	s_nop 0
	global_load_lds_dwordx4 v[230:231], off
	s_mov_b32 m0, s42
	s_nop 0
	global_load_lds_dwordx4 v[232:233], off
	s_waitcnt vmcnt(8)
	s_waitcnt lgkmcnt(0)
	s_barrier
	s_setprio 1
	s_waitcnt lgkmcnt(0)
	v_mfma_f32_16x16x32_bf16 v[62:65], v[110:113], v[162:165], v[62:65]
	v_mfma_f32_16x16x32_bf16 v[58:61], v[122:125], v[162:165], v[58:61]
	v_mfma_f32_16x16x32_bf16 v[46:49], v[110:113], v[170:173], v[46:49]
	v_mfma_f32_16x16x32_bf16 v[42:45], v[122:125], v[170:173], v[42:45]
	v_mfma_f32_16x16x32_bf16 v[30:33], v[110:113], v[178:181], v[30:33]
	v_mfma_f32_16x16x32_bf16 v[26:29], v[122:125], v[178:181], v[26:29]
	v_mfma_f32_16x16x32_bf16 v[14:17], v[110:113], v[186:189], v[14:17]
	v_mfma_f32_16x16x32_bf16 v[10:13], v[122:125], v[186:189], v[10:13]
	v_mfma_f32_16x16x32_bf16 v[62:65], v[118:121], v[166:169], v[62:65]
	v_mfma_f32_16x16x32_bf16 v[58:61], v[134:137], v[166:169], v[58:61]
	v_mfma_f32_16x16x32_bf16 v[46:49], v[118:121], v[174:177], v[46:49]
	v_mfma_f32_16x16x32_bf16 v[42:45], v[134:137], v[174:177], v[42:45]
	v_mfma_f32_16x16x32_bf16 v[30:33], v[118:121], v[182:185], v[30:33]
	v_mfma_f32_16x16x32_bf16 v[26:29], v[134:137], v[182:185], v[26:29]
	v_mfma_f32_16x16x32_bf16 v[14:17], v[118:121], v[210:213], v[14:17]
	v_mfma_f32_16x16x32_bf16 v[10:13], v[134:137], v[210:213], v[10:13]
	v_mfma_f32_16x16x32_bf16 v[54:57], v[138:141], v[162:165], v[54:57]
	v_mfma_f32_16x16x32_bf16 v[50:53], v[146:149], v[162:165], v[50:53]
	v_mfma_f32_16x16x32_bf16 v[38:41], v[138:141], v[170:173], v[38:41]
	v_mfma_f32_16x16x32_bf16 v[34:37], v[146:149], v[170:173], v[34:37]
	v_mfma_f32_16x16x32_bf16 v[22:25], v[138:141], v[178:181], v[22:25]
	v_mfma_f32_16x16x32_bf16 v[18:21], v[146:149], v[178:181], v[18:21]
	v_mfma_f32_16x16x32_bf16 v[6:9], v[138:141], v[186:189], v[6:9]
	v_mfma_f32_16x16x32_bf16 v[2:5], v[146:149], v[186:189], v[2:5]
	v_mfma_f32_16x16x32_bf16 v[54:57], v[142:145], v[166:169], v[54:57]
	v_mfma_f32_16x16x32_bf16 v[50:53], v[154:157], v[166:169], v[50:53]
	v_mfma_f32_16x16x32_bf16 v[38:41], v[142:145], v[174:177], v[38:41]
	v_mfma_f32_16x16x32_bf16 v[34:37], v[154:157], v[174:177], v[34:37]
	v_mfma_f32_16x16x32_bf16 v[22:25], v[142:145], v[182:185], v[22:25]
	v_mfma_f32_16x16x32_bf16 v[18:21], v[154:157], v[182:185], v[18:21]
	v_mfma_f32_16x16x32_bf16 v[6:9], v[142:145], v[210:213], v[6:9]
	v_mfma_f32_16x16x32_bf16 v[2:5], v[154:157], v[210:213], v[2:5]
	s_setprio 0
	s_barrier
	s_add_i32 s59, 0, 0x18000
	s_add_i32 s60, 0, 0x1c000
	v_add_u32_e32 v134, s59, v1
	v_add_u32_e32 v154, s60, v1
	ds_read_b128 v[110:113], v134
	ds_read_b128 v[118:121], v134 offset:1024
	ds_read_b128 v[122:125], v134 offset:2048
	ds_read_b128 v[134:137], v134 offset:3072
	ds_read_b128 v[138:141], v154
	ds_read_b128 v[142:145], v154 offset:1024
	ds_read_b128 v[146:149], v154 offset:2048
	ds_read_b128 v[154:157], v154 offset:3072
	s_add_u32 s24, s30, 0xb0000
	s_addc_u32 s25, s31, 0
	s_mov_b32 m0, s43
	v_lshl_add_u64 v[234:235], s[24:25], 0, v[190:191]
	ds_read_b128 v[162:165], v214 offset:32768
	ds_read_b128 v[166:169], v214 offset:33792
	ds_read_b128 v[170:173], v214 offset:34816
	ds_read_b128 v[174:177], v214 offset:35840
	ds_read_b128 v[178:181], v214 offset:36864
	ds_read_b128 v[182:185], v214 offset:37888
	ds_read_b128 v[186:189], v214 offset:38912
	ds_read_b128 v[210:213], v214 offset:39936
	global_load_lds_dwordx4 v[234:235], off
	v_lshl_add_u64 v[234:235], s[24:25], 0, v[194:195]
	s_mov_b32 m0, s44
	s_nop 0
	global_load_lds_dwordx4 v[234:235], off
	s_waitcnt vmcnt(8)
	s_waitcnt lgkmcnt(0)
	s_barrier
	s_setprio 1
	s_waitcnt lgkmcnt(0)
	v_mfma_f32_16x16x32_bf16 v[158:161], v[110:113], v[162:165], v[158:161]
	v_mfma_f32_16x16x32_bf16 v[150:153], v[122:125], v[162:165], v[150:153]
	v_mfma_f32_16x16x32_bf16 v[114:117], v[110:113], v[170:173], v[114:117]
	v_mfma_f32_16x16x32_bf16 v[106:109], v[122:125], v[170:173], v[106:109]
	v_mfma_f32_16x16x32_bf16 v[94:97], v[110:113], v[178:181], v[94:97]
	v_mfma_f32_16x16x32_bf16 v[90:93], v[122:125], v[178:181], v[90:93]
	v_mfma_f32_16x16x32_bf16 v[78:81], v[110:113], v[186:189], v[78:81]
	v_mfma_f32_16x16x32_bf16 v[74:77], v[122:125], v[186:189], v[74:77]
	v_mfma_f32_16x16x32_bf16 v[158:161], v[118:121], v[166:169], v[158:161]
	v_mfma_f32_16x16x32_bf16 v[150:153], v[134:137], v[166:169], v[150:153]
	v_mfma_f32_16x16x32_bf16 v[114:117], v[118:121], v[174:177], v[114:117]
	v_mfma_f32_16x16x32_bf16 v[106:109], v[134:137], v[174:177], v[106:109]
	v_mfma_f32_16x16x32_bf16 v[94:97], v[118:121], v[182:185], v[94:97]
	v_mfma_f32_16x16x32_bf16 v[90:93], v[134:137], v[182:185], v[90:93]
	v_mfma_f32_16x16x32_bf16 v[78:81], v[118:121], v[210:213], v[78:81]
	v_mfma_f32_16x16x32_bf16 v[74:77], v[134:137], v[210:213], v[74:77]
	v_mfma_f32_16x16x32_bf16 v[130:133], v[138:141], v[162:165], v[130:133]
	v_mfma_f32_16x16x32_bf16 v[126:129], v[146:149], v[162:165], v[126:129]
	v_mfma_f32_16x16x32_bf16 v[102:105], v[138:141], v[170:173], v[102:105]
	v_mfma_f32_16x16x32_bf16 v[98:101], v[146:149], v[170:173], v[98:101]
	v_mfma_f32_16x16x32_bf16 v[86:89], v[138:141], v[178:181], v[86:89]
	v_mfma_f32_16x16x32_bf16 v[82:85], v[146:149], v[178:181], v[82:85]
	v_mfma_f32_16x16x32_bf16 v[70:73], v[138:141], v[186:189], v[70:73]
	v_mfma_f32_16x16x32_bf16 v[66:69], v[146:149], v[186:189], v[66:69]
	v_mfma_f32_16x16x32_bf16 v[130:133], v[142:145], v[166:169], v[130:133]
	v_mfma_f32_16x16x32_bf16 v[126:129], v[154:157], v[166:169], v[126:129]
	v_mfma_f32_16x16x32_bf16 v[102:105], v[142:145], v[174:177], v[102:105]
	v_mfma_f32_16x16x32_bf16 v[98:101], v[154:157], v[174:177], v[98:101]
	v_mfma_f32_16x16x32_bf16 v[86:89], v[142:145], v[182:185], v[86:89]
	v_mfma_f32_16x16x32_bf16 v[82:85], v[154:157], v[182:185], v[82:85]
	v_mfma_f32_16x16x32_bf16 v[70:73], v[142:145], v[210:213], v[70:73]
	v_mfma_f32_16x16x32_bf16 v[66:69], v[154:157], v[210:213], v[66:69]
	s_setprio 0
	s_barrier
	s_add_i32 s24, s59, s40
	v_lshl_add_u64 v[216:217], v[216:217], 0, s[94:95]
	s_mov_b32 m0, s24
	ds_read_b128 v[162:165], v214 offset:49152
	ds_read_b128 v[166:169], v214 offset:50176
	ds_read_b128 v[170:173], v214 offset:51200
	ds_read_b128 v[174:177], v214 offset:52224
	ds_read_b128 v[178:181], v214 offset:53248
	ds_read_b128 v[182:185], v214 offset:54272
	ds_read_b128 v[186:189], v214 offset:55296
	ds_read_b128 v[210:213], v214 offset:56320
	global_load_lds_dwordx4 v[216:217], off
	s_add_i32 m0, s24, 0x2000
	s_add_u32 s24, s28, 0xb0080
	v_lshl_add_u64 v[216:217], v[228:229], 0, s[94:95]
	s_addc_u32 s25, s29, 0
	s_add_i32 s28, s60, s40
	global_load_lds_dwordx4 v[216:217], off
	v_lshl_add_u64 v[216:217], s[24:25], 0, v[192:193]
	s_mov_b32 m0, s28
	s_nop 0
	global_load_lds_dwordx4 v[216:217], off
	v_lshl_add_u64 v[216:217], s[24:25], 0, v[204:205]
	s_add_i32 m0, s28, 0x2000
	s_nop 0
	global_load_lds_dwordx4 v[216:217], off
	v_lshl_add_u64 v[216:217], v[230:231], 0, s[94:95]
	s_mov_b32 m0, s47
	s_nop 0
	global_load_lds_dwordx4 v[216:217], off
	v_lshl_add_u64 v[216:217], v[232:233], 0, s[94:95]
	s_mov_b32 m0, s48
	s_nop 0
	global_load_lds_dwordx4 v[216:217], off
	s_waitcnt vmcnt(8)
	s_waitcnt lgkmcnt(0)
	s_barrier
	s_setprio 1
	s_waitcnt lgkmcnt(0)
	v_mfma_f32_16x16x32_bf16 v[62:65], v[110:113], v[162:165], v[62:65]
	v_mfma_f32_16x16x32_bf16 v[58:61], v[122:125], v[162:165], v[58:61]
	v_mfma_f32_16x16x32_bf16 v[46:49], v[110:113], v[170:173], v[46:49]
	v_mfma_f32_16x16x32_bf16 v[42:45], v[122:125], v[170:173], v[42:45]
	v_mfma_f32_16x16x32_bf16 v[30:33], v[110:113], v[178:181], v[30:33]
	v_mfma_f32_16x16x32_bf16 v[26:29], v[122:125], v[178:181], v[26:29]
	v_mfma_f32_16x16x32_bf16 v[14:17], v[110:113], v[186:189], v[14:17]
	v_mfma_f32_16x16x32_bf16 v[10:13], v[122:125], v[186:189], v[10:13]
	v_mfma_f32_16x16x32_bf16 v[62:65], v[118:121], v[166:169], v[62:65]
	v_mfma_f32_16x16x32_bf16 v[58:61], v[134:137], v[166:169], v[58:61]
	v_mfma_f32_16x16x32_bf16 v[46:49], v[118:121], v[174:177], v[46:49]
	v_mfma_f32_16x16x32_bf16 v[42:45], v[134:137], v[174:177], v[42:45]
	v_mfma_f32_16x16x32_bf16 v[30:33], v[118:121], v[182:185], v[30:33]
	v_mfma_f32_16x16x32_bf16 v[26:29], v[134:137], v[182:185], v[26:29]
	v_mfma_f32_16x16x32_bf16 v[14:17], v[118:121], v[210:213], v[14:17]
	v_mfma_f32_16x16x32_bf16 v[10:13], v[134:137], v[210:213], v[10:13]
	v_mfma_f32_16x16x32_bf16 v[54:57], v[138:141], v[162:165], v[54:57]
	v_mfma_f32_16x16x32_bf16 v[50:53], v[146:149], v[162:165], v[50:53]
	v_mfma_f32_16x16x32_bf16 v[38:41], v[138:141], v[170:173], v[38:41]
	v_mfma_f32_16x16x32_bf16 v[34:37], v[146:149], v[170:173], v[34:37]
	v_mfma_f32_16x16x32_bf16 v[22:25], v[138:141], v[178:181], v[22:25]
	v_mfma_f32_16x16x32_bf16 v[18:21], v[146:149], v[178:181], v[18:21]
	v_mfma_f32_16x16x32_bf16 v[6:9], v[138:141], v[186:189], v[6:9]
	v_mfma_f32_16x16x32_bf16 v[2:5], v[146:149], v[186:189], v[2:5]
	v_mfma_f32_16x16x32_bf16 v[54:57], v[142:145], v[166:169], v[54:57]
	v_mfma_f32_16x16x32_bf16 v[50:53], v[154:157], v[166:169], v[50:53]
	v_mfma_f32_16x16x32_bf16 v[38:41], v[142:145], v[174:177], v[38:41]
	v_mfma_f32_16x16x32_bf16 v[34:37], v[154:157], v[174:177], v[34:37]
	v_mfma_f32_16x16x32_bf16 v[22:25], v[142:145], v[182:185], v[22:25]
	v_mfma_f32_16x16x32_bf16 v[18:21], v[154:157], v[182:185], v[18:21]
	v_mfma_f32_16x16x32_bf16 v[6:9], v[142:145], v[210:213], v[6:9]
	v_mfma_f32_16x16x32_bf16 v[2:5], v[154:157], v[210:213], v[2:5]
	s_setprio 0
	s_barrier
	s_add_i32 s58, s58, 2
	s_add_u32 s56, s56, 0x100
	s_addc_u32 s57, s57, 0
	s_cmp_gt_u32 s58, 41
	s_mov_b64 s[24:25], s[26:27]
	s_cbranch_scc0 .LBB0_220
	s_and_b64 vcc, exec, s[20:21]
	s_cbranch_vccz .LBB0_223
	s_barrier

.LBB0_252:
	s_add_i32 s15, s14, 0x100
	s_and_b64 s[12:13], s[12:13], exec
	s_cselect_b32 s13, 0, s15
	s_cselect_b32 s12, 0, 0
	s_add_u32 s16, s4, s13
	s_addc_u32 s17, s5, s12
	s_add_i32 s61, 0, 0x10000
	s_add_u32 s18, s2, s13
	s_addc_u32 s19, s3, s12
	s_add_i32 s13, 0, 0x14000
	s_add_u32 s22, s6, s14
	s_addc_u32 s23, s7, 0
	s_add_i32 s60, s61, s43
	s_add_i32 m0, s44, 0xc000
	s_add_i32 s63, s44, 0xe000
	s_add_i32 s57, s60, 0x2000
	v_add_u32_e32 v139, s61, v1
	s_add_u32 s20, s18, 0x80800
	ds_read_b128 v[140:143], v139
	ds_read_b128 v[144:147], v139 offset:1024
	ds_read_b128 v[148:151], v139 offset:2048
	ds_read_b128 v[152:155], v139 offset:3072
	v_add_u32_e32 v139, s13, v1
	s_addc_u32 s21, s19, 0
	s_add_i32 s59, s13, s43
	ds_read_b128 v[156:159], v139
	ds_read_b128 v[160:163], v139 offset:1024
	ds_read_b128 v[164:167], v139 offset:2048
	ds_read_b128 v[168:171], v139 offset:3072
	s_add_i32 s58, s59, 0x2000
	s_add_i32 s56, 0, 0x18000
	s_add_i32 s55, 0, 0x1c000
	s_add_u32 s14, s16, 0x40000
	s_addc_u32 s15, s17, 0
	s_add_i32 s54, s56, s43
	s_add_i32 s53, s54, 0x2000
	s_add_u32 s12, s18, 0x80880
	s_addc_u32 s13, s19, 0
	s_add_i32 s62, s55, s43
	s_add_i32 s61, s62, 0x2000
	v_lshl_add_u64 v[212:213], s[22:23], 0, v[130:131]
	v_lshl_add_u64 v[212:213], v[212:213], 0, s[94:95]
	ds_read_b128 v[172:175], v138
	ds_read_b128 v[176:179], v138 offset:1024
	ds_read_b128 v[180:183], v138 offset:2048
	ds_read_b128 v[184:187], v138 offset:3072
	ds_read_b128 v[188:191], v138 offset:4096
	ds_read_b128 v[192:195], v138 offset:5120
	ds_read_b128 v[204:207], v138 offset:6144
	ds_read_b128 v[208:211], v138 offset:7168
	global_load_lds_dwordx4 v[212:213], off
	v_lshl_add_u64 v[212:213], s[22:23], 0, v[134:135]
	v_lshl_add_u64 v[212:213], v[212:213], 0, s[94:95]
	s_mov_b32 m0, s63
	s_nop 0
	global_load_lds_dwordx4 v[212:213], off
	s_waitcnt vmcnt(8)
	s_waitcnt lgkmcnt(0)
	s_barrier
	s_setprio 1
	s_waitcnt lgkmcnt(0)
	v_mfma_f32_16x16x32_bf16 v[126:129], v[140:143], v[172:175], v[126:129]
	v_mfma_f32_16x16x32_bf16 v[122:125], v[148:151], v[172:175], v[122:125]
	v_mfma_f32_16x16x32_bf16 v[118:121], v[140:143], v[180:183], v[118:121]
	v_mfma_f32_16x16x32_bf16 v[114:117], v[148:151], v[180:183], v[114:117]
	v_mfma_f32_16x16x32_bf16 v[102:105], v[140:143], v[188:191], v[102:105]
	v_mfma_f32_16x16x32_bf16 v[98:101], v[148:151], v[188:191], v[98:101]
	v_mfma_f32_16x16x32_bf16 v[86:89], v[140:143], v[204:207], v[86:89]
	v_mfma_f32_16x16x32_bf16 v[82:85], v[148:151], v[204:207], v[82:85]
	v_mfma_f32_16x16x32_bf16 v[126:129], v[144:147], v[176:179], v[126:129]
	v_mfma_f32_16x16x32_bf16 v[122:125], v[152:155], v[176:179], v[122:125]
	v_mfma_f32_16x16x32_bf16 v[118:121], v[144:147], v[184:187], v[118:121]
	v_mfma_f32_16x16x32_bf16 v[114:117], v[152:155], v[184:187], v[114:117]
	v_mfma_f32_16x16x32_bf16 v[102:105], v[144:147], v[192:195], v[102:105]
	v_mfma_f32_16x16x32_bf16 v[98:101], v[152:155], v[192:195], v[98:101]
	v_mfma_f32_16x16x32_bf16 v[86:89], v[144:147], v[208:211], v[86:89]
	v_mfma_f32_16x16x32_bf16 v[82:85], v[152:155], v[208:211], v[82:85]
	v_mfma_f32_16x16x32_bf16 v[110:113], v[156:159], v[172:175], v[110:113]
	v_mfma_f32_16x16x32_bf16 v[106:109], v[164:167], v[172:175], v[106:109]
	v_mfma_f32_16x16x32_bf16 v[94:97], v[156:159], v[180:183], v[94:97]
	v_mfma_f32_16x16x32_bf16 v[90:93], v[164:167], v[180:183], v[90:93]
	v_mfma_f32_16x16x32_bf16 v[78:81], v[156:159], v[188:191], v[78:81]
	v_mfma_f32_16x16x32_bf16 v[74:77], v[164:167], v[188:191], v[74:77]
	v_mfma_f32_16x16x32_bf16 v[70:73], v[156:159], v[204:207], v[70:73]
	v_mfma_f32_16x16x32_bf16 v[66:69], v[164:167], v[204:207], v[66:69]
	v_mfma_f32_16x16x32_bf16 v[110:113], v[160:163], v[176:179], v[110:113]
	v_mfma_f32_16x16x32_bf16 v[106:109], v[168:171], v[176:179], v[106:109]
	v_mfma_f32_16x16x32_bf16 v[94:97], v[160:163], v[184:187], v[94:97]
	v_mfma_f32_16x16x32_bf16 v[90:93], v[168:171], v[184:187], v[90:93]
	v_mfma_f32_16x16x32_bf16 v[78:81], v[160:163], v[192:195], v[78:81]
	v_mfma_f32_16x16x32_bf16 v[74:77], v[168:171], v[192:195], v[74:77]
	v_mfma_f32_16x16x32_bf16 v[70:73], v[160:163], v[208:211], v[70:73]
	v_mfma_f32_16x16x32_bf16 v[66:69], v[168:171], v[208:211], v[66:69]
	s_setprio 0
	s_barrier
	v_lshl_add_u64 v[212:213], s[18:19], 0, v[132:133]
	s_mov_b32 m0, s60
	v_lshl_add_u64 v[214:215], v[212:213], 0, s[90:91]
	ds_read_b128 v[172:175], v138 offset:16384
	ds_read_b128 v[176:179], v138 offset:17408
	ds_read_b128 v[180:183], v138 offset:18432
	ds_read_b128 v[184:187], v138 offset:19456
	ds_read_b128 v[188:191], v138 offset:20480
	ds_read_b128 v[192:195], v138 offset:21504
	ds_read_b128 v[204:207], v138 offset:22528
	ds_read_b128 v[208:211], v138 offset:23552
	global_load_lds_dwordx4 v[214:215], off
	v_lshl_add_u64 v[214:215], s[18:19], 0, v[136:137]
	v_lshl_add_u64 v[216:217], v[214:215], 0, s[90:91]
	s_mov_b32 m0, s57
	v_lshl_add_u64 v[228:229], s[16:17], 0, v[134:135]
	global_load_lds_dwordx4 v[216:217], off
	v_lshl_add_u64 v[216:217], s[20:21], 0, v[132:133]
	s_mov_b32 m0, s59
	s_nop 0
	global_load_lds_dwordx4 v[216:217], off
	v_lshl_add_u64 v[216:217], s[20:21], 0, v[136:137]
	s_mov_b32 m0, s58
	s_nop 0
	global_load_lds_dwordx4 v[216:217], off
	v_lshl_add_u64 v[216:217], s[16:17], 0, v[130:131]
	s_mov_b32 m0, s44
	s_nop 0
	global_load_lds_dwordx4 v[216:217], off
	s_mov_b32 m0, s45
	s_nop 0
	global_load_lds_dwordx4 v[228:229], off
	s_waitcnt vmcnt(8)
	s_waitcnt lgkmcnt(0)
	s_barrier
	s_setprio 1
	s_waitcnt lgkmcnt(0)
	v_mfma_f32_16x16x32_bf16 v[62:65], v[140:143], v[172:175], v[62:65]
	v_mfma_f32_16x16x32_bf16 v[58:61], v[148:151], v[172:175], v[58:61]
	v_mfma_f32_16x16x32_bf16 v[54:57], v[140:143], v[180:183], v[54:57]
	v_mfma_f32_16x16x32_bf16 v[50:53], v[148:151], v[180:183], v[50:53]
	v_mfma_f32_16x16x32_bf16 v[38:41], v[140:143], v[188:191], v[38:41]
	v_mfma_f32_16x16x32_bf16 v[34:37], v[148:151], v[188:191], v[34:37]
	v_mfma_f32_16x16x32_bf16 v[22:25], v[140:143], v[204:207], v[22:25]
	v_mfma_f32_16x16x32_bf16 v[18:21], v[148:151], v[204:207], v[18:21]
	v_mfma_f32_16x16x32_bf16 v[62:65], v[144:147], v[176:179], v[62:65]
	v_mfma_f32_16x16x32_bf16 v[58:61], v[152:155], v[176:179], v[58:61]
	v_mfma_f32_16x16x32_bf16 v[54:57], v[144:147], v[184:187], v[54:57]
	v_mfma_f32_16x16x32_bf16 v[50:53], v[152:155], v[184:187], v[50:53]
	v_mfma_f32_16x16x32_bf16 v[38:41], v[144:147], v[192:195], v[38:41]
	v_mfma_f32_16x16x32_bf16 v[34:37], v[152:155], v[192:195], v[34:37]
	v_mfma_f32_16x16x32_bf16 v[22:25], v[144:147], v[208:211], v[22:25]
	v_mfma_f32_16x16x32_bf16 v[18:21], v[152:155], v[208:211], v[18:21]
	v_mfma_f32_16x16x32_bf16 v[46:49], v[156:159], v[172:175], v[46:49]
	v_mfma_f32_16x16x32_bf16 v[42:45], v[164:167], v[172:175], v[42:45]
	v_mfma_f32_16x16x32_bf16 v[30:33], v[156:159], v[180:183], v[30:33]
	v_mfma_f32_16x16x32_bf16 v[26:29], v[164:167], v[180:183], v[26:29]
	v_mfma_f32_16x16x32_bf16 v[14:17], v[156:159], v[188:191], v[14:17]
	v_mfma_f32_16x16x32_bf16 v[10:13], v[164:167], v[188:191], v[10:13]
	v_mfma_f32_16x16x32_bf16 v[6:9], v[156:159], v[204:207], v[6:9]
	v_mfma_f32_16x16x32_bf16 v[2:5], v[164:167], v[204:207], v[2:5]
	v_mfma_f32_16x16x32_bf16 v[46:49], v[160:163], v[176:179], v[46:49]
	v_mfma_f32_16x16x32_bf16 v[42:45], v[168:171], v[176:179], v[42:45]
	v_mfma_f32_16x16x32_bf16 v[30:33], v[160:163], v[184:187], v[30:33]
	v_mfma_f32_16x16x32_bf16 v[26:29], v[168:171], v[184:187], v[26:29]
	v_mfma_f32_16x16x32_bf16 v[14:17], v[160:163], v[192:195], v[14:17]
	v_mfma_f32_16x16x32_bf16 v[10:13], v[168:171], v[192:195], v[10:13]
	v_mfma_f32_16x16x32_bf16 v[6:9], v[160:163], v[208:211], v[6:9]
	v_mfma_f32_16x16x32_bf16 v[2:5], v[168:171], v[208:211], v[2:5]
	s_setprio 0
	s_barrier
	v_add_u32_e32 v139, s56, v1
	ds_read_b128 v[140:143], v139
	ds_read_b128 v[144:147], v139 offset:1024
	ds_read_b128 v[148:151], v139 offset:2048
	ds_read_b128 v[152:155], v139 offset:3072
	v_add_u32_e32 v139, s55, v1
	ds_read_b128 v[156:159], v139
	ds_read_b128 v[160:163], v139 offset:1024
	ds_read_b128 v[164:167], v139 offset:2048
	ds_read_b128 v[168:171], v139 offset:3072
	s_mov_b32 m0, s46
	v_lshl_add_u64 v[230:231], s[14:15], 0, v[130:131]
	ds_read_b128 v[172:175], v138 offset:32768
	ds_read_b128 v[176:179], v138 offset:33792
	ds_read_b128 v[180:183], v138 offset:34816
	ds_read_b128 v[184:187], v138 offset:35840
	ds_read_b128 v[188:191], v138 offset:36864
	ds_read_b128 v[192:195], v138 offset:37888
	ds_read_b128 v[204:207], v138 offset:38912
	ds_read_b128 v[208:211], v138 offset:39936
	global_load_lds_dwordx4 v[230:231], off
	v_lshl_add_u64 v[230:231], s[14:15], 0, v[134:135]
	s_mov_b32 m0, s47
	s_nop 0
	global_load_lds_dwordx4 v[230:231], off
	s_waitcnt vmcnt(8)
	s_waitcnt lgkmcnt(0)
	s_barrier
	s_setprio 1
	s_waitcnt lgkmcnt(0)
	v_mfma_f32_16x16x32_bf16 v[126:129], v[140:143], v[172:175], v[126:129]
	v_mfma_f32_16x16x32_bf16 v[122:125], v[148:151], v[172:175], v[122:125]
	v_mfma_f32_16x16x32_bf16 v[118:121], v[140:143], v[180:183], v[118:121]
	v_mfma_f32_16x16x32_bf16 v[114:117], v[148:151], v[180:183], v[114:117]
	v_mfma_f32_16x16x32_bf16 v[102:105], v[140:143], v[188:191], v[102:105]
	v_mfma_f32_16x16x32_bf16 v[98:101], v[148:151], v[188:191], v[98:101]
	v_mfma_f32_16x16x32_bf16 v[86:89], v[140:143], v[204:207], v[86:89]
	v_mfma_f32_16x16x32_bf16 v[82:85], v[148:151], v[204:207], v[82:85]
	v_mfma_f32_16x16x32_bf16 v[126:129], v[144:147], v[176:179], v[126:129]
	v_mfma_f32_16x16x32_bf16 v[122:125], v[152:155], v[176:179], v[122:125]
	v_mfma_f32_16x16x32_bf16 v[118:121], v[144:147], v[184:187], v[118:121]
	v_mfma_f32_16x16x32_bf16 v[114:117], v[152:155], v[184:187], v[114:117]
	v_mfma_f32_16x16x32_bf16 v[102:105], v[144:147], v[192:195], v[102:105]
	v_mfma_f32_16x16x32_bf16 v[98:101], v[152:155], v[192:195], v[98:101]
	v_mfma_f32_16x16x32_bf16 v[86:89], v[144:147], v[208:211], v[86:89]
	v_mfma_f32_16x16x32_bf16 v[82:85], v[152:155], v[208:211], v[82:85]
	v_mfma_f32_16x16x32_bf16 v[110:113], v[156:159], v[172:175], v[110:113]
	v_mfma_f32_16x16x32_bf16 v[106:109], v[164:167], v[172:175], v[106:109]
	v_mfma_f32_16x16x32_bf16 v[94:97], v[156:159], v[180:183], v[94:97]
	v_mfma_f32_16x16x32_bf16 v[90:93], v[164:167], v[180:183], v[90:93]
	v_mfma_f32_16x16x32_bf16 v[78:81], v[156:159], v[188:191], v[78:81]
	v_mfma_f32_16x16x32_bf16 v[74:77], v[164:167], v[188:191], v[74:77]
	v_mfma_f32_16x16x32_bf16 v[70:73], v[156:159], v[204:207], v[70:73]
	v_mfma_f32_16x16x32_bf16 v[66:69], v[164:167], v[204:207], v[66:69]
	v_mfma_f32_16x16x32_bf16 v[110:113], v[160:163], v[176:179], v[110:113]
	v_mfma_f32_16x16x32_bf16 v[106:109], v[168:171], v[176:179], v[106:109]
	v_mfma_f32_16x16x32_bf16 v[94:97], v[160:163], v[184:187], v[94:97]
	v_mfma_f32_16x16x32_bf16 v[90:93], v[168:171], v[184:187], v[90:93]
	v_mfma_f32_16x16x32_bf16 v[78:81], v[160:163], v[192:195], v[78:81]
	v_mfma_f32_16x16x32_bf16 v[74:77], v[168:171], v[192:195], v[74:77]
	v_mfma_f32_16x16x32_bf16 v[70:73], v[160:163], v[208:211], v[70:73]
	v_mfma_f32_16x16x32_bf16 v[66:69], v[168:171], v[208:211], v[66:69]
	s_setprio 0
	s_barrier
	s_mov_b32 m0, s54
	v_lshl_add_u64 v[212:213], v[212:213], 0, s[64:65]
	ds_read_b128 v[172:175], v138 offset:49152
	ds_read_b128 v[176:179], v138 offset:50176
	ds_read_b128 v[180:183], v138 offset:51200
	ds_read_b128 v[184:187], v138 offset:52224
	ds_read_b128 v[188:191], v138 offset:53248
	ds_read_b128 v[192:195], v138 offset:54272
	ds_read_b128 v[204:207], v138 offset:55296
	ds_read_b128 v[208:211], v138 offset:56320
	global_load_lds_dwordx4 v[212:213], off
	v_lshl_add_u64 v[212:213], v[214:215], 0, s[64:65]
	s_mov_b32 m0, s53
	s_nop 0
	global_load_lds_dwordx4 v[212:213], off
	v_lshl_add_u64 v[212:213], s[12:13], 0, v[132:133]
	s_mov_b32 m0, s62
	s_nop 0
	global_load_lds_dwordx4 v[212:213], off
	v_lshl_add_u64 v[212:213], s[12:13], 0, v[136:137]
	s_mov_b32 m0, s61
	s_nop 0
	global_load_lds_dwordx4 v[212:213], off
	v_lshl_add_u64 v[212:213], v[216:217], 0, s[94:95]
	s_mov_b32 m0, s51
	s_nop 0
	global_load_lds_dwordx4 v[212:213], off
	v_lshl_add_u64 v[212:213], v[228:229], 0, s[94:95]
	s_mov_b32 m0, s52
	s_nop 0
	global_load_lds_dwordx4 v[212:213], off
	s_waitcnt vmcnt(8)
	s_waitcnt lgkmcnt(0)
	s_barrier
	s_setprio 1
	s_waitcnt lgkmcnt(0)
	v_mfma_f32_16x16x32_bf16 v[62:65], v[140:143], v[172:175], v[62:65]
	v_mfma_f32_16x16x32_bf16 v[58:61], v[148:151], v[172:175], v[58:61]
	v_mfma_f32_16x16x32_bf16 v[54:57], v[140:143], v[180:183], v[54:57]
	v_mfma_f32_16x16x32_bf16 v[50:53], v[148:151], v[180:183], v[50:53]
	v_mfma_f32_16x16x32_bf16 v[38:41], v[140:143], v[188:191], v[38:41]
	v_mfma_f32_16x16x32_bf16 v[34:37], v[148:151], v[188:191], v[34:37]
	v_mfma_f32_16x16x32_bf16 v[22:25], v[140:143], v[204:207], v[22:25]
	v_mfma_f32_16x16x32_bf16 v[18:21], v[148:151], v[204:207], v[18:21]
	v_mfma_f32_16x16x32_bf16 v[62:65], v[144:147], v[176:179], v[62:65]
	v_mfma_f32_16x16x32_bf16 v[58:61], v[152:155], v[176:179], v[58:61]
	v_mfma_f32_16x16x32_bf16 v[54:57], v[144:147], v[184:187], v[54:57]
	v_mfma_f32_16x16x32_bf16 v[50:53], v[152:155], v[184:187], v[50:53]
	v_mfma_f32_16x16x32_bf16 v[38:41], v[144:147], v[192:195], v[38:41]
	v_mfma_f32_16x16x32_bf16 v[34:37], v[152:155], v[192:195], v[34:37]
	v_mfma_f32_16x16x32_bf16 v[22:25], v[144:147], v[208:211], v[22:25]
	v_mfma_f32_16x16x32_bf16 v[18:21], v[152:155], v[208:211], v[18:21]
	v_mfma_f32_16x16x32_bf16 v[46:49], v[156:159], v[172:175], v[46:49]
	v_mfma_f32_16x16x32_bf16 v[42:45], v[164:167], v[172:175], v[42:45]
	v_mfma_f32_16x16x32_bf16 v[30:33], v[156:159], v[180:183], v[30:33]
	v_mfma_f32_16x16x32_bf16 v[26:29], v[164:167], v[180:183], v[26:29]
	v_mfma_f32_16x16x32_bf16 v[14:17], v[156:159], v[188:191], v[14:17]
	v_mfma_f32_16x16x32_bf16 v[10:13], v[164:167], v[188:191], v[10:13]
	v_mfma_f32_16x16x32_bf16 v[6:9], v[156:159], v[204:207], v[6:9]
	v_mfma_f32_16x16x32_bf16 v[2:5], v[164:167], v[204:207], v[2:5]
	v_mfma_f32_16x16x32_bf16 v[46:49], v[160:163], v[176:179], v[46:49]
	v_mfma_f32_16x16x32_bf16 v[42:45], v[168:171], v[176:179], v[42:45]
	v_mfma_f32_16x16x32_bf16 v[30:33], v[160:163], v[184:187], v[30:33]
	v_mfma_f32_16x16x32_bf16 v[26:29], v[168:171], v[184:187], v[26:29]
	v_mfma_f32_16x16x32_bf16 v[14:17], v[160:163], v[192:195], v[14:17]
	v_mfma_f32_16x16x32_bf16 v[10:13], v[168:171], v[192:195], v[10:13]
	v_mfma_f32_16x16x32_bf16 v[6:9], v[160:163], v[208:211], v[6:9]
	v_mfma_f32_16x16x32_bf16 v[2:5], v[168:171], v[208:211], v[2:5]
	s_setprio 0
	s_barrier
	s_andn2_b64 vcc, exec, s[8:9]
	s_mov_b64 s[12:13], -1
	s_mov_b64 s[8:9], 0
	s_movk_i32 s14, 0x100
	s_cbranch_vccz .LBB0_252
	s_cmpk_lt_u32 s42, 0x100
	s_cbranch_scc0 .LBB0_255
	s_barrier

.LBB0_260:
	s_add_i32 s15, s14, 0x100
	s_and_b64 s[12:13], s[12:13], exec
	s_cselect_b32 s13, 0, s15
	s_cselect_b32 s12, 0, 0
	s_add_u32 s16, s2, s13
	s_addc_u32 s17, s3, s12
	s_add_i32 s56, 0, 0x10000
	s_add_u32 s18, s4, s13
	s_addc_u32 s19, s5, s12
	s_add_i32 s13, 0, 0x14000
	s_add_u32 s22, s6, s14
	s_addc_u32 s23, s7, 0
	s_add_i32 s55, s56, s39
	s_add_i32 m0, s40, 0xc000
	s_add_i32 s58, s40, 0xe000
	s_add_i32 s52, s55, 0x2000
	v_add_u32_e32 v139, s56, v1
	s_add_u32 s20, s18, 0x40000
	ds_read_b128 v[140:143], v139
	ds_read_b128 v[144:147], v139 offset:1024
	ds_read_b128 v[148:151], v139 offset:2048
	ds_read_b128 v[152:155], v139 offset:3072
	v_add_u32_e32 v139, s13, v1
	s_addc_u32 s21, s19, 0
	s_add_i32 s54, s13, s39
	ds_read_b128 v[156:159], v139
	ds_read_b128 v[160:163], v139 offset:1024
	ds_read_b128 v[164:167], v139 offset:2048
	ds_read_b128 v[168:171], v139 offset:3072
	s_add_i32 s53, s54, 0x2000
	s_add_i32 s51, 0, 0x18000
	s_add_i32 s50, 0, 0x1c000
	s_add_u32 s14, s16, 0x80000
	s_addc_u32 s15, s17, 0
	s_add_i32 s49, s51, s39
	s_add_i32 s48, s49, 0x2000
	s_add_u32 s12, s18, 0x40080
	s_addc_u32 s13, s19, 0
	s_add_i32 s57, s50, s39
	s_add_i32 s56, s57, 0x2000
	v_lshl_add_u64 v[212:213], s[22:23], 0, v[130:131]
	v_lshl_add_u64 v[212:213], v[212:213], 0, s[94:95]
	ds_read_b128 v[172:175], v138
	ds_read_b128 v[176:179], v138 offset:1024
	ds_read_b128 v[180:183], v138 offset:2048
	ds_read_b128 v[184:187], v138 offset:3072
	ds_read_b128 v[188:191], v138 offset:4096
	ds_read_b128 v[192:195], v138 offset:5120
	ds_read_b128 v[204:207], v138 offset:6144
	ds_read_b128 v[208:211], v138 offset:7168
	global_load_lds_dwordx4 v[212:213], off
	v_lshl_add_u64 v[212:213], s[22:23], 0, v[134:135]
	v_lshl_add_u64 v[212:213], v[212:213], 0, s[94:95]
	s_mov_b32 m0, s58
	s_nop 0
	global_load_lds_dwordx4 v[212:213], off
	s_waitcnt vmcnt(8)
	s_waitcnt lgkmcnt(0)
	s_barrier
	s_setprio 1
	s_waitcnt lgkmcnt(0)
	v_mfma_f32_16x16x32_bf16 v[126:129], v[140:143], v[172:175], v[126:129]
	v_mfma_f32_16x16x32_bf16 v[122:125], v[148:151], v[172:175], v[122:125]
	v_mfma_f32_16x16x32_bf16 v[118:121], v[140:143], v[180:183], v[118:121]
	v_mfma_f32_16x16x32_bf16 v[114:117], v[148:151], v[180:183], v[114:117]
	v_mfma_f32_16x16x32_bf16 v[102:105], v[140:143], v[188:191], v[102:105]
	v_mfma_f32_16x16x32_bf16 v[98:101], v[148:151], v[188:191], v[98:101]
	v_mfma_f32_16x16x32_bf16 v[86:89], v[140:143], v[204:207], v[86:89]
	v_mfma_f32_16x16x32_bf16 v[82:85], v[148:151], v[204:207], v[82:85]
	v_mfma_f32_16x16x32_bf16 v[126:129], v[144:147], v[176:179], v[126:129]
	v_mfma_f32_16x16x32_bf16 v[122:125], v[152:155], v[176:179], v[122:125]
	v_mfma_f32_16x16x32_bf16 v[118:121], v[144:147], v[184:187], v[118:121]
	v_mfma_f32_16x16x32_bf16 v[114:117], v[152:155], v[184:187], v[114:117]
	v_mfma_f32_16x16x32_bf16 v[102:105], v[144:147], v[192:195], v[102:105]
	v_mfma_f32_16x16x32_bf16 v[98:101], v[152:155], v[192:195], v[98:101]
	v_mfma_f32_16x16x32_bf16 v[86:89], v[144:147], v[208:211], v[86:89]
	v_mfma_f32_16x16x32_bf16 v[82:85], v[152:155], v[208:211], v[82:85]
	v_mfma_f32_16x16x32_bf16 v[110:113], v[156:159], v[172:175], v[110:113]
	v_mfma_f32_16x16x32_bf16 v[106:109], v[164:167], v[172:175], v[106:109]
	v_mfma_f32_16x16x32_bf16 v[94:97], v[156:159], v[180:183], v[94:97]
	v_mfma_f32_16x16x32_bf16 v[90:93], v[164:167], v[180:183], v[90:93]
	v_mfma_f32_16x16x32_bf16 v[78:81], v[156:159], v[188:191], v[78:81]
	v_mfma_f32_16x16x32_bf16 v[74:77], v[164:167], v[188:191], v[74:77]
	v_mfma_f32_16x16x32_bf16 v[70:73], v[156:159], v[204:207], v[70:73]
	v_mfma_f32_16x16x32_bf16 v[66:69], v[164:167], v[204:207], v[66:69]
	v_mfma_f32_16x16x32_bf16 v[110:113], v[160:163], v[176:179], v[110:113]
	v_mfma_f32_16x16x32_bf16 v[106:109], v[168:171], v[176:179], v[106:109]
	v_mfma_f32_16x16x32_bf16 v[94:97], v[160:163], v[184:187], v[94:97]
	v_mfma_f32_16x16x32_bf16 v[90:93], v[168:171], v[184:187], v[90:93]
	v_mfma_f32_16x16x32_bf16 v[78:81], v[160:163], v[192:195], v[78:81]
	v_mfma_f32_16x16x32_bf16 v[74:77], v[168:171], v[192:195], v[74:77]
	v_mfma_f32_16x16x32_bf16 v[70:73], v[160:163], v[208:211], v[70:73]
	v_mfma_f32_16x16x32_bf16 v[66:69], v[168:171], v[208:211], v[66:69]
	s_setprio 0
	s_barrier
	s_mov_b32 m0, s55
	v_lshl_add_u64 v[212:213], s[18:19], 0, v[132:133]
	ds_read_b128 v[172:175], v138 offset:16384
	ds_read_b128 v[176:179], v138 offset:17408
	ds_read_b128 v[180:183], v138 offset:18432
	ds_read_b128 v[184:187], v138 offset:19456
	ds_read_b128 v[188:191], v138 offset:20480
	ds_read_b128 v[192:195], v138 offset:21504
	ds_read_b128 v[204:207], v138 offset:22528
	ds_read_b128 v[208:211], v138 offset:23552
	global_load_lds_dwordx4 v[212:213], off
	v_lshl_add_u64 v[214:215], s[18:19], 0, v[136:137]
	s_mov_b32 m0, s52
	v_lshl_add_u64 v[216:217], s[20:21], 0, v[132:133]
	global_load_lds_dwordx4 v[214:215], off
	s_mov_b32 m0, s54
	v_lshl_add_u64 v[228:229], s[16:17], 0, v[134:135]
	global_load_lds_dwordx4 v[216:217], off
	v_lshl_add_u64 v[216:217], s[20:21], 0, v[136:137]
	s_mov_b32 m0, s53
	s_nop 0
	global_load_lds_dwordx4 v[216:217], off
	v_lshl_add_u64 v[216:217], s[16:17], 0, v[130:131]
	s_mov_b32 m0, s40
	s_nop 0
	global_load_lds_dwordx4 v[216:217], off
	s_mov_b32 m0, s41
	s_nop 0
	global_load_lds_dwordx4 v[228:229], off
	s_waitcnt vmcnt(8)
	s_waitcnt lgkmcnt(0)
	s_barrier
	s_setprio 1
	s_waitcnt lgkmcnt(0)
	v_mfma_f32_16x16x32_bf16 v[62:65], v[140:143], v[172:175], v[62:65]
	v_mfma_f32_16x16x32_bf16 v[58:61], v[148:151], v[172:175], v[58:61]
	v_mfma_f32_16x16x32_bf16 v[54:57], v[140:143], v[180:183], v[54:57]
	v_mfma_f32_16x16x32_bf16 v[50:53], v[148:151], v[180:183], v[50:53]
	v_mfma_f32_16x16x32_bf16 v[38:41], v[140:143], v[188:191], v[38:41]
	v_mfma_f32_16x16x32_bf16 v[34:37], v[148:151], v[188:191], v[34:37]
	v_mfma_f32_16x16x32_bf16 v[22:25], v[140:143], v[204:207], v[22:25]
	v_mfma_f32_16x16x32_bf16 v[18:21], v[148:151], v[204:207], v[18:21]
	v_mfma_f32_16x16x32_bf16 v[62:65], v[144:147], v[176:179], v[62:65]
	v_mfma_f32_16x16x32_bf16 v[58:61], v[152:155], v[176:179], v[58:61]
	v_mfma_f32_16x16x32_bf16 v[54:57], v[144:147], v[184:187], v[54:57]
	v_mfma_f32_16x16x32_bf16 v[50:53], v[152:155], v[184:187], v[50:53]
	v_mfma_f32_16x16x32_bf16 v[38:41], v[144:147], v[192:195], v[38:41]
	v_mfma_f32_16x16x32_bf16 v[34:37], v[152:155], v[192:195], v[34:37]
	v_mfma_f32_16x16x32_bf16 v[22:25], v[144:147], v[208:211], v[22:25]
	v_mfma_f32_16x16x32_bf16 v[18:21], v[152:155], v[208:211], v[18:21]
	v_mfma_f32_16x16x32_bf16 v[46:49], v[156:159], v[172:175], v[46:49]
	v_mfma_f32_16x16x32_bf16 v[42:45], v[164:167], v[172:175], v[42:45]
	v_mfma_f32_16x16x32_bf16 v[30:33], v[156:159], v[180:183], v[30:33]
	v_mfma_f32_16x16x32_bf16 v[26:29], v[164:167], v[180:183], v[26:29]
	v_mfma_f32_16x16x32_bf16 v[14:17], v[156:159], v[188:191], v[14:17]
	v_mfma_f32_16x16x32_bf16 v[10:13], v[164:167], v[188:191], v[10:13]
	v_mfma_f32_16x16x32_bf16 v[6:9], v[156:159], v[204:207], v[6:9]
	v_mfma_f32_16x16x32_bf16 v[2:5], v[164:167], v[204:207], v[2:5]
	v_mfma_f32_16x16x32_bf16 v[46:49], v[160:163], v[176:179], v[46:49]
	v_mfma_f32_16x16x32_bf16 v[42:45], v[168:171], v[176:179], v[42:45]
	v_mfma_f32_16x16x32_bf16 v[30:33], v[160:163], v[184:187], v[30:33]
	v_mfma_f32_16x16x32_bf16 v[26:29], v[168:171], v[184:187], v[26:29]
	v_mfma_f32_16x16x32_bf16 v[14:17], v[160:163], v[192:195], v[14:17]
	v_mfma_f32_16x16x32_bf16 v[10:13], v[168:171], v[192:195], v[10:13]
	v_mfma_f32_16x16x32_bf16 v[6:9], v[160:163], v[208:211], v[6:9]
	v_mfma_f32_16x16x32_bf16 v[2:5], v[168:171], v[208:211], v[2:5]
	s_setprio 0
	s_barrier
	v_add_u32_e32 v139, s51, v1
	ds_read_b128 v[140:143], v139
	ds_read_b128 v[144:147], v139 offset:1024
	ds_read_b128 v[148:151], v139 offset:2048
	ds_read_b128 v[152:155], v139 offset:3072
	v_add_u32_e32 v139, s50, v1
	ds_read_b128 v[156:159], v139
	ds_read_b128 v[160:163], v139 offset:1024
	ds_read_b128 v[164:167], v139 offset:2048
	ds_read_b128 v[168:171], v139 offset:3072
	s_mov_b32 m0, s42
	v_lshl_add_u64 v[230:231], s[14:15], 0, v[130:131]
	ds_read_b128 v[172:175], v138 offset:32768
	ds_read_b128 v[176:179], v138 offset:33792
	ds_read_b128 v[180:183], v138 offset:34816
	ds_read_b128 v[184:187], v138 offset:35840
	ds_read_b128 v[188:191], v138 offset:36864
	ds_read_b128 v[192:195], v138 offset:37888
	ds_read_b128 v[204:207], v138 offset:38912
	ds_read_b128 v[208:211], v138 offset:39936
	global_load_lds_dwordx4 v[230:231], off
	v_lshl_add_u64 v[230:231], s[14:15], 0, v[134:135]
	s_mov_b32 m0, s43
	s_nop 0
	global_load_lds_dwordx4 v[230:231], off
	s_waitcnt vmcnt(8)
	s_waitcnt lgkmcnt(0)
	s_barrier
	s_setprio 1
	s_waitcnt lgkmcnt(0)
	v_mfma_f32_16x16x32_bf16 v[126:129], v[140:143], v[172:175], v[126:129]
	v_mfma_f32_16x16x32_bf16 v[122:125], v[148:151], v[172:175], v[122:125]
	v_mfma_f32_16x16x32_bf16 v[118:121], v[140:143], v[180:183], v[118:121]
	v_mfma_f32_16x16x32_bf16 v[114:117], v[148:151], v[180:183], v[114:117]
	v_mfma_f32_16x16x32_bf16 v[102:105], v[140:143], v[188:191], v[102:105]
	v_mfma_f32_16x16x32_bf16 v[98:101], v[148:151], v[188:191], v[98:101]
	v_mfma_f32_16x16x32_bf16 v[86:89], v[140:143], v[204:207], v[86:89]
	v_mfma_f32_16x16x32_bf16 v[82:85], v[148:151], v[204:207], v[82:85]
	v_mfma_f32_16x16x32_bf16 v[126:129], v[144:147], v[176:179], v[126:129]
	v_mfma_f32_16x16x32_bf16 v[122:125], v[152:155], v[176:179], v[122:125]
	v_mfma_f32_16x16x32_bf16 v[118:121], v[144:147], v[184:187], v[118:121]
	v_mfma_f32_16x16x32_bf16 v[114:117], v[152:155], v[184:187], v[114:117]
	v_mfma_f32_16x16x32_bf16 v[102:105], v[144:147], v[192:195], v[102:105]
	v_mfma_f32_16x16x32_bf16 v[98:101], v[152:155], v[192:195], v[98:101]
	v_mfma_f32_16x16x32_bf16 v[86:89], v[144:147], v[208:211], v[86:89]
	v_mfma_f32_16x16x32_bf16 v[82:85], v[152:155], v[208:211], v[82:85]
	v_mfma_f32_16x16x32_bf16 v[110:113], v[156:159], v[172:175], v[110:113]
	v_mfma_f32_16x16x32_bf16 v[106:109], v[164:167], v[172:175], v[106:109]
	v_mfma_f32_16x16x32_bf16 v[94:97], v[156:159], v[180:183], v[94:97]
	v_mfma_f32_16x16x32_bf16 v[90:93], v[164:167], v[180:183], v[90:93]
	v_mfma_f32_16x16x32_bf16 v[78:81], v[156:159], v[188:191], v[78:81]
	v_mfma_f32_16x16x32_bf16 v[74:77], v[164:167], v[188:191], v[74:77]
	v_mfma_f32_16x16x32_bf16 v[70:73], v[156:159], v[204:207], v[70:73]
	v_mfma_f32_16x16x32_bf16 v[66:69], v[164:167], v[204:207], v[66:69]
	v_mfma_f32_16x16x32_bf16 v[110:113], v[160:163], v[176:179], v[110:113]
	v_mfma_f32_16x16x32_bf16 v[106:109], v[168:171], v[176:179], v[106:109]
	v_mfma_f32_16x16x32_bf16 v[94:97], v[160:163], v[184:187], v[94:97]
	v_mfma_f32_16x16x32_bf16 v[90:93], v[168:171], v[184:187], v[90:93]
	v_mfma_f32_16x16x32_bf16 v[78:81], v[160:163], v[192:195], v[78:81]
	v_mfma_f32_16x16x32_bf16 v[74:77], v[168:171], v[192:195], v[74:77]
	v_mfma_f32_16x16x32_bf16 v[70:73], v[160:163], v[208:211], v[70:73]
	v_mfma_f32_16x16x32_bf16 v[66:69], v[168:171], v[208:211], v[66:69]
	s_setprio 0
	s_barrier
	s_mov_b32 m0, s49
	v_lshl_add_u64 v[212:213], v[212:213], 0, s[94:95]
	ds_read_b128 v[172:175], v138 offset:49152
	ds_read_b128 v[176:179], v138 offset:50176
	ds_read_b128 v[180:183], v138 offset:51200
	ds_read_b128 v[184:187], v138 offset:52224
	ds_read_b128 v[188:191], v138 offset:53248
	ds_read_b128 v[192:195], v138 offset:54272
	ds_read_b128 v[204:207], v138 offset:55296
	ds_read_b128 v[208:211], v138 offset:56320
	global_load_lds_dwordx4 v[212:213], off
	v_lshl_add_u64 v[212:213], v[214:215], 0, s[94:95]
	s_mov_b32 m0, s48
	s_nop 0
	global_load_lds_dwordx4 v[212:213], off
	v_lshl_add_u64 v[212:213], s[12:13], 0, v[132:133]
	s_mov_b32 m0, s57
	s_nop 0
	global_load_lds_dwordx4 v[212:213], off
	v_lshl_add_u64 v[212:213], s[12:13], 0, v[136:137]
	s_mov_b32 m0, s56
	s_nop 0
	global_load_lds_dwordx4 v[212:213], off
	v_lshl_add_u64 v[212:213], v[216:217], 0, s[94:95]
	s_mov_b32 m0, s46
	s_nop 0
	global_load_lds_dwordx4 v[212:213], off
	v_lshl_add_u64 v[212:213], v[228:229], 0, s[94:95]
	s_mov_b32 m0, s47
	s_nop 0
	global_load_lds_dwordx4 v[212:213], off
	s_waitcnt vmcnt(8)
	s_waitcnt lgkmcnt(0)
	s_barrier
	s_setprio 1
	s_waitcnt lgkmcnt(0)
	v_mfma_f32_16x16x32_bf16 v[62:65], v[140:143], v[172:175], v[62:65]
	v_mfma_f32_16x16x32_bf16 v[58:61], v[148:151], v[172:175], v[58:61]
	v_mfma_f32_16x16x32_bf16 v[54:57], v[140:143], v[180:183], v[54:57]
	v_mfma_f32_16x16x32_bf16 v[50:53], v[148:151], v[180:183], v[50:53]
	v_mfma_f32_16x16x32_bf16 v[38:41], v[140:143], v[188:191], v[38:41]
	v_mfma_f32_16x16x32_bf16 v[34:37], v[148:151], v[188:191], v[34:37]
	v_mfma_f32_16x16x32_bf16 v[22:25], v[140:143], v[204:207], v[22:25]
	v_mfma_f32_16x16x32_bf16 v[18:21], v[148:151], v[204:207], v[18:21]
	v_mfma_f32_16x16x32_bf16 v[62:65], v[144:147], v[176:179], v[62:65]
	v_mfma_f32_16x16x32_bf16 v[58:61], v[152:155], v[176:179], v[58:61]
	v_mfma_f32_16x16x32_bf16 v[54:57], v[144:147], v[184:187], v[54:57]
	v_mfma_f32_16x16x32_bf16 v[50:53], v[152:155], v[184:187], v[50:53]
	v_mfma_f32_16x16x32_bf16 v[38:41], v[144:147], v[192:195], v[38:41]
	v_mfma_f32_16x16x32_bf16 v[34:37], v[152:155], v[192:195], v[34:37]
	v_mfma_f32_16x16x32_bf16 v[22:25], v[144:147], v[208:211], v[22:25]
	v_mfma_f32_16x16x32_bf16 v[18:21], v[152:155], v[208:211], v[18:21]
	v_mfma_f32_16x16x32_bf16 v[46:49], v[156:159], v[172:175], v[46:49]
	v_mfma_f32_16x16x32_bf16 v[42:45], v[164:167], v[172:175], v[42:45]
	v_mfma_f32_16x16x32_bf16 v[30:33], v[156:159], v[180:183], v[30:33]
	v_mfma_f32_16x16x32_bf16 v[26:29], v[164:167], v[180:183], v[26:29]
	v_mfma_f32_16x16x32_bf16 v[14:17], v[156:159], v[188:191], v[14:17]
	v_mfma_f32_16x16x32_bf16 v[10:13], v[164:167], v[188:191], v[10:13]
	v_mfma_f32_16x16x32_bf16 v[6:9], v[156:159], v[204:207], v[6:9]
	v_mfma_f32_16x16x32_bf16 v[2:5], v[164:167], v[204:207], v[2:5]
	v_mfma_f32_16x16x32_bf16 v[46:49], v[160:163], v[176:179], v[46:49]
	v_mfma_f32_16x16x32_bf16 v[42:45], v[168:171], v[176:179], v[42:45]
	v_mfma_f32_16x16x32_bf16 v[30:33], v[160:163], v[184:187], v[30:33]
	v_mfma_f32_16x16x32_bf16 v[26:29], v[168:171], v[184:187], v[26:29]
	v_mfma_f32_16x16x32_bf16 v[14:17], v[160:163], v[192:195], v[14:17]
	v_mfma_f32_16x16x32_bf16 v[10:13], v[168:171], v[192:195], v[10:13]
	v_mfma_f32_16x16x32_bf16 v[6:9], v[160:163], v[208:211], v[6:9]
	v_mfma_f32_16x16x32_bf16 v[2:5], v[168:171], v[208:211], v[2:5]
	s_setprio 0
	s_barrier
	s_andn2_b64 vcc, exec, s[8:9]
	s_mov_b64 s[12:13], -1
	s_mov_b64 s[8:9], 0
	s_movk_i32 s14, 0x100
	s_cbranch_vccz .LBB0_260
	s_cmpk_lt_u32 s38, 0x100
	s_cbranch_scc0 .LBB0_246
	s_barrier
	s_branch .LBB0_246

.LBB0_326:
	s_add_u32 s30, s28, 0xfffc0080
	s_addc_u32 s31, s29, -1
	s_add_i32 s72, 0, 0x10000
	s_cmp_eq_u32 s71, 12
	s_cselect_b32 s35, s5, s31
	s_cselect_b32 s34, s21, s30
	s_cselect_b32 s31, s19, s70
	s_cselect_b32 s30, s36, s37
	s_add_i32 s74, 0, 0x14000
	v_add_u32_e32 v154, s72, v1
	v_add_u32_e32 v167, s74, v1
	ds_read_b128 v[142:145], v154
	ds_read_b128 v[146:149], v154 offset:1024
	ds_read_b128 v[150:153], v154 offset:2048
	ds_read_b128 v[154:157], v154 offset:3072
	ds_read_b128 v[158:161], v167
	ds_read_b128 v[162:165], v167 offset:1024
	ds_read_b128 v[168:171], v167 offset:2048
	ds_read_b128 v[172:175], v167 offset:3072
	v_lshl_add_u64 v[216:217], s[28:29], 0, v[138:139]
	s_add_i32 m0, s27, 0xc000
	ds_read_b128 v[176:179], v166
	ds_read_b128 v[180:183], v166 offset:1024
	ds_read_b128 v[184:187], v166 offset:2048
	ds_read_b128 v[188:191], v166 offset:3072
	ds_read_b128 v[192:195], v166 offset:4096
	ds_read_b128 v[204:207], v166 offset:5120
	ds_read_b128 v[208:211], v166 offset:6144
	ds_read_b128 v[212:215], v166 offset:7168
	global_load_lds_dwordx4 v[216:217], off
	v_lshl_add_u64 v[216:217], s[28:29], 0, v[140:141]
	s_add_i32 m0, s27, 0xe000
	s_nop 0
	global_load_lds_dwordx4 v[216:217], off
	s_waitcnt vmcnt(8)
	s_waitcnt lgkmcnt(0)
	s_barrier
	s_setprio 1
	s_waitcnt lgkmcnt(0)
	v_mfma_f32_16x16x32_bf16 v[126:129], v[142:145], v[176:179], v[126:129]
	v_mfma_f32_16x16x32_bf16 v[122:125], v[150:153], v[176:179], v[122:125]
	v_mfma_f32_16x16x32_bf16 v[110:113], v[142:145], v[184:187], v[110:113]
	v_mfma_f32_16x16x32_bf16 v[106:109], v[150:153], v[184:187], v[106:109]
	v_mfma_f32_16x16x32_bf16 v[94:97], v[142:145], v[192:195], v[94:97]
	v_mfma_f32_16x16x32_bf16 v[90:93], v[150:153], v[192:195], v[90:93]
	v_mfma_f32_16x16x32_bf16 v[78:81], v[142:145], v[208:211], v[78:81]
	v_mfma_f32_16x16x32_bf16 v[74:77], v[150:153], v[208:211], v[74:77]
	v_mfma_f32_16x16x32_bf16 v[126:129], v[146:149], v[180:183], v[126:129]
	v_mfma_f32_16x16x32_bf16 v[122:125], v[154:157], v[180:183], v[122:125]
	v_mfma_f32_16x16x32_bf16 v[110:113], v[146:149], v[188:191], v[110:113]
	v_mfma_f32_16x16x32_bf16 v[106:109], v[154:157], v[188:191], v[106:109]
	v_mfma_f32_16x16x32_bf16 v[94:97], v[146:149], v[204:207], v[94:97]
	v_mfma_f32_16x16x32_bf16 v[90:93], v[154:157], v[204:207], v[90:93]
	v_mfma_f32_16x16x32_bf16 v[78:81], v[146:149], v[212:215], v[78:81]
	v_mfma_f32_16x16x32_bf16 v[74:77], v[154:157], v[212:215], v[74:77]
	v_mfma_f32_16x16x32_bf16 v[118:121], v[158:161], v[176:179], v[118:121]
	v_mfma_f32_16x16x32_bf16 v[114:117], v[168:171], v[176:179], v[114:117]
	v_mfma_f32_16x16x32_bf16 v[102:105], v[158:161], v[184:187], v[102:105]
	v_mfma_f32_16x16x32_bf16 v[98:101], v[168:171], v[184:187], v[98:101]
	v_mfma_f32_16x16x32_bf16 v[86:89], v[158:161], v[192:195], v[86:89]
	v_mfma_f32_16x16x32_bf16 v[82:85], v[168:171], v[192:195], v[82:85]
	v_mfma_f32_16x16x32_bf16 v[70:73], v[158:161], v[208:211], v[70:73]
	v_mfma_f32_16x16x32_bf16 v[66:69], v[168:171], v[208:211], v[66:69]
	v_mfma_f32_16x16x32_bf16 v[118:121], v[162:165], v[180:183], v[118:121]
	v_mfma_f32_16x16x32_bf16 v[114:117], v[172:175], v[180:183], v[114:117]
	v_mfma_f32_16x16x32_bf16 v[102:105], v[162:165], v[188:191], v[102:105]
	v_mfma_f32_16x16x32_bf16 v[98:101], v[172:175], v[188:191], v[98:101]
	v_mfma_f32_16x16x32_bf16 v[86:89], v[162:165], v[204:207], v[86:89]
	v_mfma_f32_16x16x32_bf16 v[82:85], v[172:175], v[204:207], v[82:85]
	v_mfma_f32_16x16x32_bf16 v[70:73], v[162:165], v[212:215], v[70:73]
	v_mfma_f32_16x16x32_bf16 v[66:69], v[172:175], v[212:215], v[66:69]
	s_setprio 0
	s_barrier
	s_add_i32 s72, s72, s44
	v_lshl_add_u64 v[216:217], s[30:31], 0, v[132:133]
	s_mov_b32 m0, s72
	ds_read_b128 v[176:179], v166 offset:16384
	ds_read_b128 v[180:183], v166 offset:17408
	ds_read_b128 v[184:187], v166 offset:18432
	ds_read_b128 v[188:191], v166 offset:19456
	ds_read_b128 v[192:195], v166 offset:20480
	ds_read_b128 v[204:207], v166 offset:21504
	ds_read_b128 v[208:211], v166 offset:22528
	ds_read_b128 v[212:215], v166 offset:23552
	global_load_lds_dwordx4 v[216:217], off
	s_add_i32 m0, s72, 0x2000
	s_add_u32 s72, s30, 0x40000
	v_lshl_add_u64 v[228:229], s[30:31], 0, v[136:137]
	s_addc_u32 s73, s31, 0
	s_add_i32 s74, s74, s44
	global_load_lds_dwordx4 v[228:229], off
	v_lshl_add_u64 v[230:231], s[72:73], 0, v[132:133]
	s_mov_b32 m0, s74
	v_lshl_add_u64 v[232:233], s[34:35], 0, v[134:135]
	global_load_lds_dwordx4 v[230:231], off
	v_lshl_add_u64 v[230:231], s[72:73], 0, v[136:137]
	s_add_i32 m0, s74, 0x2000
	s_nop 0
	global_load_lds_dwordx4 v[230:231], off
	v_lshl_add_u64 v[230:231], s[34:35], 0, v[130:131]
	s_mov_b32 m0, s27
	s_nop 0
	global_load_lds_dwordx4 v[230:231], off
	s_mov_b32 m0, s45
	s_nop 0
	global_load_lds_dwordx4 v[232:233], off
	s_waitcnt vmcnt(8)
	s_waitcnt lgkmcnt(0)
	s_barrier
	s_setprio 1
	s_waitcnt lgkmcnt(0)
	v_mfma_f32_16x16x32_bf16 v[62:65], v[142:145], v[176:179], v[62:65]
	v_mfma_f32_16x16x32_bf16 v[58:61], v[150:153], v[176:179], v[58:61]
	v_mfma_f32_16x16x32_bf16 v[46:49], v[142:145], v[184:187], v[46:49]
	v_mfma_f32_16x16x32_bf16 v[42:45], v[150:153], v[184:187], v[42:45]
	v_mfma_f32_16x16x32_bf16 v[30:33], v[142:145], v[192:195], v[30:33]
	v_mfma_f32_16x16x32_bf16 v[26:29], v[150:153], v[192:195], v[26:29]
	v_mfma_f32_16x16x32_bf16 v[14:17], v[142:145], v[208:211], v[14:17]
	v_mfma_f32_16x16x32_bf16 v[10:13], v[150:153], v[208:211], v[10:13]
	v_mfma_f32_16x16x32_bf16 v[62:65], v[146:149], v[180:183], v[62:65]
	v_mfma_f32_16x16x32_bf16 v[58:61], v[154:157], v[180:183], v[58:61]
	v_mfma_f32_16x16x32_bf16 v[46:49], v[146:149], v[188:191], v[46:49]
	v_mfma_f32_16x16x32_bf16 v[42:45], v[154:157], v[188:191], v[42:45]
	v_mfma_f32_16x16x32_bf16 v[30:33], v[146:149], v[204:207], v[30:33]
	v_mfma_f32_16x16x32_bf16 v[26:29], v[154:157], v[204:207], v[26:29]
	v_mfma_f32_16x16x32_bf16 v[14:17], v[146:149], v[212:215], v[14:17]
	v_mfma_f32_16x16x32_bf16 v[10:13], v[154:157], v[212:215], v[10:13]
	v_mfma_f32_16x16x32_bf16 v[54:57], v[158:161], v[176:179], v[54:57]
	v_mfma_f32_16x16x32_bf16 v[50:53], v[168:171], v[176:179], v[50:53]
	v_mfma_f32_16x16x32_bf16 v[38:41], v[158:161], v[184:187], v[38:41]
	v_mfma_f32_16x16x32_bf16 v[34:37], v[168:171], v[184:187], v[34:37]
	v_mfma_f32_16x16x32_bf16 v[22:25], v[158:161], v[192:195], v[22:25]
	v_mfma_f32_16x16x32_bf16 v[18:21], v[168:171], v[192:195], v[18:21]
	v_mfma_f32_16x16x32_bf16 v[6:9], v[158:161], v[208:211], v[6:9]
	v_mfma_f32_16x16x32_bf16 v[2:5], v[168:171], v[208:211], v[2:5]
	v_mfma_f32_16x16x32_bf16 v[54:57], v[162:165], v[180:183], v[54:57]
	v_mfma_f32_16x16x32_bf16 v[50:53], v[172:175], v[180:183], v[50:53]
	v_mfma_f32_16x16x32_bf16 v[38:41], v[162:165], v[188:191], v[38:41]
	v_mfma_f32_16x16x32_bf16 v[34:37], v[172:175], v[188:191], v[34:37]
	v_mfma_f32_16x16x32_bf16 v[22:25], v[162:165], v[204:207], v[22:25]
	v_mfma_f32_16x16x32_bf16 v[18:21], v[172:175], v[204:207], v[18:21]
	v_mfma_f32_16x16x32_bf16 v[6:9], v[162:165], v[212:215], v[6:9]
	v_mfma_f32_16x16x32_bf16 v[2:5], v[172:175], v[212:215], v[2:5]
	s_setprio 0
	s_barrier
	s_add_i32 s72, 0, 0x18000
	s_add_i32 s73, 0, 0x1c000
	v_add_u32_e32 v154, s72, v1
	v_add_u32_e32 v167, s73, v1
	ds_read_b128 v[142:145], v154
	ds_read_b128 v[146:149], v154 offset:1024
	ds_read_b128 v[150:153], v154 offset:2048
	ds_read_b128 v[154:157], v154 offset:3072
	ds_read_b128 v[158:161], v167
	ds_read_b128 v[162:165], v167 offset:1024
	ds_read_b128 v[168:171], v167 offset:2048
	ds_read_b128 v[172:175], v167 offset:3072
	s_add_u32 s34, s34, 0x40000
	s_addc_u32 s35, s35, 0
	s_mov_b32 m0, s46
	v_lshl_add_u64 v[234:235], s[34:35], 0, v[130:131]
	ds_read_b128 v[176:179], v166 offset:32768
	ds_read_b128 v[180:183], v166 offset:33792
	ds_read_b128 v[184:187], v166 offset:34816
	ds_read_b128 v[188:191], v166 offset:35840
	ds_read_b128 v[192:195], v166 offset:36864
	ds_read_b128 v[204:207], v166 offset:37888
	ds_read_b128 v[208:211], v166 offset:38912
	ds_read_b128 v[212:215], v166 offset:39936
	global_load_lds_dwordx4 v[234:235], off
	v_lshl_add_u64 v[234:235], s[34:35], 0, v[134:135]
	s_mov_b32 m0, s47
	s_nop 0
	global_load_lds_dwordx4 v[234:235], off
	s_waitcnt vmcnt(8)
	s_waitcnt lgkmcnt(0)
	s_barrier
	s_setprio 1
	s_waitcnt lgkmcnt(0)
	v_mfma_f32_16x16x32_bf16 v[126:129], v[142:145], v[176:179], v[126:129]
	v_mfma_f32_16x16x32_bf16 v[122:125], v[150:153], v[176:179], v[122:125]
	v_mfma_f32_16x16x32_bf16 v[110:113], v[142:145], v[184:187], v[110:113]
	v_mfma_f32_16x16x32_bf16 v[106:109], v[150:153], v[184:187], v[106:109]
	v_mfma_f32_16x16x32_bf16 v[94:97], v[142:145], v[192:195], v[94:97]
	v_mfma_f32_16x16x32_bf16 v[90:93], v[150:153], v[192:195], v[90:93]
	v_mfma_f32_16x16x32_bf16 v[78:81], v[142:145], v[208:211], v[78:81]
	v_mfma_f32_16x16x32_bf16 v[74:77], v[150:153], v[208:211], v[74:77]
	v_mfma_f32_16x16x32_bf16 v[126:129], v[146:149], v[180:183], v[126:129]
	v_mfma_f32_16x16x32_bf16 v[122:125], v[154:157], v[180:183], v[122:125]
	v_mfma_f32_16x16x32_bf16 v[110:113], v[146:149], v[188:191], v[110:113]
	v_mfma_f32_16x16x32_bf16 v[106:109], v[154:157], v[188:191], v[106:109]
	v_mfma_f32_16x16x32_bf16 v[94:97], v[146:149], v[204:207], v[94:97]
	v_mfma_f32_16x16x32_bf16 v[90:93], v[154:157], v[204:207], v[90:93]
	v_mfma_f32_16x16x32_bf16 v[78:81], v[146:149], v[212:215], v[78:81]
	v_mfma_f32_16x16x32_bf16 v[74:77], v[154:157], v[212:215], v[74:77]
	v_mfma_f32_16x16x32_bf16 v[118:121], v[158:161], v[176:179], v[118:121]
	v_mfma_f32_16x16x32_bf16 v[114:117], v[168:171], v[176:179], v[114:117]
	v_mfma_f32_16x16x32_bf16 v[102:105], v[158:161], v[184:187], v[102:105]
	v_mfma_f32_16x16x32_bf16 v[98:101], v[168:171], v[184:187], v[98:101]
	v_mfma_f32_16x16x32_bf16 v[86:89], v[158:161], v[192:195], v[86:89]
	v_mfma_f32_16x16x32_bf16 v[82:85], v[168:171], v[192:195], v[82:85]
	v_mfma_f32_16x16x32_bf16 v[70:73], v[158:161], v[208:211], v[70:73]
	v_mfma_f32_16x16x32_bf16 v[66:69], v[168:171], v[208:211], v[66:69]
	v_mfma_f32_16x16x32_bf16 v[118:121], v[162:165], v[180:183], v[118:121]
	v_mfma_f32_16x16x32_bf16 v[114:117], v[172:175], v[180:183], v[114:117]
	v_mfma_f32_16x16x32_bf16 v[102:105], v[162:165], v[188:191], v[102:105]
	v_mfma_f32_16x16x32_bf16 v[98:101], v[172:175], v[188:191], v[98:101]
	v_mfma_f32_16x16x32_bf16 v[86:89], v[162:165], v[204:207], v[86:89]
	v_mfma_f32_16x16x32_bf16 v[82:85], v[172:175], v[204:207], v[82:85]
	v_mfma_f32_16x16x32_bf16 v[70:73], v[162:165], v[212:215], v[70:73]
	v_mfma_f32_16x16x32_bf16 v[66:69], v[172:175], v[212:215], v[66:69]
	s_setprio 0
	s_barrier
	s_add_i32 s34, s72, s44
	v_lshl_add_u64 v[216:217], v[216:217], 0, s[94:95]
	s_mov_b32 m0, s34
	ds_read_b128 v[176:179], v166 offset:49152
	ds_read_b128 v[180:183], v166 offset:50176
	ds_read_b128 v[184:187], v166 offset:51200
	ds_read_b128 v[188:191], v166 offset:52224
	ds_read_b128 v[192:195], v166 offset:53248
	ds_read_b128 v[204:207], v166 offset:54272
	ds_read_b128 v[208:211], v166 offset:55296
	ds_read_b128 v[212:215], v166 offset:56320
	global_load_lds_dwordx4 v[216:217], off
	s_add_i32 m0, s34, 0x2000
	s_add_u32 s30, s30, 0x40080
	v_lshl_add_u64 v[216:217], v[228:229], 0, s[94:95]
	s_addc_u32 s31, s31, 0
	s_add_i32 s34, s73, s44
	global_load_lds_dwordx4 v[216:217], off
	v_lshl_add_u64 v[216:217], s[30:31], 0, v[132:133]
	s_mov_b32 m0, s34
	s_nop 0
	global_load_lds_dwordx4 v[216:217], off
	v_lshl_add_u64 v[216:217], s[30:31], 0, v[136:137]
	s_add_i32 m0, s34, 0x2000
	s_nop 0
	global_load_lds_dwordx4 v[216:217], off
	v_lshl_add_u64 v[216:217], v[230:231], 0, s[94:95]
	s_mov_b32 m0, s60
	s_nop 0
	global_load_lds_dwordx4 v[216:217], off
	v_lshl_add_u64 v[216:217], v[232:233], 0, s[94:95]
	s_mov_b32 m0, s61
	s_nop 0
	global_load_lds_dwordx4 v[216:217], off
	s_waitcnt vmcnt(8)
	s_waitcnt lgkmcnt(0)
	s_barrier
	s_setprio 1
	s_waitcnt lgkmcnt(0)
	v_mfma_f32_16x16x32_bf16 v[62:65], v[142:145], v[176:179], v[62:65]
	v_mfma_f32_16x16x32_bf16 v[58:61], v[150:153], v[176:179], v[58:61]
	v_mfma_f32_16x16x32_bf16 v[46:49], v[142:145], v[184:187], v[46:49]
	v_mfma_f32_16x16x32_bf16 v[42:45], v[150:153], v[184:187], v[42:45]
	v_mfma_f32_16x16x32_bf16 v[30:33], v[142:145], v[192:195], v[30:33]
	v_mfma_f32_16x16x32_bf16 v[26:29], v[150:153], v[192:195], v[26:29]
	v_mfma_f32_16x16x32_bf16 v[14:17], v[142:145], v[208:211], v[14:17]
	v_mfma_f32_16x16x32_bf16 v[10:13], v[150:153], v[208:211], v[10:13]
	v_mfma_f32_16x16x32_bf16 v[62:65], v[146:149], v[180:183], v[62:65]
	v_mfma_f32_16x16x32_bf16 v[58:61], v[154:157], v[180:183], v[58:61]
	v_mfma_f32_16x16x32_bf16 v[46:49], v[146:149], v[188:191], v[46:49]
	v_mfma_f32_16x16x32_bf16 v[42:45], v[154:157], v[188:191], v[42:45]
	v_mfma_f32_16x16x32_bf16 v[30:33], v[146:149], v[204:207], v[30:33]
	v_mfma_f32_16x16x32_bf16 v[26:29], v[154:157], v[204:207], v[26:29]
	v_mfma_f32_16x16x32_bf16 v[14:17], v[146:149], v[212:215], v[14:17]
	v_mfma_f32_16x16x32_bf16 v[10:13], v[154:157], v[212:215], v[10:13]
	v_mfma_f32_16x16x32_bf16 v[54:57], v[158:161], v[176:179], v[54:57]
	v_mfma_f32_16x16x32_bf16 v[50:53], v[168:171], v[176:179], v[50:53]
	v_mfma_f32_16x16x32_bf16 v[38:41], v[158:161], v[184:187], v[38:41]
	v_mfma_f32_16x16x32_bf16 v[34:37], v[168:171], v[184:187], v[34:37]
	v_mfma_f32_16x16x32_bf16 v[22:25], v[158:161], v[192:195], v[22:25]
	v_mfma_f32_16x16x32_bf16 v[18:21], v[168:171], v[192:195], v[18:21]
	v_mfma_f32_16x16x32_bf16 v[6:9], v[158:161], v[208:211], v[6:9]
	v_mfma_f32_16x16x32_bf16 v[2:5], v[168:171], v[208:211], v[2:5]
	v_mfma_f32_16x16x32_bf16 v[54:57], v[162:165], v[180:183], v[54:57]
	v_mfma_f32_16x16x32_bf16 v[50:53], v[172:175], v[180:183], v[50:53]
	v_mfma_f32_16x16x32_bf16 v[38:41], v[162:165], v[188:191], v[38:41]
	v_mfma_f32_16x16x32_bf16 v[34:37], v[172:175], v[188:191], v[34:37]
	v_mfma_f32_16x16x32_bf16 v[22:25], v[162:165], v[204:207], v[22:25]
	v_mfma_f32_16x16x32_bf16 v[18:21], v[172:175], v[204:207], v[18:21]
	v_mfma_f32_16x16x32_bf16 v[6:9], v[162:165], v[212:215], v[6:9]
	v_mfma_f32_16x16x32_bf16 v[2:5], v[172:175], v[212:215], v[2:5]
	s_setprio 0
	s_barrier
	s_add_i32 s71, s71, 2
	s_add_u32 s28, s28, 0x100
	s_addc_u32 s29, s29, 0
	s_add_u32 s37, s37, 0x100
	s_addc_u32 s70, s70, 0
	s_cmp_gt_u32 s71, 13
	s_cbranch_scc0 .LBB0_326
	s_and_b64 vcc, exec, s[14:15]
	s_cbranch_vccz .LBB0_329
	s_barrier

.LBB0_807:
	s_add_u32 s36, s26, s34
	s_addc_u32 s37, s27, s35
	s_add_u32 s36, s36, 0x100
	s_addc_u32 s37, s37, 0
	s_add_u32 s65, s62, s34
	s_addc_u32 s66, s63, s35
	s_add_i32 s67, 0, 0x10000
	s_cmpk_eq_i32 s34, 0x700
	s_cselect_b32 s39, s19, s37
	s_cselect_b32 s38, s25, s36
	s_cselect_b32 s37, s17, s66
	s_cselect_b32 s36, s60, s65
	s_add_i32 s65, 0, 0x14000
	v_add_u32_e32 v142, s67, v1
	v_add_u32_e32 v158, s65, v1
	ds_read_b128 v[130:133], v142
	ds_read_b128 v[134:137], v142 offset:1024
	ds_read_b128 v[138:141], v142 offset:2048
	ds_read_b128 v[142:145], v142 offset:3072
	ds_read_b128 v[146:149], v158
	ds_read_b128 v[150:153], v158 offset:1024
	ds_read_b128 v[154:157], v158 offset:2048
	ds_read_b128 v[158:161], v158 offset:3072
	v_lshl_add_u64 v[196:197], v[206:207], 0, s[34:35]
	s_add_i32 m0, s46, 0xc000
	ds_read_b128 v[162:165], v228
	ds_read_b128 v[166:169], v228 offset:1024
	ds_read_b128 v[170:173], v228 offset:2048
	ds_read_b128 v[174:177], v228 offset:3072
	ds_read_b128 v[178:181], v228 offset:4096
	ds_read_b128 v[182:185], v228 offset:5120
	ds_read_b128 v[210:213], v228 offset:6144
	ds_read_b128 v[214:217], v228 offset:7168
	global_load_lds_dwordx4 v[196:197], off
	v_lshl_add_u64 v[196:197], v[208:209], 0, s[34:35]
	s_add_i32 m0, s46, 0xe000
	s_nop 0
	global_load_lds_dwordx4 v[196:197], off
	s_waitcnt vmcnt(8)
	s_waitcnt lgkmcnt(0)
	s_barrier
	s_setprio 1
	s_waitcnt lgkmcnt(0)
	v_mfma_f32_16x16x32_bf16 v[126:129], v[130:133], v[162:165], v[126:129]
	v_mfma_f32_16x16x32_bf16 v[122:125], v[138:141], v[162:165], v[122:125]
	v_mfma_f32_16x16x32_bf16 v[110:113], v[130:133], v[170:173], v[110:113]
	v_mfma_f32_16x16x32_bf16 v[106:109], v[138:141], v[170:173], v[106:109]
	v_mfma_f32_16x16x32_bf16 v[94:97], v[130:133], v[178:181], v[94:97]
	v_mfma_f32_16x16x32_bf16 v[90:93], v[138:141], v[178:181], v[90:93]
	v_mfma_f32_16x16x32_bf16 v[78:81], v[130:133], v[210:213], v[78:81]
	v_mfma_f32_16x16x32_bf16 v[74:77], v[138:141], v[210:213], v[74:77]
	v_mfma_f32_16x16x32_bf16 v[126:129], v[134:137], v[166:169], v[126:129]
	v_mfma_f32_16x16x32_bf16 v[122:125], v[142:145], v[166:169], v[122:125]
	v_mfma_f32_16x16x32_bf16 v[110:113], v[134:137], v[174:177], v[110:113]
	v_mfma_f32_16x16x32_bf16 v[106:109], v[142:145], v[174:177], v[106:109]
	v_mfma_f32_16x16x32_bf16 v[94:97], v[134:137], v[182:185], v[94:97]
	v_mfma_f32_16x16x32_bf16 v[90:93], v[142:145], v[182:185], v[90:93]
	v_mfma_f32_16x16x32_bf16 v[78:81], v[134:137], v[214:217], v[78:81]
	v_mfma_f32_16x16x32_bf16 v[74:77], v[142:145], v[214:217], v[74:77]
	v_mfma_f32_16x16x32_bf16 v[118:121], v[146:149], v[162:165], v[118:121]
	v_mfma_f32_16x16x32_bf16 v[114:117], v[154:157], v[162:165], v[114:117]
	v_mfma_f32_16x16x32_bf16 v[102:105], v[146:149], v[170:173], v[102:105]
	v_mfma_f32_16x16x32_bf16 v[98:101], v[154:157], v[170:173], v[98:101]
	v_mfma_f32_16x16x32_bf16 v[86:89], v[146:149], v[178:181], v[86:89]
	v_mfma_f32_16x16x32_bf16 v[82:85], v[154:157], v[178:181], v[82:85]
	v_mfma_f32_16x16x32_bf16 v[70:73], v[146:149], v[210:213], v[70:73]
	v_mfma_f32_16x16x32_bf16 v[66:69], v[154:157], v[210:213], v[66:69]
	v_mfma_f32_16x16x32_bf16 v[118:121], v[150:153], v[166:169], v[118:121]
	v_mfma_f32_16x16x32_bf16 v[114:117], v[158:161], v[166:169], v[114:117]
	v_mfma_f32_16x16x32_bf16 v[102:105], v[150:153], v[174:177], v[102:105]
	v_mfma_f32_16x16x32_bf16 v[98:101], v[158:161], v[174:177], v[98:101]
	v_mfma_f32_16x16x32_bf16 v[86:89], v[150:153], v[182:185], v[86:89]
	v_mfma_f32_16x16x32_bf16 v[82:85], v[158:161], v[182:185], v[82:85]
	v_mfma_f32_16x16x32_bf16 v[70:73], v[150:153], v[214:217], v[70:73]
	v_mfma_f32_16x16x32_bf16 v[66:69], v[158:161], v[214:217], v[66:69]
	s_setprio 0
	s_barrier
	s_add_i32 s66, s67, s45
	v_lshl_add_u64 v[196:197], s[36:37], 0, v[190:191]
	s_mov_b32 m0, s66
	ds_read_b128 v[162:165], v228 offset:16384
	ds_read_b128 v[166:169], v228 offset:17408
	ds_read_b128 v[170:173], v228 offset:18432
	ds_read_b128 v[174:177], v228 offset:19456
	ds_read_b128 v[178:181], v228 offset:20480
	ds_read_b128 v[182:185], v228 offset:21504
	ds_read_b128 v[210:213], v228 offset:22528
	ds_read_b128 v[214:217], v228 offset:23552
	global_load_lds_dwordx4 v[196:197], off
	s_add_i32 m0, s66, 0x2000
	s_add_u32 s66, s36, 0x40000
	v_lshl_add_u64 v[198:199], s[36:37], 0, v[186:187]
	s_addc_u32 s67, s37, 0
	s_add_i32 s65, s65, s45
	global_load_lds_dwordx4 v[198:199], off
	v_lshl_add_u64 v[220:221], s[66:67], 0, v[190:191]
	s_mov_b32 m0, s65
	v_lshl_add_u64 v[222:223], s[38:39], 0, v[188:189]
	global_load_lds_dwordx4 v[220:221], off
	v_lshl_add_u64 v[220:221], s[66:67], 0, v[186:187]
	s_add_i32 m0, s65, 0x2000
	s_nop 0
	global_load_lds_dwordx4 v[220:221], off
	v_lshl_add_u64 v[220:221], s[38:39], 0, v[192:193]
	s_mov_b32 m0, s46
	s_nop 0
	global_load_lds_dwordx4 v[220:221], off
	s_mov_b32 m0, s47
	s_nop 0
	global_load_lds_dwordx4 v[222:223], off
	s_waitcnt vmcnt(8)
	s_waitcnt lgkmcnt(0)
	s_barrier
	s_setprio 1
	s_waitcnt lgkmcnt(0)
	v_mfma_f32_16x16x32_bf16 v[62:65], v[130:133], v[162:165], v[62:65]
	v_mfma_f32_16x16x32_bf16 v[58:61], v[138:141], v[162:165], v[58:61]
	v_mfma_f32_16x16x32_bf16 v[46:49], v[130:133], v[170:173], v[46:49]
	v_mfma_f32_16x16x32_bf16 v[42:45], v[138:141], v[170:173], v[42:45]
	v_mfma_f32_16x16x32_bf16 v[30:33], v[130:133], v[178:181], v[30:33]
	v_mfma_f32_16x16x32_bf16 v[26:29], v[138:141], v[178:181], v[26:29]
	v_mfma_f32_16x16x32_bf16 v[14:17], v[130:133], v[210:213], v[14:17]
	v_mfma_f32_16x16x32_bf16 v[10:13], v[138:141], v[210:213], v[10:13]
	v_mfma_f32_16x16x32_bf16 v[62:65], v[134:137], v[166:169], v[62:65]
	v_mfma_f32_16x16x32_bf16 v[58:61], v[142:145], v[166:169], v[58:61]
	v_mfma_f32_16x16x32_bf16 v[46:49], v[134:137], v[174:177], v[46:49]
	v_mfma_f32_16x16x32_bf16 v[42:45], v[142:145], v[174:177], v[42:45]
	v_mfma_f32_16x16x32_bf16 v[30:33], v[134:137], v[182:185], v[30:33]
	v_mfma_f32_16x16x32_bf16 v[26:29], v[142:145], v[182:185], v[26:29]
	v_mfma_f32_16x16x32_bf16 v[14:17], v[134:137], v[214:217], v[14:17]
	v_mfma_f32_16x16x32_bf16 v[10:13], v[142:145], v[214:217], v[10:13]
	v_mfma_f32_16x16x32_bf16 v[54:57], v[146:149], v[162:165], v[54:57]
	v_mfma_f32_16x16x32_bf16 v[50:53], v[154:157], v[162:165], v[50:53]
	v_mfma_f32_16x16x32_bf16 v[38:41], v[146:149], v[170:173], v[38:41]
	v_mfma_f32_16x16x32_bf16 v[34:37], v[154:157], v[170:173], v[34:37]
	v_mfma_f32_16x16x32_bf16 v[22:25], v[146:149], v[178:181], v[22:25]
	v_mfma_f32_16x16x32_bf16 v[18:21], v[154:157], v[178:181], v[18:21]
	v_mfma_f32_16x16x32_bf16 v[6:9], v[146:149], v[210:213], v[6:9]
	v_mfma_f32_16x16x32_bf16 v[2:5], v[154:157], v[210:213], v[2:5]
	v_mfma_f32_16x16x32_bf16 v[54:57], v[150:153], v[166:169], v[54:57]
	v_mfma_f32_16x16x32_bf16 v[50:53], v[158:161], v[166:169], v[50:53]
	v_mfma_f32_16x16x32_bf16 v[38:41], v[150:153], v[174:177], v[38:41]
	v_mfma_f32_16x16x32_bf16 v[34:37], v[158:161], v[174:177], v[34:37]
	v_mfma_f32_16x16x32_bf16 v[22:25], v[150:153], v[182:185], v[22:25]
	v_mfma_f32_16x16x32_bf16 v[18:21], v[158:161], v[182:185], v[18:21]
	v_mfma_f32_16x16x32_bf16 v[6:9], v[150:153], v[214:217], v[6:9]
	v_mfma_f32_16x16x32_bf16 v[2:5], v[158:161], v[214:217], v[2:5]
	s_setprio 0
	s_barrier
	s_add_i32 s65, 0, 0x18000
	s_add_i32 s66, 0, 0x1c000
	v_add_u32_e32 v142, s65, v1
	v_add_u32_e32 v158, s66, v1
	ds_read_b128 v[130:133], v142
	ds_read_b128 v[134:137], v142 offset:1024
	ds_read_b128 v[138:141], v142 offset:2048
	ds_read_b128 v[142:145], v142 offset:3072
	ds_read_b128 v[146:149], v158
	ds_read_b128 v[150:153], v158 offset:1024
	ds_read_b128 v[154:157], v158 offset:2048
	ds_read_b128 v[158:161], v158 offset:3072
	s_add_u32 s38, s38, 0x40000
	s_addc_u32 s39, s39, 0
	s_mov_b32 m0, s48
	v_lshl_add_u64 v[230:231], s[38:39], 0, v[192:193]
	ds_read_b128 v[162:165], v228 offset:32768
	ds_read_b128 v[166:169], v228 offset:33792
	ds_read_b128 v[170:173], v228 offset:34816
	ds_read_b128 v[174:177], v228 offset:35840
	ds_read_b128 v[178:181], v228 offset:36864
	ds_read_b128 v[182:185], v228 offset:37888
	ds_read_b128 v[210:213], v228 offset:38912
	ds_read_b128 v[214:217], v228 offset:39936
	global_load_lds_dwordx4 v[230:231], off
	v_lshl_add_u64 v[230:231], s[38:39], 0, v[188:189]
	s_mov_b32 m0, s49
	s_nop 0
	global_load_lds_dwordx4 v[230:231], off
	s_waitcnt vmcnt(8)
	s_waitcnt lgkmcnt(0)
	s_barrier
	s_setprio 1
	s_waitcnt lgkmcnt(0)
	v_mfma_f32_16x16x32_bf16 v[126:129], v[130:133], v[162:165], v[126:129]
	v_mfma_f32_16x16x32_bf16 v[122:125], v[138:141], v[162:165], v[122:125]
	v_mfma_f32_16x16x32_bf16 v[110:113], v[130:133], v[170:173], v[110:113]
	v_mfma_f32_16x16x32_bf16 v[106:109], v[138:141], v[170:173], v[106:109]
	v_mfma_f32_16x16x32_bf16 v[94:97], v[130:133], v[178:181], v[94:97]
	v_mfma_f32_16x16x32_bf16 v[90:93], v[138:141], v[178:181], v[90:93]
	v_mfma_f32_16x16x32_bf16 v[78:81], v[130:133], v[210:213], v[78:81]
	v_mfma_f32_16x16x32_bf16 v[74:77], v[138:141], v[210:213], v[74:77]
	v_mfma_f32_16x16x32_bf16 v[126:129], v[134:137], v[166:169], v[126:129]
	v_mfma_f32_16x16x32_bf16 v[122:125], v[142:145], v[166:169], v[122:125]
	v_mfma_f32_16x16x32_bf16 v[110:113], v[134:137], v[174:177], v[110:113]
	v_mfma_f32_16x16x32_bf16 v[106:109], v[142:145], v[174:177], v[106:109]
	v_mfma_f32_16x16x32_bf16 v[94:97], v[134:137], v[182:185], v[94:97]
	v_mfma_f32_16x16x32_bf16 v[90:93], v[142:145], v[182:185], v[90:93]
	v_mfma_f32_16x16x32_bf16 v[78:81], v[134:137], v[214:217], v[78:81]
	v_mfma_f32_16x16x32_bf16 v[74:77], v[142:145], v[214:217], v[74:77]
	v_mfma_f32_16x16x32_bf16 v[118:121], v[146:149], v[162:165], v[118:121]
	v_mfma_f32_16x16x32_bf16 v[114:117], v[154:157], v[162:165], v[114:117]
	v_mfma_f32_16x16x32_bf16 v[102:105], v[146:149], v[170:173], v[102:105]
	v_mfma_f32_16x16x32_bf16 v[98:101], v[154:157], v[170:173], v[98:101]
	v_mfma_f32_16x16x32_bf16 v[86:89], v[146:149], v[178:181], v[86:89]
	v_mfma_f32_16x16x32_bf16 v[82:85], v[154:157], v[178:181], v[82:85]
	v_mfma_f32_16x16x32_bf16 v[70:73], v[146:149], v[210:213], v[70:73]
	v_mfma_f32_16x16x32_bf16 v[66:69], v[154:157], v[210:213], v[66:69]
	v_mfma_f32_16x16x32_bf16 v[118:121], v[150:153], v[166:169], v[118:121]
	v_mfma_f32_16x16x32_bf16 v[114:117], v[158:161], v[166:169], v[114:117]
	v_mfma_f32_16x16x32_bf16 v[102:105], v[150:153], v[174:177], v[102:105]
	v_mfma_f32_16x16x32_bf16 v[98:101], v[158:161], v[174:177], v[98:101]
	v_mfma_f32_16x16x32_bf16 v[86:89], v[150:153], v[182:185], v[86:89]
	v_mfma_f32_16x16x32_bf16 v[82:85], v[158:161], v[182:185], v[82:85]
	v_mfma_f32_16x16x32_bf16 v[70:73], v[150:153], v[214:217], v[70:73]
	v_mfma_f32_16x16x32_bf16 v[66:69], v[158:161], v[214:217], v[66:69]
	s_setprio 0
	s_barrier
	s_add_i32 s38, s65, s45
	v_lshl_add_u64 v[196:197], v[196:197], 0, s[94:95]
	s_mov_b32 m0, s38
	ds_read_b128 v[162:165], v228 offset:49152
	ds_read_b128 v[166:169], v228 offset:50176
	ds_read_b128 v[170:173], v228 offset:51200
	ds_read_b128 v[174:177], v228 offset:52224
	ds_read_b128 v[178:181], v228 offset:53248
	ds_read_b128 v[182:185], v228 offset:54272
	ds_read_b128 v[210:213], v228 offset:55296
	ds_read_b128 v[214:217], v228 offset:56320
	global_load_lds_dwordx4 v[196:197], off
	s_add_i32 m0, s38, 0x2000
	s_add_u32 s36, s36, 0x40080
	v_lshl_add_u64 v[196:197], v[198:199], 0, s[94:95]
	s_addc_u32 s37, s37, 0
	s_add_i32 s38, s66, s45
	global_load_lds_dwordx4 v[196:197], off
	v_lshl_add_u64 v[196:197], s[36:37], 0, v[190:191]
	s_mov_b32 m0, s38
	s_nop 0
	global_load_lds_dwordx4 v[196:197], off
	v_lshl_add_u64 v[196:197], s[36:37], 0, v[186:187]
	s_add_i32 m0, s38, 0x2000
	s_nop 0
	global_load_lds_dwordx4 v[196:197], off
	v_lshl_add_u64 v[196:197], v[220:221], 0, s[94:95]
	s_mov_b32 m0, s55
	s_nop 0
	global_load_lds_dwordx4 v[196:197], off
	v_lshl_add_u64 v[196:197], v[222:223], 0, s[94:95]
	s_mov_b32 m0, s56
	s_nop 0
	global_load_lds_dwordx4 v[196:197], off
	s_waitcnt vmcnt(8)
	s_waitcnt lgkmcnt(0)
	s_barrier
	s_setprio 1
	s_waitcnt lgkmcnt(0)
	v_mfma_f32_16x16x32_bf16 v[62:65], v[130:133], v[162:165], v[62:65]
	v_mfma_f32_16x16x32_bf16 v[58:61], v[138:141], v[162:165], v[58:61]
	v_mfma_f32_16x16x32_bf16 v[46:49], v[130:133], v[170:173], v[46:49]
	v_mfma_f32_16x16x32_bf16 v[42:45], v[138:141], v[170:173], v[42:45]
	v_mfma_f32_16x16x32_bf16 v[30:33], v[130:133], v[178:181], v[30:33]
	v_mfma_f32_16x16x32_bf16 v[26:29], v[138:141], v[178:181], v[26:29]
	v_mfma_f32_16x16x32_bf16 v[14:17], v[130:133], v[210:213], v[14:17]
	v_mfma_f32_16x16x32_bf16 v[10:13], v[138:141], v[210:213], v[10:13]
	v_mfma_f32_16x16x32_bf16 v[62:65], v[134:137], v[166:169], v[62:65]
	v_mfma_f32_16x16x32_bf16 v[58:61], v[142:145], v[166:169], v[58:61]
	v_mfma_f32_16x16x32_bf16 v[46:49], v[134:137], v[174:177], v[46:49]
	v_mfma_f32_16x16x32_bf16 v[42:45], v[142:145], v[174:177], v[42:45]
	v_mfma_f32_16x16x32_bf16 v[30:33], v[134:137], v[182:185], v[30:33]
	v_mfma_f32_16x16x32_bf16 v[26:29], v[142:145], v[182:185], v[26:29]
	v_mfma_f32_16x16x32_bf16 v[14:17], v[134:137], v[214:217], v[14:17]
	v_mfma_f32_16x16x32_bf16 v[10:13], v[142:145], v[214:217], v[10:13]
	v_mfma_f32_16x16x32_bf16 v[54:57], v[146:149], v[162:165], v[54:57]
	v_mfma_f32_16x16x32_bf16 v[50:53], v[154:157], v[162:165], v[50:53]
	v_mfma_f32_16x16x32_bf16 v[38:41], v[146:149], v[170:173], v[38:41]
	v_mfma_f32_16x16x32_bf16 v[34:37], v[154:157], v[170:173], v[34:37]
	v_mfma_f32_16x16x32_bf16 v[22:25], v[146:149], v[178:181], v[22:25]
	v_mfma_f32_16x16x32_bf16 v[18:21], v[154:157], v[178:181], v[18:21]
	v_mfma_f32_16x16x32_bf16 v[6:9], v[146:149], v[210:213], v[6:9]
	v_mfma_f32_16x16x32_bf16 v[2:5], v[154:157], v[210:213], v[2:5]
	v_mfma_f32_16x16x32_bf16 v[54:57], v[150:153], v[166:169], v[54:57]
	v_mfma_f32_16x16x32_bf16 v[50:53], v[158:161], v[166:169], v[50:53]
	v_mfma_f32_16x16x32_bf16 v[38:41], v[150:153], v[174:177], v[38:41]
	v_mfma_f32_16x16x32_bf16 v[34:37], v[158:161], v[174:177], v[34:37]
	v_mfma_f32_16x16x32_bf16 v[22:25], v[150:153], v[182:185], v[22:25]
	v_mfma_f32_16x16x32_bf16 v[18:21], v[158:161], v[182:185], v[18:21]
	v_mfma_f32_16x16x32_bf16 v[6:9], v[150:153], v[214:217], v[6:9]
	v_mfma_f32_16x16x32_bf16 v[2:5], v[158:161], v[214:217], v[2:5]
	s_setprio 0
	s_barrier
	s_add_i32 s36, s64, 2
	s_add_u32 s34, s34, 0x100
	s_addc_u32 s35, s35, 0
	s_cmp_gt_u32 s64, 13
	s_mov_b32 s64, s36
	s_cbranch_scc1 .LBB0_812

.LBB0_890:
	s_add_u32 s28, s26, 0xfffc0080
	s_addc_u32 s29, s27, -1
	s_add_i32 s55, 0, 0x10000
	s_cmp_eq_u32 s54, 12
	s_cselect_b32 s31, s17, s29
	s_cselect_b32 s30, s23, s28
	s_cselect_b32 s29, s15, s53
	s_cselect_b32 s28, s51, s52
	s_add_i32 s58, 0, 0x14000
	v_add_u32_e32 v134, s55, v1
	v_add_u32_e32 v154, s58, v1
	ds_read_b128 v[110:113], v134
	ds_read_b128 v[118:121], v134 offset:1024
	ds_read_b128 v[122:125], v134 offset:2048
	ds_read_b128 v[134:137], v134 offset:3072
	ds_read_b128 v[138:141], v154
	ds_read_b128 v[142:145], v154 offset:1024
	ds_read_b128 v[146:149], v154 offset:2048
	ds_read_b128 v[154:157], v154 offset:3072
	v_lshl_add_u64 v[196:197], s[26:27], 0, v[206:207]
	s_add_i32 m0, s25, 0xc000
	ds_read_b128 v[162:165], v214
	ds_read_b128 v[166:169], v214 offset:1024
	ds_read_b128 v[170:173], v214 offset:2048
	ds_read_b128 v[174:177], v214 offset:3072
	ds_read_b128 v[178:181], v214 offset:4096
	ds_read_b128 v[182:185], v214 offset:5120
	ds_read_b128 v[186:189], v214 offset:6144
	ds_read_b128 v[210:213], v214 offset:7168
	global_load_lds_dwordx4 v[196:197], off
	v_lshl_add_u64 v[196:197], s[26:27], 0, v[208:209]
	s_add_i32 m0, s25, 0xe000
	s_nop 0
	global_load_lds_dwordx4 v[196:197], off
	s_waitcnt vmcnt(8)
	s_waitcnt lgkmcnt(0)
	s_barrier
	s_setprio 1
	s_waitcnt lgkmcnt(0)
	v_mfma_f32_16x16x32_bf16 v[158:161], v[110:113], v[162:165], v[158:161]
	v_mfma_f32_16x16x32_bf16 v[150:153], v[122:125], v[162:165], v[150:153]
	v_mfma_f32_16x16x32_bf16 v[114:117], v[110:113], v[170:173], v[114:117]
	v_mfma_f32_16x16x32_bf16 v[106:109], v[122:125], v[170:173], v[106:109]
	v_mfma_f32_16x16x32_bf16 v[94:97], v[110:113], v[178:181], v[94:97]
	v_mfma_f32_16x16x32_bf16 v[90:93], v[122:125], v[178:181], v[90:93]
	v_mfma_f32_16x16x32_bf16 v[78:81], v[110:113], v[186:189], v[78:81]
	v_mfma_f32_16x16x32_bf16 v[74:77], v[122:125], v[186:189], v[74:77]
	v_mfma_f32_16x16x32_bf16 v[158:161], v[118:121], v[166:169], v[158:161]
	v_mfma_f32_16x16x32_bf16 v[150:153], v[134:137], v[166:169], v[150:153]
	v_mfma_f32_16x16x32_bf16 v[114:117], v[118:121], v[174:177], v[114:117]
	v_mfma_f32_16x16x32_bf16 v[106:109], v[134:137], v[174:177], v[106:109]
	v_mfma_f32_16x16x32_bf16 v[94:97], v[118:121], v[182:185], v[94:97]
	v_mfma_f32_16x16x32_bf16 v[90:93], v[134:137], v[182:185], v[90:93]
	v_mfma_f32_16x16x32_bf16 v[78:81], v[118:121], v[210:213], v[78:81]
	v_mfma_f32_16x16x32_bf16 v[74:77], v[134:137], v[210:213], v[74:77]
	v_mfma_f32_16x16x32_bf16 v[130:133], v[138:141], v[162:165], v[130:133]
	v_mfma_f32_16x16x32_bf16 v[126:129], v[146:149], v[162:165], v[126:129]
	v_mfma_f32_16x16x32_bf16 v[102:105], v[138:141], v[170:173], v[102:105]
	v_mfma_f32_16x16x32_bf16 v[98:101], v[146:149], v[170:173], v[98:101]
	v_mfma_f32_16x16x32_bf16 v[86:89], v[138:141], v[178:181], v[86:89]
	v_mfma_f32_16x16x32_bf16 v[82:85], v[146:149], v[178:181], v[82:85]
	v_mfma_f32_16x16x32_bf16 v[70:73], v[138:141], v[186:189], v[70:73]
	v_mfma_f32_16x16x32_bf16 v[66:69], v[146:149], v[186:189], v[66:69]
	v_mfma_f32_16x16x32_bf16 v[130:133], v[142:145], v[166:169], v[130:133]
	v_mfma_f32_16x16x32_bf16 v[126:129], v[154:157], v[166:169], v[126:129]
	v_mfma_f32_16x16x32_bf16 v[102:105], v[142:145], v[174:177], v[102:105]
	v_mfma_f32_16x16x32_bf16 v[98:101], v[154:157], v[174:177], v[98:101]
	v_mfma_f32_16x16x32_bf16 v[86:89], v[142:145], v[182:185], v[86:89]
	v_mfma_f32_16x16x32_bf16 v[82:85], v[154:157], v[182:185], v[82:85]
	v_mfma_f32_16x16x32_bf16 v[70:73], v[142:145], v[210:213], v[70:73]
	v_mfma_f32_16x16x32_bf16 v[66:69], v[154:157], v[210:213], v[66:69]
	s_setprio 0
	s_barrier
	s_add_i32 s55, s55, s40
	v_lshl_add_u64 v[196:197], s[28:29], 0, v[192:193]
	s_mov_b32 m0, s55
	ds_read_b128 v[162:165], v214 offset:16384
	ds_read_b128 v[166:169], v214 offset:17408
	ds_read_b128 v[170:173], v214 offset:18432
	ds_read_b128 v[174:177], v214 offset:19456
	ds_read_b128 v[178:181], v214 offset:20480
	ds_read_b128 v[182:185], v214 offset:21504
	ds_read_b128 v[186:189], v214 offset:22528
	ds_read_b128 v[210:213], v214 offset:23552
	global_load_lds_dwordx4 v[196:197], off
	s_add_i32 m0, s55, 0x2000
	s_add_u32 s56, s28, 0x40000
	v_lshl_add_u64 v[198:199], s[28:29], 0, v[204:205]
	s_addc_u32 s57, s29, 0
	s_add_i32 s55, s58, s40
	global_load_lds_dwordx4 v[198:199], off
	v_lshl_add_u64 v[216:217], s[56:57], 0, v[192:193]
	s_mov_b32 m0, s55
	v_lshl_add_u64 v[220:221], s[30:31], 0, v[194:195]
	global_load_lds_dwordx4 v[216:217], off
	v_lshl_add_u64 v[216:217], s[56:57], 0, v[204:205]
	s_add_i32 m0, s55, 0x2000
	s_nop 0
	global_load_lds_dwordx4 v[216:217], off
	v_lshl_add_u64 v[216:217], s[30:31], 0, v[190:191]
	s_mov_b32 m0, s25
	s_nop 0
	global_load_lds_dwordx4 v[216:217], off
	s_mov_b32 m0, s41
	s_nop 0
	global_load_lds_dwordx4 v[220:221], off
	s_waitcnt vmcnt(8)
	s_waitcnt lgkmcnt(0)
	s_barrier
	s_setprio 1
	s_waitcnt lgkmcnt(0)
	v_mfma_f32_16x16x32_bf16 v[62:65], v[110:113], v[162:165], v[62:65]
	v_mfma_f32_16x16x32_bf16 v[58:61], v[122:125], v[162:165], v[58:61]
	v_mfma_f32_16x16x32_bf16 v[46:49], v[110:113], v[170:173], v[46:49]
	v_mfma_f32_16x16x32_bf16 v[42:45], v[122:125], v[170:173], v[42:45]
	v_mfma_f32_16x16x32_bf16 v[30:33], v[110:113], v[178:181], v[30:33]
	v_mfma_f32_16x16x32_bf16 v[26:29], v[122:125], v[178:181], v[26:29]
	v_mfma_f32_16x16x32_bf16 v[14:17], v[110:113], v[186:189], v[14:17]
	v_mfma_f32_16x16x32_bf16 v[10:13], v[122:125], v[186:189], v[10:13]
	v_mfma_f32_16x16x32_bf16 v[62:65], v[118:121], v[166:169], v[62:65]
	v_mfma_f32_16x16x32_bf16 v[58:61], v[134:137], v[166:169], v[58:61]
	v_mfma_f32_16x16x32_bf16 v[46:49], v[118:121], v[174:177], v[46:49]
	v_mfma_f32_16x16x32_bf16 v[42:45], v[134:137], v[174:177], v[42:45]
	v_mfma_f32_16x16x32_bf16 v[30:33], v[118:121], v[182:185], v[30:33]
	v_mfma_f32_16x16x32_bf16 v[26:29], v[134:137], v[182:185], v[26:29]
	v_mfma_f32_16x16x32_bf16 v[14:17], v[118:121], v[210:213], v[14:17]
	v_mfma_f32_16x16x32_bf16 v[10:13], v[134:137], v[210:213], v[10:13]
	v_mfma_f32_16x16x32_bf16 v[54:57], v[138:141], v[162:165], v[54:57]
	v_mfma_f32_16x16x32_bf16 v[50:53], v[146:149], v[162:165], v[50:53]
	v_mfma_f32_16x16x32_bf16 v[38:41], v[138:141], v[170:173], v[38:41]
	v_mfma_f32_16x16x32_bf16 v[34:37], v[146:149], v[170:173], v[34:37]
	v_mfma_f32_16x16x32_bf16 v[22:25], v[138:141], v[178:181], v[22:25]
	v_mfma_f32_16x16x32_bf16 v[18:21], v[146:149], v[178:181], v[18:21]
	v_mfma_f32_16x16x32_bf16 v[6:9], v[138:141], v[186:189], v[6:9]
	v_mfma_f32_16x16x32_bf16 v[2:5], v[146:149], v[186:189], v[2:5]
	v_mfma_f32_16x16x32_bf16 v[54:57], v[142:145], v[166:169], v[54:57]
	v_mfma_f32_16x16x32_bf16 v[50:53], v[154:157], v[166:169], v[50:53]
	v_mfma_f32_16x16x32_bf16 v[38:41], v[142:145], v[174:177], v[38:41]
	v_mfma_f32_16x16x32_bf16 v[34:37], v[154:157], v[174:177], v[34:37]
	v_mfma_f32_16x16x32_bf16 v[22:25], v[142:145], v[182:185], v[22:25]
	v_mfma_f32_16x16x32_bf16 v[18:21], v[154:157], v[182:185], v[18:21]
	v_mfma_f32_16x16x32_bf16 v[6:9], v[142:145], v[210:213], v[6:9]
	v_mfma_f32_16x16x32_bf16 v[2:5], v[154:157], v[210:213], v[2:5]
	s_setprio 0
	s_barrier
	s_add_i32 s55, 0, 0x18000
	s_add_i32 s56, 0, 0x1c000
	v_add_u32_e32 v134, s55, v1
	v_add_u32_e32 v154, s56, v1
	ds_read_b128 v[110:113], v134
	ds_read_b128 v[118:121], v134 offset:1024
	ds_read_b128 v[122:125], v134 offset:2048
	ds_read_b128 v[134:137], v134 offset:3072
	ds_read_b128 v[138:141], v154
	ds_read_b128 v[142:145], v154 offset:1024
	ds_read_b128 v[146:149], v154 offset:2048
	ds_read_b128 v[154:157], v154 offset:3072
	s_add_u32 s30, s30, 0x40000
	s_addc_u32 s31, s31, 0
	s_mov_b32 m0, s42
	v_lshl_add_u64 v[222:223], s[30:31], 0, v[190:191]
	ds_read_b128 v[162:165], v214 offset:32768
	ds_read_b128 v[166:169], v214 offset:33792
	ds_read_b128 v[170:173], v214 offset:34816
	ds_read_b128 v[174:177], v214 offset:35840
	ds_read_b128 v[178:181], v214 offset:36864
	ds_read_b128 v[182:185], v214 offset:37888
	ds_read_b128 v[186:189], v214 offset:38912
	ds_read_b128 v[210:213], v214 offset:39936
	global_load_lds_dwordx4 v[222:223], off
	v_lshl_add_u64 v[222:223], s[30:31], 0, v[194:195]
	s_mov_b32 m0, s43
	s_nop 0
	global_load_lds_dwordx4 v[222:223], off
	s_waitcnt vmcnt(8)
	s_waitcnt lgkmcnt(0)
	s_barrier
	s_setprio 1
	s_waitcnt lgkmcnt(0)
	v_mfma_f32_16x16x32_bf16 v[158:161], v[110:113], v[162:165], v[158:161]
	v_mfma_f32_16x16x32_bf16 v[150:153], v[122:125], v[162:165], v[150:153]
	v_mfma_f32_16x16x32_bf16 v[114:117], v[110:113], v[170:173], v[114:117]
	v_mfma_f32_16x16x32_bf16 v[106:109], v[122:125], v[170:173], v[106:109]
	v_mfma_f32_16x16x32_bf16 v[94:97], v[110:113], v[178:181], v[94:97]
	v_mfma_f32_16x16x32_bf16 v[90:93], v[122:125], v[178:181], v[90:93]
	v_mfma_f32_16x16x32_bf16 v[78:81], v[110:113], v[186:189], v[78:81]
	v_mfma_f32_16x16x32_bf16 v[74:77], v[122:125], v[186:189], v[74:77]
	v_mfma_f32_16x16x32_bf16 v[158:161], v[118:121], v[166:169], v[158:161]
	v_mfma_f32_16x16x32_bf16 v[150:153], v[134:137], v[166:169], v[150:153]
	v_mfma_f32_16x16x32_bf16 v[114:117], v[118:121], v[174:177], v[114:117]
	v_mfma_f32_16x16x32_bf16 v[106:109], v[134:137], v[174:177], v[106:109]
	v_mfma_f32_16x16x32_bf16 v[94:97], v[118:121], v[182:185], v[94:97]
	v_mfma_f32_16x16x32_bf16 v[90:93], v[134:137], v[182:185], v[90:93]
	v_mfma_f32_16x16x32_bf16 v[78:81], v[118:121], v[210:213], v[78:81]
	v_mfma_f32_16x16x32_bf16 v[74:77], v[134:137], v[210:213], v[74:77]
	v_mfma_f32_16x16x32_bf16 v[130:133], v[138:141], v[162:165], v[130:133]
	v_mfma_f32_16x16x32_bf16 v[126:129], v[146:149], v[162:165], v[126:129]
	v_mfma_f32_16x16x32_bf16 v[102:105], v[138:141], v[170:173], v[102:105]
	v_mfma_f32_16x16x32_bf16 v[98:101], v[146:149], v[170:173], v[98:101]
	v_mfma_f32_16x16x32_bf16 v[86:89], v[138:141], v[178:181], v[86:89]
	v_mfma_f32_16x16x32_bf16 v[82:85], v[146:149], v[178:181], v[82:85]
	v_mfma_f32_16x16x32_bf16 v[70:73], v[138:141], v[186:189], v[70:73]
	v_mfma_f32_16x16x32_bf16 v[66:69], v[146:149], v[186:189], v[66:69]
	v_mfma_f32_16x16x32_bf16 v[130:133], v[142:145], v[166:169], v[130:133]
	v_mfma_f32_16x16x32_bf16 v[126:129], v[154:157], v[166:169], v[126:129]
	v_mfma_f32_16x16x32_bf16 v[102:105], v[142:145], v[174:177], v[102:105]
	v_mfma_f32_16x16x32_bf16 v[98:101], v[154:157], v[174:177], v[98:101]
	v_mfma_f32_16x16x32_bf16 v[86:89], v[142:145], v[182:185], v[86:89]
	v_mfma_f32_16x16x32_bf16 v[82:85], v[154:157], v[182:185], v[82:85]
	v_mfma_f32_16x16x32_bf16 v[70:73], v[142:145], v[210:213], v[70:73]
	v_mfma_f32_16x16x32_bf16 v[66:69], v[154:157], v[210:213], v[66:69]
	s_setprio 0
	s_barrier
	s_add_i32 s30, s55, s40
	v_lshl_add_u64 v[196:197], v[196:197], 0, s[94:95]
	s_mov_b32 m0, s30
	ds_read_b128 v[162:165], v214 offset:49152
	ds_read_b128 v[166:169], v214 offset:50176
	ds_read_b128 v[170:173], v214 offset:51200
	ds_read_b128 v[174:177], v214 offset:52224
	ds_read_b128 v[178:181], v214 offset:53248
	ds_read_b128 v[182:185], v214 offset:54272
	ds_read_b128 v[186:189], v214 offset:55296
	ds_read_b128 v[210:213], v214 offset:56320
	global_load_lds_dwordx4 v[196:197], off
	s_add_i32 m0, s30, 0x2000
	s_add_u32 s28, s28, 0x40080
	v_lshl_add_u64 v[196:197], v[198:199], 0, s[94:95]
	s_addc_u32 s29, s29, 0
	s_add_i32 s30, s56, s40
	global_load_lds_dwordx4 v[196:197], off
	v_lshl_add_u64 v[196:197], s[28:29], 0, v[192:193]
	s_mov_b32 m0, s30
	s_nop 0
	global_load_lds_dwordx4 v[196:197], off
	v_lshl_add_u64 v[196:197], s[28:29], 0, v[204:205]
	s_add_i32 m0, s30, 0x2000
	s_nop 0
	global_load_lds_dwordx4 v[196:197], off
	v_lshl_add_u64 v[196:197], v[216:217], 0, s[94:95]
	s_mov_b32 m0, s46
	s_nop 0
	global_load_lds_dwordx4 v[196:197], off
	v_lshl_add_u64 v[196:197], v[220:221], 0, s[94:95]
	s_mov_b32 m0, s47
	s_nop 0
	global_load_lds_dwordx4 v[196:197], off
	s_waitcnt vmcnt(8)
	s_waitcnt lgkmcnt(0)
	s_barrier
	s_setprio 1
	s_waitcnt lgkmcnt(0)
	v_mfma_f32_16x16x32_bf16 v[62:65], v[110:113], v[162:165], v[62:65]
	v_mfma_f32_16x16x32_bf16 v[58:61], v[122:125], v[162:165], v[58:61]
	v_mfma_f32_16x16x32_bf16 v[46:49], v[110:113], v[170:173], v[46:49]
	v_mfma_f32_16x16x32_bf16 v[42:45], v[122:125], v[170:173], v[42:45]
	v_mfma_f32_16x16x32_bf16 v[30:33], v[110:113], v[178:181], v[30:33]
	v_mfma_f32_16x16x32_bf16 v[26:29], v[122:125], v[178:181], v[26:29]
	v_mfma_f32_16x16x32_bf16 v[14:17], v[110:113], v[186:189], v[14:17]
	v_mfma_f32_16x16x32_bf16 v[10:13], v[122:125], v[186:189], v[10:13]
	v_mfma_f32_16x16x32_bf16 v[62:65], v[118:121], v[166:169], v[62:65]
	v_mfma_f32_16x16x32_bf16 v[58:61], v[134:137], v[166:169], v[58:61]
	v_mfma_f32_16x16x32_bf16 v[46:49], v[118:121], v[174:177], v[46:49]
	v_mfma_f32_16x16x32_bf16 v[42:45], v[134:137], v[174:177], v[42:45]
	v_mfma_f32_16x16x32_bf16 v[30:33], v[118:121], v[182:185], v[30:33]
	v_mfma_f32_16x16x32_bf16 v[26:29], v[134:137], v[182:185], v[26:29]
	v_mfma_f32_16x16x32_bf16 v[14:17], v[118:121], v[210:213], v[14:17]
	v_mfma_f32_16x16x32_bf16 v[10:13], v[134:137], v[210:213], v[10:13]
	v_mfma_f32_16x16x32_bf16 v[54:57], v[138:141], v[162:165], v[54:57]
	v_mfma_f32_16x16x32_bf16 v[50:53], v[146:149], v[162:165], v[50:53]
	v_mfma_f32_16x16x32_bf16 v[38:41], v[138:141], v[170:173], v[38:41]
	v_mfma_f32_16x16x32_bf16 v[34:37], v[146:149], v[170:173], v[34:37]
	v_mfma_f32_16x16x32_bf16 v[22:25], v[138:141], v[178:181], v[22:25]
	v_mfma_f32_16x16x32_bf16 v[18:21], v[146:149], v[178:181], v[18:21]
	v_mfma_f32_16x16x32_bf16 v[6:9], v[138:141], v[186:189], v[6:9]
	v_mfma_f32_16x16x32_bf16 v[2:5], v[146:149], v[186:189], v[2:5]
	v_mfma_f32_16x16x32_bf16 v[54:57], v[142:145], v[166:169], v[54:57]
	v_mfma_f32_16x16x32_bf16 v[50:53], v[154:157], v[166:169], v[50:53]
	v_mfma_f32_16x16x32_bf16 v[38:41], v[142:145], v[174:177], v[38:41]
	v_mfma_f32_16x16x32_bf16 v[34:37], v[154:157], v[174:177], v[34:37]
	v_mfma_f32_16x16x32_bf16 v[22:25], v[142:145], v[182:185], v[22:25]
	v_mfma_f32_16x16x32_bf16 v[18:21], v[154:157], v[182:185], v[18:21]
	v_mfma_f32_16x16x32_bf16 v[6:9], v[142:145], v[210:213], v[6:9]
	v_mfma_f32_16x16x32_bf16 v[2:5], v[154:157], v[210:213], v[2:5]
	s_setprio 0
	s_barrier
	s_add_i32 s54, s54, 2
	s_add_u32 s26, s26, 0x100
	s_addc_u32 s27, s27, 0
	s_add_u32 s52, s52, 0x100
	s_addc_u32 s53, s53, 0
	s_cmp_gt_u32 s54, 13
	s_cbranch_scc0 .LBB0_890
	s_and_b64 vcc, exec, s[12:13]
	s_cbranch_vccz .LBB0_893
	s_barrier

.LBB0_984:
	s_add_u32 s28, s4, 0xfffc0080
	s_addc_u32 s29, s5, -1
	s_add_i32 s58, 0, 0x10000
	s_cmp_eq_u32 s57, 12
	s_cselect_b32 s31, s19, s29
	s_cselect_b32 s30, s53, s28
	s_cselect_b32 s29, s17, s56
	s_cselect_b32 s28, s54, s55
	s_add_i32 s60, 0, 0x14000
	v_add_u32_e32 v154, s58, v1
	v_add_u32_e32 v170, s60, v1
	ds_read_b128 v[142:145], v154
	ds_read_b128 v[146:149], v154 offset:1024
	ds_read_b128 v[150:153], v154 offset:2048
	ds_read_b128 v[154:157], v154 offset:3072
	ds_read_b128 v[158:161], v170
	ds_read_b128 v[162:165], v170 offset:1024
	ds_read_b128 v[166:169], v170 offset:2048
	ds_read_b128 v[170:173], v170 offset:3072
	v_lshl_add_u64 v[196:197], s[4:5], 0, v[138:139]
	s_add_i32 m0, s25, 0xc000
	ds_read_b128 v[174:177], v190
	ds_read_b128 v[178:181], v190 offset:1024
	ds_read_b128 v[182:185], v190 offset:2048
	ds_read_b128 v[186:189], v190 offset:3072
	ds_read_b128 v[192:195], v190 offset:4096
	ds_read_b128 v[204:207], v190 offset:5120
	ds_read_b128 v[208:211], v190 offset:6144
	ds_read_b128 v[212:215], v190 offset:7168
	global_load_lds_dwordx4 v[196:197], off
	v_lshl_add_u64 v[196:197], s[4:5], 0, v[140:141]
	s_add_i32 m0, s25, 0xe000
	s_nop 0
	global_load_lds_dwordx4 v[196:197], off
	s_waitcnt vmcnt(8)
	s_waitcnt lgkmcnt(0)
	s_barrier
	s_setprio 1
	s_waitcnt lgkmcnt(0)
	v_mfma_f32_16x16x32_bf16 v[126:129], v[142:145], v[174:177], v[126:129]
	v_mfma_f32_16x16x32_bf16 v[122:125], v[150:153], v[174:177], v[122:125]
	v_mfma_f32_16x16x32_bf16 v[110:113], v[142:145], v[182:185], v[110:113]
	v_mfma_f32_16x16x32_bf16 v[106:109], v[150:153], v[182:185], v[106:109]
	v_mfma_f32_16x16x32_bf16 v[94:97], v[142:145], v[192:195], v[94:97]
	v_mfma_f32_16x16x32_bf16 v[90:93], v[150:153], v[192:195], v[90:93]
	v_mfma_f32_16x16x32_bf16 v[78:81], v[142:145], v[208:211], v[78:81]
	v_mfma_f32_16x16x32_bf16 v[74:77], v[150:153], v[208:211], v[74:77]
	v_mfma_f32_16x16x32_bf16 v[126:129], v[146:149], v[178:181], v[126:129]
	v_mfma_f32_16x16x32_bf16 v[122:125], v[154:157], v[178:181], v[122:125]
	v_mfma_f32_16x16x32_bf16 v[110:113], v[146:149], v[186:189], v[110:113]
	v_mfma_f32_16x16x32_bf16 v[106:109], v[154:157], v[186:189], v[106:109]
	v_mfma_f32_16x16x32_bf16 v[94:97], v[146:149], v[204:207], v[94:97]
	v_mfma_f32_16x16x32_bf16 v[90:93], v[154:157], v[204:207], v[90:93]
	v_mfma_f32_16x16x32_bf16 v[78:81], v[146:149], v[212:215], v[78:81]
	v_mfma_f32_16x16x32_bf16 v[74:77], v[154:157], v[212:215], v[74:77]
	v_mfma_f32_16x16x32_bf16 v[118:121], v[158:161], v[174:177], v[118:121]
	v_mfma_f32_16x16x32_bf16 v[114:117], v[166:169], v[174:177], v[114:117]
	v_mfma_f32_16x16x32_bf16 v[102:105], v[158:161], v[182:185], v[102:105]
	v_mfma_f32_16x16x32_bf16 v[98:101], v[166:169], v[182:185], v[98:101]
	v_mfma_f32_16x16x32_bf16 v[86:89], v[158:161], v[192:195], v[86:89]
	v_mfma_f32_16x16x32_bf16 v[82:85], v[166:169], v[192:195], v[82:85]
	v_mfma_f32_16x16x32_bf16 v[70:73], v[158:161], v[208:211], v[70:73]
	v_mfma_f32_16x16x32_bf16 v[66:69], v[166:169], v[208:211], v[66:69]
	v_mfma_f32_16x16x32_bf16 v[118:121], v[162:165], v[178:181], v[118:121]
	v_mfma_f32_16x16x32_bf16 v[114:117], v[170:173], v[178:181], v[114:117]
	v_mfma_f32_16x16x32_bf16 v[102:105], v[162:165], v[186:189], v[102:105]
	v_mfma_f32_16x16x32_bf16 v[98:101], v[170:173], v[186:189], v[98:101]
	v_mfma_f32_16x16x32_bf16 v[86:89], v[162:165], v[204:207], v[86:89]
	v_mfma_f32_16x16x32_bf16 v[82:85], v[170:173], v[204:207], v[82:85]
	v_mfma_f32_16x16x32_bf16 v[70:73], v[162:165], v[212:215], v[70:73]
	v_mfma_f32_16x16x32_bf16 v[66:69], v[170:173], v[212:215], v[66:69]
	s_setprio 0
	s_barrier
	s_add_i32 s58, s58, s40
	v_lshl_add_u64 v[196:197], s[28:29], 0, v[132:133]
	s_mov_b32 m0, s58
	ds_read_b128 v[174:177], v190 offset:16384
	ds_read_b128 v[178:181], v190 offset:17408
	ds_read_b128 v[182:185], v190 offset:18432
	ds_read_b128 v[186:189], v190 offset:19456
	ds_read_b128 v[192:195], v190 offset:20480
	ds_read_b128 v[204:207], v190 offset:21504
	ds_read_b128 v[208:211], v190 offset:22528
	ds_read_b128 v[212:215], v190 offset:23552
	global_load_lds_dwordx4 v[196:197], off
	s_add_i32 m0, s58, 0x2000
	s_add_u32 s58, s28, 0x40000
	v_lshl_add_u64 v[198:199], s[28:29], 0, v[136:137]
	s_addc_u32 s59, s29, 0
	s_add_i32 s60, s60, s40
	global_load_lds_dwordx4 v[198:199], off
	v_lshl_add_u64 v[216:217], s[58:59], 0, v[132:133]
	s_mov_b32 m0, s60
	v_lshl_add_u64 v[220:221], s[30:31], 0, v[134:135]
	global_load_lds_dwordx4 v[216:217], off
	v_lshl_add_u64 v[216:217], s[58:59], 0, v[136:137]
	s_add_i32 m0, s60, 0x2000
	s_nop 0
	global_load_lds_dwordx4 v[216:217], off
	v_lshl_add_u64 v[216:217], s[30:31], 0, v[130:131]
	s_mov_b32 m0, s25
	s_nop 0
	global_load_lds_dwordx4 v[216:217], off
	s_mov_b32 m0, s27
	s_nop 0
	global_load_lds_dwordx4 v[220:221], off
	s_waitcnt vmcnt(8)
	s_waitcnt lgkmcnt(0)
	s_barrier
	s_setprio 1
	s_waitcnt lgkmcnt(0)
	v_mfma_f32_16x16x32_bf16 v[62:65], v[142:145], v[174:177], v[62:65]
	v_mfma_f32_16x16x32_bf16 v[58:61], v[150:153], v[174:177], v[58:61]
	v_mfma_f32_16x16x32_bf16 v[46:49], v[142:145], v[182:185], v[46:49]
	v_mfma_f32_16x16x32_bf16 v[42:45], v[150:153], v[182:185], v[42:45]
	v_mfma_f32_16x16x32_bf16 v[30:33], v[142:145], v[192:195], v[30:33]
	v_mfma_f32_16x16x32_bf16 v[26:29], v[150:153], v[192:195], v[26:29]
	v_mfma_f32_16x16x32_bf16 v[14:17], v[142:145], v[208:211], v[14:17]
	v_mfma_f32_16x16x32_bf16 v[10:13], v[150:153], v[208:211], v[10:13]
	v_mfma_f32_16x16x32_bf16 v[62:65], v[146:149], v[178:181], v[62:65]
	v_mfma_f32_16x16x32_bf16 v[58:61], v[154:157], v[178:181], v[58:61]
	v_mfma_f32_16x16x32_bf16 v[46:49], v[146:149], v[186:189], v[46:49]
	v_mfma_f32_16x16x32_bf16 v[42:45], v[154:157], v[186:189], v[42:45]
	v_mfma_f32_16x16x32_bf16 v[30:33], v[146:149], v[204:207], v[30:33]
	v_mfma_f32_16x16x32_bf16 v[26:29], v[154:157], v[204:207], v[26:29]
	v_mfma_f32_16x16x32_bf16 v[14:17], v[146:149], v[212:215], v[14:17]
	v_mfma_f32_16x16x32_bf16 v[10:13], v[154:157], v[212:215], v[10:13]
	v_mfma_f32_16x16x32_bf16 v[54:57], v[158:161], v[174:177], v[54:57]
	v_mfma_f32_16x16x32_bf16 v[50:53], v[166:169], v[174:177], v[50:53]
	v_mfma_f32_16x16x32_bf16 v[38:41], v[158:161], v[182:185], v[38:41]
	v_mfma_f32_16x16x32_bf16 v[34:37], v[166:169], v[182:185], v[34:37]
	v_mfma_f32_16x16x32_bf16 v[22:25], v[158:161], v[192:195], v[22:25]
	v_mfma_f32_16x16x32_bf16 v[18:21], v[166:169], v[192:195], v[18:21]
	v_mfma_f32_16x16x32_bf16 v[6:9], v[158:161], v[208:211], v[6:9]
	v_mfma_f32_16x16x32_bf16 v[2:5], v[166:169], v[208:211], v[2:5]
	v_mfma_f32_16x16x32_bf16 v[54:57], v[162:165], v[178:181], v[54:57]
	v_mfma_f32_16x16x32_bf16 v[50:53], v[170:173], v[178:181], v[50:53]
	v_mfma_f32_16x16x32_bf16 v[38:41], v[162:165], v[186:189], v[38:41]
	v_mfma_f32_16x16x32_bf16 v[34:37], v[170:173], v[186:189], v[34:37]
	v_mfma_f32_16x16x32_bf16 v[22:25], v[162:165], v[204:207], v[22:25]
	v_mfma_f32_16x16x32_bf16 v[18:21], v[170:173], v[204:207], v[18:21]
	v_mfma_f32_16x16x32_bf16 v[6:9], v[162:165], v[212:215], v[6:9]
	v_mfma_f32_16x16x32_bf16 v[2:5], v[170:173], v[212:215], v[2:5]
	s_setprio 0
	s_barrier
	s_add_i32 s58, 0, 0x18000
	s_add_i32 s59, 0, 0x1c000
	v_add_u32_e32 v154, s58, v1
	v_add_u32_e32 v170, s59, v1
	ds_read_b128 v[142:145], v154
	ds_read_b128 v[146:149], v154 offset:1024
	ds_read_b128 v[150:153], v154 offset:2048
	ds_read_b128 v[154:157], v154 offset:3072
	ds_read_b128 v[158:161], v170
	ds_read_b128 v[162:165], v170 offset:1024
	ds_read_b128 v[166:169], v170 offset:2048
	ds_read_b128 v[170:173], v170 offset:3072
	s_add_u32 s30, s30, 0x40000
	s_addc_u32 s31, s31, 0
	s_mov_b32 m0, s41
	v_lshl_add_u64 v[222:223], s[30:31], 0, v[130:131]
	ds_read_b128 v[174:177], v190 offset:32768
	ds_read_b128 v[178:181], v190 offset:33792
	ds_read_b128 v[182:185], v190 offset:34816
	ds_read_b128 v[186:189], v190 offset:35840
	ds_read_b128 v[192:195], v190 offset:36864
	ds_read_b128 v[204:207], v190 offset:37888
	ds_read_b128 v[208:211], v190 offset:38912
	ds_read_b128 v[212:215], v190 offset:39936
	global_load_lds_dwordx4 v[222:223], off
	v_lshl_add_u64 v[222:223], s[30:31], 0, v[134:135]
	s_mov_b32 m0, s42
	s_nop 0
	global_load_lds_dwordx4 v[222:223], off
	s_waitcnt vmcnt(8)
	s_waitcnt lgkmcnt(0)
	s_barrier
	s_setprio 1
	s_waitcnt lgkmcnt(0)
	v_mfma_f32_16x16x32_bf16 v[126:129], v[142:145], v[174:177], v[126:129]
	v_mfma_f32_16x16x32_bf16 v[122:125], v[150:153], v[174:177], v[122:125]
	v_mfma_f32_16x16x32_bf16 v[110:113], v[142:145], v[182:185], v[110:113]
	v_mfma_f32_16x16x32_bf16 v[106:109], v[150:153], v[182:185], v[106:109]
	v_mfma_f32_16x16x32_bf16 v[94:97], v[142:145], v[192:195], v[94:97]
	v_mfma_f32_16x16x32_bf16 v[90:93], v[150:153], v[192:195], v[90:93]
	v_mfma_f32_16x16x32_bf16 v[78:81], v[142:145], v[208:211], v[78:81]
	v_mfma_f32_16x16x32_bf16 v[74:77], v[150:153], v[208:211], v[74:77]
	v_mfma_f32_16x16x32_bf16 v[126:129], v[146:149], v[178:181], v[126:129]
	v_mfma_f32_16x16x32_bf16 v[122:125], v[154:157], v[178:181], v[122:125]
	v_mfma_f32_16x16x32_bf16 v[110:113], v[146:149], v[186:189], v[110:113]
	v_mfma_f32_16x16x32_bf16 v[106:109], v[154:157], v[186:189], v[106:109]
	v_mfma_f32_16x16x32_bf16 v[94:97], v[146:149], v[204:207], v[94:97]
	v_mfma_f32_16x16x32_bf16 v[90:93], v[154:157], v[204:207], v[90:93]
	v_mfma_f32_16x16x32_bf16 v[78:81], v[146:149], v[212:215], v[78:81]
	v_mfma_f32_16x16x32_bf16 v[74:77], v[154:157], v[212:215], v[74:77]
	v_mfma_f32_16x16x32_bf16 v[118:121], v[158:161], v[174:177], v[118:121]
	v_mfma_f32_16x16x32_bf16 v[114:117], v[166:169], v[174:177], v[114:117]
	v_mfma_f32_16x16x32_bf16 v[102:105], v[158:161], v[182:185], v[102:105]
	v_mfma_f32_16x16x32_bf16 v[98:101], v[166:169], v[182:185], v[98:101]
	v_mfma_f32_16x16x32_bf16 v[86:89], v[158:161], v[192:195], v[86:89]
	v_mfma_f32_16x16x32_bf16 v[82:85], v[166:169], v[192:195], v[82:85]
	v_mfma_f32_16x16x32_bf16 v[70:73], v[158:161], v[208:211], v[70:73]
	v_mfma_f32_16x16x32_bf16 v[66:69], v[166:169], v[208:211], v[66:69]
	v_mfma_f32_16x16x32_bf16 v[118:121], v[162:165], v[178:181], v[118:121]
	v_mfma_f32_16x16x32_bf16 v[114:117], v[170:173], v[178:181], v[114:117]
	v_mfma_f32_16x16x32_bf16 v[102:105], v[162:165], v[186:189], v[102:105]
	v_mfma_f32_16x16x32_bf16 v[98:101], v[170:173], v[186:189], v[98:101]
	v_mfma_f32_16x16x32_bf16 v[86:89], v[162:165], v[204:207], v[86:89]
	v_mfma_f32_16x16x32_bf16 v[82:85], v[170:173], v[204:207], v[82:85]
	v_mfma_f32_16x16x32_bf16 v[70:73], v[162:165], v[212:215], v[70:73]
	v_mfma_f32_16x16x32_bf16 v[66:69], v[170:173], v[212:215], v[66:69]
	s_setprio 0
	s_barrier
	s_add_i32 s30, s58, s40
	v_lshl_add_u64 v[196:197], v[196:197], 0, s[94:95]
	s_mov_b32 m0, s30
	ds_read_b128 v[174:177], v190 offset:49152
	ds_read_b128 v[178:181], v190 offset:50176
	ds_read_b128 v[182:185], v190 offset:51200
	ds_read_b128 v[186:189], v190 offset:52224
	ds_read_b128 v[192:195], v190 offset:53248
	ds_read_b128 v[204:207], v190 offset:54272
	ds_read_b128 v[208:211], v190 offset:55296
	ds_read_b128 v[212:215], v190 offset:56320
	global_load_lds_dwordx4 v[196:197], off
	s_add_i32 m0, s30, 0x2000
	s_add_u32 s28, s28, 0x40080
	v_lshl_add_u64 v[196:197], v[198:199], 0, s[94:95]
	s_addc_u32 s29, s29, 0
	s_add_i32 s30, s59, s40
	global_load_lds_dwordx4 v[196:197], off
	v_lshl_add_u64 v[196:197], s[28:29], 0, v[132:133]
	s_mov_b32 m0, s30
	s_nop 0
	global_load_lds_dwordx4 v[196:197], off
	v_lshl_add_u64 v[196:197], s[28:29], 0, v[136:137]
	s_add_i32 m0, s30, 0x2000
	s_nop 0
	global_load_lds_dwordx4 v[196:197], off
	v_lshl_add_u64 v[196:197], v[216:217], 0, s[94:95]
	s_mov_b32 m0, s45
	s_nop 0
	global_load_lds_dwordx4 v[196:197], off
	v_lshl_add_u64 v[196:197], v[220:221], 0, s[94:95]
	s_mov_b32 m0, s46
	s_nop 0
	global_load_lds_dwordx4 v[196:197], off
	s_waitcnt vmcnt(8)
	s_waitcnt lgkmcnt(0)
	s_barrier
	s_setprio 1
	s_waitcnt lgkmcnt(0)
	v_mfma_f32_16x16x32_bf16 v[62:65], v[142:145], v[174:177], v[62:65]
	v_mfma_f32_16x16x32_bf16 v[58:61], v[150:153], v[174:177], v[58:61]
	v_mfma_f32_16x16x32_bf16 v[46:49], v[142:145], v[182:185], v[46:49]
	v_mfma_f32_16x16x32_bf16 v[42:45], v[150:153], v[182:185], v[42:45]
	v_mfma_f32_16x16x32_bf16 v[30:33], v[142:145], v[192:195], v[30:33]
	v_mfma_f32_16x16x32_bf16 v[26:29], v[150:153], v[192:195], v[26:29]
	v_mfma_f32_16x16x32_bf16 v[14:17], v[142:145], v[208:211], v[14:17]
	v_mfma_f32_16x16x32_bf16 v[10:13], v[150:153], v[208:211], v[10:13]
	v_mfma_f32_16x16x32_bf16 v[62:65], v[146:149], v[178:181], v[62:65]
	v_mfma_f32_16x16x32_bf16 v[58:61], v[154:157], v[178:181], v[58:61]
	v_mfma_f32_16x16x32_bf16 v[46:49], v[146:149], v[186:189], v[46:49]
	v_mfma_f32_16x16x32_bf16 v[42:45], v[154:157], v[186:189], v[42:45]
	v_mfma_f32_16x16x32_bf16 v[30:33], v[146:149], v[204:207], v[30:33]
	v_mfma_f32_16x16x32_bf16 v[26:29], v[154:157], v[204:207], v[26:29]
	v_mfma_f32_16x16x32_bf16 v[14:17], v[146:149], v[212:215], v[14:17]
	v_mfma_f32_16x16x32_bf16 v[10:13], v[154:157], v[212:215], v[10:13]
	v_mfma_f32_16x16x32_bf16 v[54:57], v[158:161], v[174:177], v[54:57]
	v_mfma_f32_16x16x32_bf16 v[50:53], v[166:169], v[174:177], v[50:53]
	v_mfma_f32_16x16x32_bf16 v[38:41], v[158:161], v[182:185], v[38:41]
	v_mfma_f32_16x16x32_bf16 v[34:37], v[166:169], v[182:185], v[34:37]
	v_mfma_f32_16x16x32_bf16 v[22:25], v[158:161], v[192:195], v[22:25]
	v_mfma_f32_16x16x32_bf16 v[18:21], v[166:169], v[192:195], v[18:21]
	v_mfma_f32_16x16x32_bf16 v[6:9], v[158:161], v[208:211], v[6:9]
	v_mfma_f32_16x16x32_bf16 v[2:5], v[166:169], v[208:211], v[2:5]
	v_mfma_f32_16x16x32_bf16 v[54:57], v[162:165], v[178:181], v[54:57]
	v_mfma_f32_16x16x32_bf16 v[50:53], v[170:173], v[178:181], v[50:53]
	v_mfma_f32_16x16x32_bf16 v[38:41], v[162:165], v[186:189], v[38:41]
	v_mfma_f32_16x16x32_bf16 v[34:37], v[170:173], v[186:189], v[34:37]
	v_mfma_f32_16x16x32_bf16 v[22:25], v[162:165], v[204:207], v[22:25]
	v_mfma_f32_16x16x32_bf16 v[18:21], v[170:173], v[204:207], v[18:21]
	v_mfma_f32_16x16x32_bf16 v[6:9], v[162:165], v[212:215], v[6:9]
	v_mfma_f32_16x16x32_bf16 v[2:5], v[170:173], v[212:215], v[2:5]
	s_setprio 0
	s_barrier
	s_add_i32 s57, s57, 2
	s_add_u32 s4, s4, 0x100
	s_addc_u32 s5, s5, 0
	s_add_u32 s55, s55, 0x100
	s_addc_u32 s56, s56, 0
	s_cmp_gt_u32 s57, 13
	s_cbranch_scc0 .LBB0_984
	s_and_b64 vcc, exec, s[14:15]
	s_cbranch_vccz .LBB0_987
	s_barrier

.LBB0_1096:
	s_add_u32 s28, s4, 0xfffc0080
	s_addc_u32 s29, s5, -1
	s_add_i32 s53, 0, 0x10000
	s_cmp_eq_u32 s52, 12
	s_cselect_b32 s31, s17, s29
	s_cselect_b32 s30, s19, s28
	s_cselect_b32 s29, s21, s51
	s_cselect_b32 s28, s20, s50
	s_add_i32 s56, 0, 0x14000
	v_add_u32_e32 v134, s53, v1
	v_add_u32_e32 v154, s56, v1
	ds_read_b128 v[110:113], v134
	ds_read_b128 v[118:121], v134 offset:1024
	ds_read_b128 v[122:125], v134 offset:2048
	ds_read_b128 v[134:137], v134 offset:3072
	ds_read_b128 v[138:141], v154
	ds_read_b128 v[142:145], v154 offset:1024
	ds_read_b128 v[146:149], v154 offset:2048
	ds_read_b128 v[154:157], v154 offset:3072
	v_lshl_add_u64 v[196:197], s[4:5], 0, v[206:207]
	s_add_i32 m0, s25, 0xc000
	ds_read_b128 v[162:165], v214
	ds_read_b128 v[166:169], v214 offset:1024
	ds_read_b128 v[170:173], v214 offset:2048
	ds_read_b128 v[174:177], v214 offset:3072
	ds_read_b128 v[178:181], v214 offset:4096
	ds_read_b128 v[182:185], v214 offset:5120
	ds_read_b128 v[186:189], v214 offset:6144
	ds_read_b128 v[210:213], v214 offset:7168
	global_load_lds_dwordx4 v[196:197], off
	v_lshl_add_u64 v[196:197], s[4:5], 0, v[208:209]
	s_add_i32 m0, s25, 0xe000
	s_nop 0
	global_load_lds_dwordx4 v[196:197], off
	s_waitcnt vmcnt(8)
	s_waitcnt lgkmcnt(0)
	s_barrier
	s_setprio 1
	s_waitcnt lgkmcnt(0)
	v_mfma_f32_16x16x32_bf16 v[158:161], v[110:113], v[162:165], v[158:161]
	v_mfma_f32_16x16x32_bf16 v[150:153], v[122:125], v[162:165], v[150:153]
	v_mfma_f32_16x16x32_bf16 v[114:117], v[110:113], v[170:173], v[114:117]
	v_mfma_f32_16x16x32_bf16 v[106:109], v[122:125], v[170:173], v[106:109]
	v_mfma_f32_16x16x32_bf16 v[94:97], v[110:113], v[178:181], v[94:97]
	v_mfma_f32_16x16x32_bf16 v[90:93], v[122:125], v[178:181], v[90:93]
	v_mfma_f32_16x16x32_bf16 v[78:81], v[110:113], v[186:189], v[78:81]
	v_mfma_f32_16x16x32_bf16 v[74:77], v[122:125], v[186:189], v[74:77]
	v_mfma_f32_16x16x32_bf16 v[158:161], v[118:121], v[166:169], v[158:161]
	v_mfma_f32_16x16x32_bf16 v[150:153], v[134:137], v[166:169], v[150:153]
	v_mfma_f32_16x16x32_bf16 v[114:117], v[118:121], v[174:177], v[114:117]
	v_mfma_f32_16x16x32_bf16 v[106:109], v[134:137], v[174:177], v[106:109]
	v_mfma_f32_16x16x32_bf16 v[94:97], v[118:121], v[182:185], v[94:97]
	v_mfma_f32_16x16x32_bf16 v[90:93], v[134:137], v[182:185], v[90:93]
	v_mfma_f32_16x16x32_bf16 v[78:81], v[118:121], v[210:213], v[78:81]
	v_mfma_f32_16x16x32_bf16 v[74:77], v[134:137], v[210:213], v[74:77]
	v_mfma_f32_16x16x32_bf16 v[130:133], v[138:141], v[162:165], v[130:133]
	v_mfma_f32_16x16x32_bf16 v[126:129], v[146:149], v[162:165], v[126:129]
	v_mfma_f32_16x16x32_bf16 v[102:105], v[138:141], v[170:173], v[102:105]
	v_mfma_f32_16x16x32_bf16 v[98:101], v[146:149], v[170:173], v[98:101]
	v_mfma_f32_16x16x32_bf16 v[86:89], v[138:141], v[178:181], v[86:89]
	v_mfma_f32_16x16x32_bf16 v[82:85], v[146:149], v[178:181], v[82:85]
	v_mfma_f32_16x16x32_bf16 v[70:73], v[138:141], v[186:189], v[70:73]
	v_mfma_f32_16x16x32_bf16 v[66:69], v[146:149], v[186:189], v[66:69]
	v_mfma_f32_16x16x32_bf16 v[130:133], v[142:145], v[166:169], v[130:133]
	v_mfma_f32_16x16x32_bf16 v[126:129], v[154:157], v[166:169], v[126:129]
	v_mfma_f32_16x16x32_bf16 v[102:105], v[142:145], v[174:177], v[102:105]
	v_mfma_f32_16x16x32_bf16 v[98:101], v[154:157], v[174:177], v[98:101]
	v_mfma_f32_16x16x32_bf16 v[86:89], v[142:145], v[182:185], v[86:89]
	v_mfma_f32_16x16x32_bf16 v[82:85], v[154:157], v[182:185], v[82:85]
	v_mfma_f32_16x16x32_bf16 v[70:73], v[142:145], v[210:213], v[70:73]
	v_mfma_f32_16x16x32_bf16 v[66:69], v[154:157], v[210:213], v[66:69]
	s_setprio 0
	s_barrier
	s_add_i32 s53, s53, s40
	v_lshl_add_u64 v[196:197], s[28:29], 0, v[192:193]
	s_mov_b32 m0, s53
	ds_read_b128 v[162:165], v214 offset:16384
	ds_read_b128 v[166:169], v214 offset:17408
	ds_read_b128 v[170:173], v214 offset:18432
	ds_read_b128 v[174:177], v214 offset:19456
	ds_read_b128 v[178:181], v214 offset:20480
	ds_read_b128 v[182:185], v214 offset:21504
	ds_read_b128 v[186:189], v214 offset:22528
	ds_read_b128 v[210:213], v214 offset:23552
	global_load_lds_dwordx4 v[196:197], off
	s_add_i32 m0, s53, 0x2000
	s_add_u32 s54, s28, 0x40000
	v_lshl_add_u64 v[198:199], s[28:29], 0, v[204:205]
	s_addc_u32 s55, s29, 0
	s_add_i32 s53, s56, s40
	global_load_lds_dwordx4 v[198:199], off
	v_lshl_add_u64 v[216:217], s[54:55], 0, v[192:193]
	s_mov_b32 m0, s53
	v_lshl_add_u64 v[220:221], s[30:31], 0, v[194:195]
	global_load_lds_dwordx4 v[216:217], off
	v_lshl_add_u64 v[216:217], s[54:55], 0, v[204:205]
	s_add_i32 m0, s53, 0x2000
	s_nop 0
	global_load_lds_dwordx4 v[216:217], off
	v_lshl_add_u64 v[216:217], s[30:31], 0, v[190:191]
	s_mov_b32 m0, s25
	s_nop 0
	global_load_lds_dwordx4 v[216:217], off
	s_mov_b32 m0, s27
	s_nop 0
	global_load_lds_dwordx4 v[220:221], off
	s_waitcnt vmcnt(8)
	s_waitcnt lgkmcnt(0)
	s_barrier
	s_setprio 1
	s_waitcnt lgkmcnt(0)
	v_mfma_f32_16x16x32_bf16 v[62:65], v[110:113], v[162:165], v[62:65]
	v_mfma_f32_16x16x32_bf16 v[58:61], v[122:125], v[162:165], v[58:61]
	v_mfma_f32_16x16x32_bf16 v[46:49], v[110:113], v[170:173], v[46:49]
	v_mfma_f32_16x16x32_bf16 v[42:45], v[122:125], v[170:173], v[42:45]
	v_mfma_f32_16x16x32_bf16 v[30:33], v[110:113], v[178:181], v[30:33]
	v_mfma_f32_16x16x32_bf16 v[26:29], v[122:125], v[178:181], v[26:29]
	v_mfma_f32_16x16x32_bf16 v[14:17], v[110:113], v[186:189], v[14:17]
	v_mfma_f32_16x16x32_bf16 v[10:13], v[122:125], v[186:189], v[10:13]
	v_mfma_f32_16x16x32_bf16 v[62:65], v[118:121], v[166:169], v[62:65]
	v_mfma_f32_16x16x32_bf16 v[58:61], v[134:137], v[166:169], v[58:61]
	v_mfma_f32_16x16x32_bf16 v[46:49], v[118:121], v[174:177], v[46:49]
	v_mfma_f32_16x16x32_bf16 v[42:45], v[134:137], v[174:177], v[42:45]
	v_mfma_f32_16x16x32_bf16 v[30:33], v[118:121], v[182:185], v[30:33]
	v_mfma_f32_16x16x32_bf16 v[26:29], v[134:137], v[182:185], v[26:29]
	v_mfma_f32_16x16x32_bf16 v[14:17], v[118:121], v[210:213], v[14:17]
	v_mfma_f32_16x16x32_bf16 v[10:13], v[134:137], v[210:213], v[10:13]
	v_mfma_f32_16x16x32_bf16 v[54:57], v[138:141], v[162:165], v[54:57]
	v_mfma_f32_16x16x32_bf16 v[50:53], v[146:149], v[162:165], v[50:53]
	v_mfma_f32_16x16x32_bf16 v[38:41], v[138:141], v[170:173], v[38:41]
	v_mfma_f32_16x16x32_bf16 v[34:37], v[146:149], v[170:173], v[34:37]
	v_mfma_f32_16x16x32_bf16 v[22:25], v[138:141], v[178:181], v[22:25]
	v_mfma_f32_16x16x32_bf16 v[18:21], v[146:149], v[178:181], v[18:21]
	v_mfma_f32_16x16x32_bf16 v[6:9], v[138:141], v[186:189], v[6:9]
	v_mfma_f32_16x16x32_bf16 v[2:5], v[146:149], v[186:189], v[2:5]
	v_mfma_f32_16x16x32_bf16 v[54:57], v[142:145], v[166:169], v[54:57]
	v_mfma_f32_16x16x32_bf16 v[50:53], v[154:157], v[166:169], v[50:53]
	v_mfma_f32_16x16x32_bf16 v[38:41], v[142:145], v[174:177], v[38:41]
	v_mfma_f32_16x16x32_bf16 v[34:37], v[154:157], v[174:177], v[34:37]
	v_mfma_f32_16x16x32_bf16 v[22:25], v[142:145], v[182:185], v[22:25]
	v_mfma_f32_16x16x32_bf16 v[18:21], v[154:157], v[182:185], v[18:21]
	v_mfma_f32_16x16x32_bf16 v[6:9], v[142:145], v[210:213], v[6:9]
	v_mfma_f32_16x16x32_bf16 v[2:5], v[154:157], v[210:213], v[2:5]
	s_setprio 0
	s_barrier
	s_add_i32 s53, 0, 0x18000
	s_add_i32 s54, 0, 0x1c000
	v_add_u32_e32 v134, s53, v1
	v_add_u32_e32 v154, s54, v1
	ds_read_b128 v[110:113], v134
	ds_read_b128 v[118:121], v134 offset:1024
	ds_read_b128 v[122:125], v134 offset:2048
	ds_read_b128 v[134:137], v134 offset:3072
	ds_read_b128 v[138:141], v154
	ds_read_b128 v[142:145], v154 offset:1024
	ds_read_b128 v[146:149], v154 offset:2048
	ds_read_b128 v[154:157], v154 offset:3072
	s_add_u32 s30, s30, 0x40000
	s_addc_u32 s31, s31, 0
	s_mov_b32 m0, s41
	v_lshl_add_u64 v[222:223], s[30:31], 0, v[190:191]
	ds_read_b128 v[162:165], v214 offset:32768
	ds_read_b128 v[166:169], v214 offset:33792
	ds_read_b128 v[170:173], v214 offset:34816
	ds_read_b128 v[174:177], v214 offset:35840
	ds_read_b128 v[178:181], v214 offset:36864
	ds_read_b128 v[182:185], v214 offset:37888
	ds_read_b128 v[186:189], v214 offset:38912
	ds_read_b128 v[210:213], v214 offset:39936
	global_load_lds_dwordx4 v[222:223], off
	v_lshl_add_u64 v[222:223], s[30:31], 0, v[194:195]
	s_mov_b32 m0, s42
	s_nop 0
	global_load_lds_dwordx4 v[222:223], off
	s_waitcnt vmcnt(8)
	s_waitcnt lgkmcnt(0)
	s_barrier
	s_setprio 1
	s_waitcnt lgkmcnt(0)
	v_mfma_f32_16x16x32_bf16 v[158:161], v[110:113], v[162:165], v[158:161]
	v_mfma_f32_16x16x32_bf16 v[150:153], v[122:125], v[162:165], v[150:153]
	v_mfma_f32_16x16x32_bf16 v[114:117], v[110:113], v[170:173], v[114:117]
	v_mfma_f32_16x16x32_bf16 v[106:109], v[122:125], v[170:173], v[106:109]
	v_mfma_f32_16x16x32_bf16 v[94:97], v[110:113], v[178:181], v[94:97]
	v_mfma_f32_16x16x32_bf16 v[90:93], v[122:125], v[178:181], v[90:93]
	v_mfma_f32_16x16x32_bf16 v[78:81], v[110:113], v[186:189], v[78:81]
	v_mfma_f32_16x16x32_bf16 v[74:77], v[122:125], v[186:189], v[74:77]
	v_mfma_f32_16x16x32_bf16 v[158:161], v[118:121], v[166:169], v[158:161]
	v_mfma_f32_16x16x32_bf16 v[150:153], v[134:137], v[166:169], v[150:153]
	v_mfma_f32_16x16x32_bf16 v[114:117], v[118:121], v[174:177], v[114:117]
	v_mfma_f32_16x16x32_bf16 v[106:109], v[134:137], v[174:177], v[106:109]
	v_mfma_f32_16x16x32_bf16 v[94:97], v[118:121], v[182:185], v[94:97]
	v_mfma_f32_16x16x32_bf16 v[90:93], v[134:137], v[182:185], v[90:93]
	v_mfma_f32_16x16x32_bf16 v[78:81], v[118:121], v[210:213], v[78:81]
	v_mfma_f32_16x16x32_bf16 v[74:77], v[134:137], v[210:213], v[74:77]
	v_mfma_f32_16x16x32_bf16 v[130:133], v[138:141], v[162:165], v[130:133]
	v_mfma_f32_16x16x32_bf16 v[126:129], v[146:149], v[162:165], v[126:129]
	v_mfma_f32_16x16x32_bf16 v[102:105], v[138:141], v[170:173], v[102:105]
	v_mfma_f32_16x16x32_bf16 v[98:101], v[146:149], v[170:173], v[98:101]
	v_mfma_f32_16x16x32_bf16 v[86:89], v[138:141], v[178:181], v[86:89]
	v_mfma_f32_16x16x32_bf16 v[82:85], v[146:149], v[178:181], v[82:85]
	v_mfma_f32_16x16x32_bf16 v[70:73], v[138:141], v[186:189], v[70:73]
	v_mfma_f32_16x16x32_bf16 v[66:69], v[146:149], v[186:189], v[66:69]
	v_mfma_f32_16x16x32_bf16 v[130:133], v[142:145], v[166:169], v[130:133]
	v_mfma_f32_16x16x32_bf16 v[126:129], v[154:157], v[166:169], v[126:129]
	v_mfma_f32_16x16x32_bf16 v[102:105], v[142:145], v[174:177], v[102:105]
	v_mfma_f32_16x16x32_bf16 v[98:101], v[154:157], v[174:177], v[98:101]
	v_mfma_f32_16x16x32_bf16 v[86:89], v[142:145], v[182:185], v[86:89]
	v_mfma_f32_16x16x32_bf16 v[82:85], v[154:157], v[182:185], v[82:85]
	v_mfma_f32_16x16x32_bf16 v[70:73], v[142:145], v[210:213], v[70:73]
	v_mfma_f32_16x16x32_bf16 v[66:69], v[154:157], v[210:213], v[66:69]
	s_setprio 0
	s_barrier
	s_add_i32 s30, s53, s40
	v_lshl_add_u64 v[196:197], v[196:197], 0, s[94:95]
	s_mov_b32 m0, s30
	ds_read_b128 v[162:165], v214 offset:49152
	ds_read_b128 v[166:169], v214 offset:50176
	ds_read_b128 v[170:173], v214 offset:51200
	ds_read_b128 v[174:177], v214 offset:52224
	ds_read_b128 v[178:181], v214 offset:53248
	ds_read_b128 v[182:185], v214 offset:54272
	ds_read_b128 v[186:189], v214 offset:55296
	ds_read_b128 v[210:213], v214 offset:56320
	global_load_lds_dwordx4 v[196:197], off
	s_add_i32 m0, s30, 0x2000
	s_add_u32 s28, s28, 0x40080
	v_lshl_add_u64 v[196:197], v[198:199], 0, s[94:95]
	s_addc_u32 s29, s29, 0
	s_add_i32 s30, s54, s40
	global_load_lds_dwordx4 v[196:197], off
	v_lshl_add_u64 v[196:197], s[28:29], 0, v[192:193]
	s_mov_b32 m0, s30
	s_nop 0
	global_load_lds_dwordx4 v[196:197], off
	v_lshl_add_u64 v[196:197], s[28:29], 0, v[204:205]
	s_add_i32 m0, s30, 0x2000
	s_nop 0
	global_load_lds_dwordx4 v[196:197], off
	v_lshl_add_u64 v[196:197], v[216:217], 0, s[94:95]
	s_mov_b32 m0, s45
	s_nop 0
	global_load_lds_dwordx4 v[196:197], off
	v_lshl_add_u64 v[196:197], v[220:221], 0, s[94:95]
	s_mov_b32 m0, s46
	s_nop 0
	global_load_lds_dwordx4 v[196:197], off
	s_waitcnt vmcnt(8)
	s_waitcnt lgkmcnt(0)
	s_barrier
	s_setprio 1
	s_waitcnt lgkmcnt(0)
	v_mfma_f32_16x16x32_bf16 v[62:65], v[110:113], v[162:165], v[62:65]
	v_mfma_f32_16x16x32_bf16 v[58:61], v[122:125], v[162:165], v[58:61]
	v_mfma_f32_16x16x32_bf16 v[46:49], v[110:113], v[170:173], v[46:49]
	v_mfma_f32_16x16x32_bf16 v[42:45], v[122:125], v[170:173], v[42:45]
	v_mfma_f32_16x16x32_bf16 v[30:33], v[110:113], v[178:181], v[30:33]
	v_mfma_f32_16x16x32_bf16 v[26:29], v[122:125], v[178:181], v[26:29]
	v_mfma_f32_16x16x32_bf16 v[14:17], v[110:113], v[186:189], v[14:17]
	v_mfma_f32_16x16x32_bf16 v[10:13], v[122:125], v[186:189], v[10:13]
	v_mfma_f32_16x16x32_bf16 v[62:65], v[118:121], v[166:169], v[62:65]
	v_mfma_f32_16x16x32_bf16 v[58:61], v[134:137], v[166:169], v[58:61]
	v_mfma_f32_16x16x32_bf16 v[46:49], v[118:121], v[174:177], v[46:49]
	v_mfma_f32_16x16x32_bf16 v[42:45], v[134:137], v[174:177], v[42:45]
	v_mfma_f32_16x16x32_bf16 v[30:33], v[118:121], v[182:185], v[30:33]
	v_mfma_f32_16x16x32_bf16 v[26:29], v[134:137], v[182:185], v[26:29]
	v_mfma_f32_16x16x32_bf16 v[14:17], v[118:121], v[210:213], v[14:17]
	v_mfma_f32_16x16x32_bf16 v[10:13], v[134:137], v[210:213], v[10:13]
	v_mfma_f32_16x16x32_bf16 v[54:57], v[138:141], v[162:165], v[54:57]
	v_mfma_f32_16x16x32_bf16 v[50:53], v[146:149], v[162:165], v[50:53]
	v_mfma_f32_16x16x32_bf16 v[38:41], v[138:141], v[170:173], v[38:41]
	v_mfma_f32_16x16x32_bf16 v[34:37], v[146:149], v[170:173], v[34:37]
	v_mfma_f32_16x16x32_bf16 v[22:25], v[138:141], v[178:181], v[22:25]
	v_mfma_f32_16x16x32_bf16 v[18:21], v[146:149], v[178:181], v[18:21]
	v_mfma_f32_16x16x32_bf16 v[6:9], v[138:141], v[186:189], v[6:9]
	v_mfma_f32_16x16x32_bf16 v[2:5], v[146:149], v[186:189], v[2:5]
	v_mfma_f32_16x16x32_bf16 v[54:57], v[142:145], v[166:169], v[54:57]
	v_mfma_f32_16x16x32_bf16 v[50:53], v[154:157], v[166:169], v[50:53]
	v_mfma_f32_16x16x32_bf16 v[38:41], v[142:145], v[174:177], v[38:41]
	v_mfma_f32_16x16x32_bf16 v[34:37], v[154:157], v[174:177], v[34:37]
	v_mfma_f32_16x16x32_bf16 v[22:25], v[142:145], v[182:185], v[22:25]
	v_mfma_f32_16x16x32_bf16 v[18:21], v[154:157], v[182:185], v[18:21]
	v_mfma_f32_16x16x32_bf16 v[6:9], v[142:145], v[210:213], v[6:9]
	v_mfma_f32_16x16x32_bf16 v[2:5], v[154:157], v[210:213], v[2:5]
	s_setprio 0
	s_barrier
	s_add_i32 s52, s52, 2
	s_add_u32 s4, s4, 0x100
	s_addc_u32 s5, s5, 0
	s_add_u32 s50, s50, 0x100
	s_addc_u32 s51, s51, 0
	s_cmp_gt_u32 s52, 13
	s_cbranch_scc0 .LBB0_1096
	s_and_b64 vcc, exec, s[14:15]
	s_cbranch_vccz .LBB0_1099
	s_barrier

.LBB0_1180:
	s_add_u32 s26, s24, 0xfffc0080
	s_addc_u32 s27, s25, -1
	s_add_i32 s55, 0, 0x10000
	s_cmp_eq_u32 s54, 12
	s_cselect_b32 s29, s17, s27
	s_cselect_b32 s28, s50, s26
	v_add_u32_e32 v150, s55, v1
	s_cselect_b32 s27, s15, s53
	s_cselect_b32 s26, s51, s52
	s_add_i32 s58, 0, 0x14000
	ds_read_b128 v[142:145], v150
	ds_read_b128 v[146:149], v150 offset:1024
	ds_read_b128 v[154:157], v150 offset:2048
	ds_read_b128 v[158:161], v150 offset:3072
	v_add_u32_e32 v150, s58, v1
	ds_read_b128 v[162:165], v150
	ds_read_b128 v[166:169], v150 offset:1024
	ds_read_b128 v[170:173], v150 offset:2048
	ds_read_b128 v[174:177], v150 offset:3072
	v_lshl_add_u64 v[150:151], s[24:25], 0, v[138:139]
	s_add_i32 m0, s40, 0xc000
	ds_read_b128 v[178:181], v152
	ds_read_b128 v[182:185], v152 offset:1024
	ds_read_b128 v[186:189], v152 offset:2048
	ds_read_b128 v[190:193], v152 offset:3072
	ds_read_b128 v[204:207], v152 offset:4096
	ds_read_b128 v[208:211], v152 offset:5120
	ds_read_b128 v[212:215], v152 offset:6144
	ds_read_b128 v[228:231], v152 offset:7168
	global_load_lds_dwordx4 v[150:151], off
	v_lshl_add_u64 v[150:151], s[24:25], 0, v[140:141]
	s_add_i32 m0, s40, 0xe000
	s_nop 0
	global_load_lds_dwordx4 v[150:151], off
	s_waitcnt vmcnt(8)
	s_waitcnt lgkmcnt(0)
	s_barrier
	s_setprio 1
	s_waitcnt lgkmcnt(0)
	v_mfma_f32_16x16x32_bf16 v[126:129], v[142:145], v[178:181], v[126:129]
	v_mfma_f32_16x16x32_bf16 v[122:125], v[154:157], v[178:181], v[122:125]
	v_mfma_f32_16x16x32_bf16 v[110:113], v[142:145], v[186:189], v[110:113]
	v_mfma_f32_16x16x32_bf16 v[106:109], v[154:157], v[186:189], v[106:109]
	v_mfma_f32_16x16x32_bf16 v[94:97], v[142:145], v[204:207], v[94:97]
	v_mfma_f32_16x16x32_bf16 v[90:93], v[154:157], v[204:207], v[90:93]
	v_mfma_f32_16x16x32_bf16 v[78:81], v[142:145], v[212:215], v[78:81]
	v_mfma_f32_16x16x32_bf16 v[74:77], v[154:157], v[212:215], v[74:77]
	v_mfma_f32_16x16x32_bf16 v[126:129], v[146:149], v[182:185], v[126:129]
	v_mfma_f32_16x16x32_bf16 v[122:125], v[158:161], v[182:185], v[122:125]
	v_mfma_f32_16x16x32_bf16 v[110:113], v[146:149], v[190:193], v[110:113]
	v_mfma_f32_16x16x32_bf16 v[106:109], v[158:161], v[190:193], v[106:109]
	v_mfma_f32_16x16x32_bf16 v[94:97], v[146:149], v[208:211], v[94:97]
	v_mfma_f32_16x16x32_bf16 v[90:93], v[158:161], v[208:211], v[90:93]
	v_mfma_f32_16x16x32_bf16 v[78:81], v[146:149], v[228:231], v[78:81]
	v_mfma_f32_16x16x32_bf16 v[74:77], v[158:161], v[228:231], v[74:77]
	v_mfma_f32_16x16x32_bf16 v[118:121], v[162:165], v[178:181], v[118:121]
	v_mfma_f32_16x16x32_bf16 v[114:117], v[170:173], v[178:181], v[114:117]
	v_mfma_f32_16x16x32_bf16 v[102:105], v[162:165], v[186:189], v[102:105]
	v_mfma_f32_16x16x32_bf16 v[98:101], v[170:173], v[186:189], v[98:101]
	v_mfma_f32_16x16x32_bf16 v[86:89], v[162:165], v[204:207], v[86:89]
	v_mfma_f32_16x16x32_bf16 v[82:85], v[170:173], v[204:207], v[82:85]
	v_mfma_f32_16x16x32_bf16 v[70:73], v[162:165], v[212:215], v[70:73]
	v_mfma_f32_16x16x32_bf16 v[66:69], v[170:173], v[212:215], v[66:69]
	v_mfma_f32_16x16x32_bf16 v[118:121], v[166:169], v[182:185], v[118:121]
	v_mfma_f32_16x16x32_bf16 v[114:117], v[174:177], v[182:185], v[114:117]
	v_mfma_f32_16x16x32_bf16 v[102:105], v[166:169], v[190:193], v[102:105]
	v_mfma_f32_16x16x32_bf16 v[98:101], v[174:177], v[190:193], v[98:101]
	v_mfma_f32_16x16x32_bf16 v[86:89], v[166:169], v[208:211], v[86:89]
	v_mfma_f32_16x16x32_bf16 v[82:85], v[174:177], v[208:211], v[82:85]
	v_mfma_f32_16x16x32_bf16 v[70:73], v[166:169], v[228:231], v[70:73]
	v_mfma_f32_16x16x32_bf16 v[66:69], v[174:177], v[228:231], v[66:69]
	s_setprio 0
	s_barrier
	s_add_i32 s55, s55, s39
	v_lshl_add_u64 v[150:151], s[26:27], 0, v[134:135]
	s_mov_b32 m0, s55
	ds_read_b128 v[178:181], v152 offset:16384
	ds_read_b128 v[182:185], v152 offset:17408
	ds_read_b128 v[186:189], v152 offset:18432
	ds_read_b128 v[190:193], v152 offset:19456
	ds_read_b128 v[204:207], v152 offset:20480
	ds_read_b128 v[208:211], v152 offset:21504
	ds_read_b128 v[212:215], v152 offset:22528
	ds_read_b128 v[228:231], v152 offset:23552
	global_load_lds_dwordx4 v[150:151], off
	s_add_i32 m0, s55, 0x2000
	s_add_u32 s56, s26, 0x40000
	v_lshl_add_u64 v[194:195], s[26:27], 0, v[130:131]
	s_addc_u32 s57, s27, 0
	s_add_i32 s55, s58, s39
	global_load_lds_dwordx4 v[194:195], off
	v_lshl_add_u64 v[196:197], s[56:57], 0, v[134:135]
	s_mov_b32 m0, s55
	v_lshl_add_u64 v[198:199], s[28:29], 0, v[132:133]
	global_load_lds_dwordx4 v[196:197], off
	v_lshl_add_u64 v[196:197], s[56:57], 0, v[130:131]
	s_add_i32 m0, s55, 0x2000
	s_nop 0
	global_load_lds_dwordx4 v[196:197], off
	v_lshl_add_u64 v[196:197], s[28:29], 0, v[136:137]
	s_mov_b32 m0, s40
	s_nop 0
	global_load_lds_dwordx4 v[196:197], off
	s_mov_b32 m0, s41
	s_nop 0
	global_load_lds_dwordx4 v[198:199], off
	s_waitcnt vmcnt(8)
	s_waitcnt lgkmcnt(0)
	s_barrier
	s_setprio 1
	s_waitcnt lgkmcnt(0)
	v_mfma_f32_16x16x32_bf16 v[62:65], v[142:145], v[178:181], v[62:65]
	v_mfma_f32_16x16x32_bf16 v[58:61], v[154:157], v[178:181], v[58:61]
	v_mfma_f32_16x16x32_bf16 v[46:49], v[142:145], v[186:189], v[46:49]
	v_mfma_f32_16x16x32_bf16 v[42:45], v[154:157], v[186:189], v[42:45]
	v_mfma_f32_16x16x32_bf16 v[30:33], v[142:145], v[204:207], v[30:33]
	v_mfma_f32_16x16x32_bf16 v[26:29], v[154:157], v[204:207], v[26:29]
	v_mfma_f32_16x16x32_bf16 v[14:17], v[142:145], v[212:215], v[14:17]
	v_mfma_f32_16x16x32_bf16 v[10:13], v[154:157], v[212:215], v[10:13]
	v_mfma_f32_16x16x32_bf16 v[62:65], v[146:149], v[182:185], v[62:65]
	v_mfma_f32_16x16x32_bf16 v[58:61], v[158:161], v[182:185], v[58:61]
	v_mfma_f32_16x16x32_bf16 v[46:49], v[146:149], v[190:193], v[46:49]
	v_mfma_f32_16x16x32_bf16 v[42:45], v[158:161], v[190:193], v[42:45]
	v_mfma_f32_16x16x32_bf16 v[30:33], v[146:149], v[208:211], v[30:33]
	v_mfma_f32_16x16x32_bf16 v[26:29], v[158:161], v[208:211], v[26:29]
	v_mfma_f32_16x16x32_bf16 v[14:17], v[146:149], v[228:231], v[14:17]
	v_mfma_f32_16x16x32_bf16 v[10:13], v[158:161], v[228:231], v[10:13]
	v_mfma_f32_16x16x32_bf16 v[54:57], v[162:165], v[178:181], v[54:57]
	v_mfma_f32_16x16x32_bf16 v[50:53], v[170:173], v[178:181], v[50:53]
	v_mfma_f32_16x16x32_bf16 v[38:41], v[162:165], v[186:189], v[38:41]
	v_mfma_f32_16x16x32_bf16 v[34:37], v[170:173], v[186:189], v[34:37]
	v_mfma_f32_16x16x32_bf16 v[22:25], v[162:165], v[204:207], v[22:25]
	v_mfma_f32_16x16x32_bf16 v[18:21], v[170:173], v[204:207], v[18:21]
	v_mfma_f32_16x16x32_bf16 v[6:9], v[162:165], v[212:215], v[6:9]
	v_mfma_f32_16x16x32_bf16 v[2:5], v[170:173], v[212:215], v[2:5]
	v_mfma_f32_16x16x32_bf16 v[54:57], v[166:169], v[182:185], v[54:57]
	v_mfma_f32_16x16x32_bf16 v[50:53], v[174:177], v[182:185], v[50:53]
	v_mfma_f32_16x16x32_bf16 v[38:41], v[166:169], v[190:193], v[38:41]
	v_mfma_f32_16x16x32_bf16 v[34:37], v[174:177], v[190:193], v[34:37]
	v_mfma_f32_16x16x32_bf16 v[22:25], v[166:169], v[208:211], v[22:25]
	v_mfma_f32_16x16x32_bf16 v[18:21], v[174:177], v[208:211], v[18:21]
	v_mfma_f32_16x16x32_bf16 v[6:9], v[166:169], v[228:231], v[6:9]
	v_mfma_f32_16x16x32_bf16 v[2:5], v[174:177], v[228:231], v[2:5]
	s_setprio 0
	s_barrier
	s_add_i32 s55, 0, 0x18000
	v_add_u32_e32 v153, s55, v1
	s_add_i32 s56, 0, 0x1c000
	ds_read_b128 v[142:145], v153
	ds_read_b128 v[146:149], v153 offset:1024
	ds_read_b128 v[154:157], v153 offset:2048
	ds_read_b128 v[158:161], v153 offset:3072
	v_add_u32_e32 v153, s56, v1
	ds_read_b128 v[162:165], v153
	ds_read_b128 v[166:169], v153 offset:1024
	ds_read_b128 v[170:173], v153 offset:2048
	ds_read_b128 v[174:177], v153 offset:3072
	s_add_u32 s28, s28, 0x40000
	s_addc_u32 s29, s29, 0
	s_mov_b32 m0, s42
	v_lshl_add_u64 v[216:217], s[28:29], 0, v[136:137]
	ds_read_b128 v[178:181], v152 offset:32768
	ds_read_b128 v[182:185], v152 offset:33792
	ds_read_b128 v[186:189], v152 offset:34816
	ds_read_b128 v[190:193], v152 offset:35840
	ds_read_b128 v[204:207], v152 offset:36864
	ds_read_b128 v[208:211], v152 offset:37888
	ds_read_b128 v[212:215], v152 offset:38912
	ds_read_b128 v[228:231], v152 offset:39936
	global_load_lds_dwordx4 v[216:217], off
	v_lshl_add_u64 v[216:217], s[28:29], 0, v[132:133]
	s_mov_b32 m0, s43
	s_nop 0
	global_load_lds_dwordx4 v[216:217], off
	s_waitcnt vmcnt(8)
	s_waitcnt lgkmcnt(0)
	s_barrier
	s_setprio 1
	s_waitcnt lgkmcnt(0)
	v_mfma_f32_16x16x32_bf16 v[126:129], v[142:145], v[178:181], v[126:129]
	v_mfma_f32_16x16x32_bf16 v[122:125], v[154:157], v[178:181], v[122:125]
	v_mfma_f32_16x16x32_bf16 v[110:113], v[142:145], v[186:189], v[110:113]
	v_mfma_f32_16x16x32_bf16 v[106:109], v[154:157], v[186:189], v[106:109]
	v_mfma_f32_16x16x32_bf16 v[94:97], v[142:145], v[204:207], v[94:97]
	v_mfma_f32_16x16x32_bf16 v[90:93], v[154:157], v[204:207], v[90:93]
	v_mfma_f32_16x16x32_bf16 v[78:81], v[142:145], v[212:215], v[78:81]
	v_mfma_f32_16x16x32_bf16 v[74:77], v[154:157], v[212:215], v[74:77]
	v_mfma_f32_16x16x32_bf16 v[126:129], v[146:149], v[182:185], v[126:129]
	v_mfma_f32_16x16x32_bf16 v[122:125], v[158:161], v[182:185], v[122:125]
	v_mfma_f32_16x16x32_bf16 v[110:113], v[146:149], v[190:193], v[110:113]
	v_mfma_f32_16x16x32_bf16 v[106:109], v[158:161], v[190:193], v[106:109]
	v_mfma_f32_16x16x32_bf16 v[94:97], v[146:149], v[208:211], v[94:97]
	v_mfma_f32_16x16x32_bf16 v[90:93], v[158:161], v[208:211], v[90:93]
	v_mfma_f32_16x16x32_bf16 v[78:81], v[146:149], v[228:231], v[78:81]
	v_mfma_f32_16x16x32_bf16 v[74:77], v[158:161], v[228:231], v[74:77]
	v_mfma_f32_16x16x32_bf16 v[118:121], v[162:165], v[178:181], v[118:121]
	v_mfma_f32_16x16x32_bf16 v[114:117], v[170:173], v[178:181], v[114:117]
	v_mfma_f32_16x16x32_bf16 v[102:105], v[162:165], v[186:189], v[102:105]
	v_mfma_f32_16x16x32_bf16 v[98:101], v[170:173], v[186:189], v[98:101]
	v_mfma_f32_16x16x32_bf16 v[86:89], v[162:165], v[204:207], v[86:89]
	v_mfma_f32_16x16x32_bf16 v[82:85], v[170:173], v[204:207], v[82:85]
	v_mfma_f32_16x16x32_bf16 v[70:73], v[162:165], v[212:215], v[70:73]
	v_mfma_f32_16x16x32_bf16 v[66:69], v[170:173], v[212:215], v[66:69]
	v_mfma_f32_16x16x32_bf16 v[118:121], v[166:169], v[182:185], v[118:121]
	v_mfma_f32_16x16x32_bf16 v[114:117], v[174:177], v[182:185], v[114:117]
	v_mfma_f32_16x16x32_bf16 v[102:105], v[166:169], v[190:193], v[102:105]
	v_mfma_f32_16x16x32_bf16 v[98:101], v[174:177], v[190:193], v[98:101]
	v_mfma_f32_16x16x32_bf16 v[86:89], v[166:169], v[208:211], v[86:89]
	v_mfma_f32_16x16x32_bf16 v[82:85], v[174:177], v[208:211], v[82:85]
	v_mfma_f32_16x16x32_bf16 v[70:73], v[166:169], v[228:231], v[70:73]
	v_mfma_f32_16x16x32_bf16 v[66:69], v[174:177], v[228:231], v[66:69]
	s_setprio 0
	s_barrier
	s_add_i32 s28, s55, s39
	v_lshl_add_u64 v[150:151], v[150:151], 0, s[94:95]
	s_mov_b32 m0, s28
	ds_read_b128 v[178:181], v152 offset:49152
	ds_read_b128 v[182:185], v152 offset:50176
	ds_read_b128 v[186:189], v152 offset:51200
	ds_read_b128 v[190:193], v152 offset:52224
	ds_read_b128 v[204:207], v152 offset:53248
	ds_read_b128 v[208:211], v152 offset:54272
	ds_read_b128 v[212:215], v152 offset:55296
	ds_read_b128 v[228:231], v152 offset:56320
	global_load_lds_dwordx4 v[150:151], off
	s_add_i32 m0, s28, 0x2000
	s_add_u32 s26, s26, 0x40080
	v_lshl_add_u64 v[150:151], v[194:195], 0, s[94:95]
	s_addc_u32 s27, s27, 0
	s_add_i32 s28, s56, s39
	global_load_lds_dwordx4 v[150:151], off
	v_lshl_add_u64 v[150:151], s[26:27], 0, v[134:135]
	s_mov_b32 m0, s28
	s_nop 0
	global_load_lds_dwordx4 v[150:151], off
	v_lshl_add_u64 v[150:151], s[26:27], 0, v[130:131]
	s_add_i32 m0, s28, 0x2000
	s_nop 0
	global_load_lds_dwordx4 v[150:151], off
	v_lshl_add_u64 v[150:151], v[196:197], 0, s[94:95]
	s_mov_b32 m0, s47
	s_nop 0
	global_load_lds_dwordx4 v[150:151], off
	v_lshl_add_u64 v[150:151], v[198:199], 0, s[94:95]
	s_mov_b32 m0, s48
	s_nop 0
	global_load_lds_dwordx4 v[150:151], off
	s_waitcnt vmcnt(8)
	s_waitcnt lgkmcnt(0)
	s_barrier
	s_setprio 1
	s_waitcnt lgkmcnt(0)
	v_mfma_f32_16x16x32_bf16 v[62:65], v[142:145], v[178:181], v[62:65]
	v_mfma_f32_16x16x32_bf16 v[58:61], v[154:157], v[178:181], v[58:61]
	v_mfma_f32_16x16x32_bf16 v[46:49], v[142:145], v[186:189], v[46:49]
	v_mfma_f32_16x16x32_bf16 v[42:45], v[154:157], v[186:189], v[42:45]
	v_mfma_f32_16x16x32_bf16 v[30:33], v[142:145], v[204:207], v[30:33]
	v_mfma_f32_16x16x32_bf16 v[26:29], v[154:157], v[204:207], v[26:29]
	v_mfma_f32_16x16x32_bf16 v[14:17], v[142:145], v[212:215], v[14:17]
	v_mfma_f32_16x16x32_bf16 v[10:13], v[154:157], v[212:215], v[10:13]
	v_mfma_f32_16x16x32_bf16 v[62:65], v[146:149], v[182:185], v[62:65]
	v_mfma_f32_16x16x32_bf16 v[58:61], v[158:161], v[182:185], v[58:61]
	v_mfma_f32_16x16x32_bf16 v[46:49], v[146:149], v[190:193], v[46:49]
	v_mfma_f32_16x16x32_bf16 v[42:45], v[158:161], v[190:193], v[42:45]
	v_mfma_f32_16x16x32_bf16 v[30:33], v[146:149], v[208:211], v[30:33]
	v_mfma_f32_16x16x32_bf16 v[26:29], v[158:161], v[208:211], v[26:29]
	v_mfma_f32_16x16x32_bf16 v[14:17], v[146:149], v[228:231], v[14:17]
	v_mfma_f32_16x16x32_bf16 v[10:13], v[158:161], v[228:231], v[10:13]
	v_mfma_f32_16x16x32_bf16 v[54:57], v[162:165], v[178:181], v[54:57]
	v_mfma_f32_16x16x32_bf16 v[50:53], v[170:173], v[178:181], v[50:53]
	v_mfma_f32_16x16x32_bf16 v[38:41], v[162:165], v[186:189], v[38:41]
	v_mfma_f32_16x16x32_bf16 v[34:37], v[170:173], v[186:189], v[34:37]
	v_mfma_f32_16x16x32_bf16 v[22:25], v[162:165], v[204:207], v[22:25]
	v_mfma_f32_16x16x32_bf16 v[18:21], v[170:173], v[204:207], v[18:21]
	v_mfma_f32_16x16x32_bf16 v[6:9], v[162:165], v[212:215], v[6:9]
	v_mfma_f32_16x16x32_bf16 v[2:5], v[170:173], v[212:215], v[2:5]
	v_mfma_f32_16x16x32_bf16 v[54:57], v[166:169], v[182:185], v[54:57]
	v_mfma_f32_16x16x32_bf16 v[50:53], v[174:177], v[182:185], v[50:53]
	v_mfma_f32_16x16x32_bf16 v[38:41], v[166:169], v[190:193], v[38:41]
	v_mfma_f32_16x16x32_bf16 v[34:37], v[174:177], v[190:193], v[34:37]
	v_mfma_f32_16x16x32_bf16 v[22:25], v[166:169], v[208:211], v[22:25]
	v_mfma_f32_16x16x32_bf16 v[18:21], v[174:177], v[208:211], v[18:21]
	v_mfma_f32_16x16x32_bf16 v[6:9], v[166:169], v[228:231], v[6:9]
	v_mfma_f32_16x16x32_bf16 v[2:5], v[174:177], v[228:231], v[2:5]
	s_setprio 0
	s_barrier
	s_add_i32 s54, s54, 2
	s_add_u32 s24, s24, 0x100
	s_addc_u32 s25, s25, 0
	s_add_u32 s52, s52, 0x100
	s_addc_u32 s53, s53, 0
	s_cmp_gt_u32 s54, 13
	s_cbranch_scc0 .LBB0_1180
	s_and_b64 vcc, exec, s[12:13]
	s_cbranch_vccz .LBB0_1183
	s_barrier

.LBB0_1263:
	s_add_u32 s20, s18, 0x100
	s_addc_u32 s21, s19, 0
	s_add_i32 s53, 0, 0x10000
	s_cmp_eq_u32 s52, 40
	s_cselect_b32 s25, s5, s21
	s_cselect_b32 s24, s4, s20
	s_cselect_b32 s23, s17, s51
	s_cselect_b32 s22, s16, s50
	s_add_i32 s54, 0, 0x14000
	v_add_u32_e32 v134, s53, v1
	v_add_u32_e32 v154, s54, v1
	ds_read_b128 v[110:113], v134
	ds_read_b128 v[118:121], v134 offset:1024
	ds_read_b128 v[122:125], v134 offset:2048
	ds_read_b128 v[134:137], v134 offset:3072
	ds_read_b128 v[138:141], v154
	ds_read_b128 v[142:145], v154 offset:1024
	ds_read_b128 v[146:149], v154 offset:2048
	ds_read_b128 v[154:157], v154 offset:3072
	v_lshl_add_u64 v[196:197], s[18:19], 0, v[206:207]
	s_add_i32 m0, s35, 0xc000
	ds_read_b128 v[162:165], v214
	ds_read_b128 v[166:169], v214 offset:1024
	ds_read_b128 v[170:173], v214 offset:2048
	ds_read_b128 v[174:177], v214 offset:3072
	ds_read_b128 v[178:181], v214 offset:4096
	ds_read_b128 v[182:185], v214 offset:5120
	ds_read_b128 v[186:189], v214 offset:6144
	ds_read_b128 v[210:213], v214 offset:7168
	global_load_lds_dwordx4 v[196:197], off
	v_lshl_add_u64 v[196:197], s[18:19], 0, v[208:209]
	s_add_i32 m0, s35, 0xe000
	s_nop 0
	global_load_lds_dwordx4 v[196:197], off
	s_waitcnt vmcnt(8)
	s_waitcnt lgkmcnt(0)
	s_barrier
	s_setprio 1
	s_waitcnt lgkmcnt(0)
	v_mfma_f32_16x16x32_bf16 v[158:161], v[110:113], v[162:165], v[158:161]
	v_mfma_f32_16x16x32_bf16 v[150:153], v[122:125], v[162:165], v[150:153]
	v_mfma_f32_16x16x32_bf16 v[114:117], v[110:113], v[170:173], v[114:117]
	v_mfma_f32_16x16x32_bf16 v[106:109], v[122:125], v[170:173], v[106:109]
	v_mfma_f32_16x16x32_bf16 v[94:97], v[110:113], v[178:181], v[94:97]
	v_mfma_f32_16x16x32_bf16 v[90:93], v[122:125], v[178:181], v[90:93]
	v_mfma_f32_16x16x32_bf16 v[78:81], v[110:113], v[186:189], v[78:81]
	v_mfma_f32_16x16x32_bf16 v[74:77], v[122:125], v[186:189], v[74:77]
	v_mfma_f32_16x16x32_bf16 v[158:161], v[118:121], v[166:169], v[158:161]
	v_mfma_f32_16x16x32_bf16 v[150:153], v[134:137], v[166:169], v[150:153]
	v_mfma_f32_16x16x32_bf16 v[114:117], v[118:121], v[174:177], v[114:117]
	v_mfma_f32_16x16x32_bf16 v[106:109], v[134:137], v[174:177], v[106:109]
	v_mfma_f32_16x16x32_bf16 v[94:97], v[118:121], v[182:185], v[94:97]
	v_mfma_f32_16x16x32_bf16 v[90:93], v[134:137], v[182:185], v[90:93]
	v_mfma_f32_16x16x32_bf16 v[78:81], v[118:121], v[210:213], v[78:81]
	v_mfma_f32_16x16x32_bf16 v[74:77], v[134:137], v[210:213], v[74:77]
	v_mfma_f32_16x16x32_bf16 v[130:133], v[138:141], v[162:165], v[130:133]
	v_mfma_f32_16x16x32_bf16 v[126:129], v[146:149], v[162:165], v[126:129]
	v_mfma_f32_16x16x32_bf16 v[102:105], v[138:141], v[170:173], v[102:105]
	v_mfma_f32_16x16x32_bf16 v[98:101], v[146:149], v[170:173], v[98:101]
	v_mfma_f32_16x16x32_bf16 v[86:89], v[138:141], v[178:181], v[86:89]
	v_mfma_f32_16x16x32_bf16 v[82:85], v[146:149], v[178:181], v[82:85]
	v_mfma_f32_16x16x32_bf16 v[70:73], v[138:141], v[186:189], v[70:73]
	v_mfma_f32_16x16x32_bf16 v[66:69], v[146:149], v[186:189], v[66:69]
	v_mfma_f32_16x16x32_bf16 v[130:133], v[142:145], v[166:169], v[130:133]
	v_mfma_f32_16x16x32_bf16 v[126:129], v[154:157], v[166:169], v[126:129]
	v_mfma_f32_16x16x32_bf16 v[102:105], v[142:145], v[174:177], v[102:105]
	v_mfma_f32_16x16x32_bf16 v[98:101], v[154:157], v[174:177], v[98:101]
	v_mfma_f32_16x16x32_bf16 v[86:89], v[142:145], v[182:185], v[86:89]
	v_mfma_f32_16x16x32_bf16 v[82:85], v[154:157], v[182:185], v[82:85]
	v_mfma_f32_16x16x32_bf16 v[70:73], v[142:145], v[210:213], v[70:73]
	v_mfma_f32_16x16x32_bf16 v[66:69], v[154:157], v[210:213], v[66:69]
	s_setprio 0
	s_barrier
	s_add_i32 s18, s53, s34
	v_lshl_add_u64 v[196:197], s[22:23], 0, v[192:193]
	s_mov_b32 m0, s18
	ds_read_b128 v[162:165], v214 offset:16384
	ds_read_b128 v[166:169], v214 offset:17408
	ds_read_b128 v[170:173], v214 offset:18432
	ds_read_b128 v[174:177], v214 offset:19456
	ds_read_b128 v[178:181], v214 offset:20480
	ds_read_b128 v[182:185], v214 offset:21504
	ds_read_b128 v[186:189], v214 offset:22528
	ds_read_b128 v[210:213], v214 offset:23552
	global_load_lds_dwordx4 v[196:197], off
	s_add_i32 m0, s18, 0x2000
	s_add_u32 s18, s22, 0xb0000
	v_lshl_add_u64 v[198:199], s[22:23], 0, v[204:205]
	s_addc_u32 s19, s23, 0
	s_add_i32 s53, s54, s34
	global_load_lds_dwordx4 v[198:199], off
	v_lshl_add_u64 v[216:217], s[18:19], 0, v[192:193]
	s_mov_b32 m0, s53
	v_lshl_add_u64 v[220:221], s[24:25], 0, v[194:195]
	global_load_lds_dwordx4 v[216:217], off
	v_lshl_add_u64 v[216:217], s[18:19], 0, v[204:205]
	s_add_i32 m0, s53, 0x2000
	s_nop 0
	global_load_lds_dwordx4 v[216:217], off
	v_lshl_add_u64 v[216:217], s[24:25], 0, v[190:191]
	s_mov_b32 m0, s35
	s_nop 0
	global_load_lds_dwordx4 v[216:217], off
	s_mov_b32 m0, s36
	s_nop 0
	global_load_lds_dwordx4 v[220:221], off
	s_waitcnt vmcnt(8)
	s_waitcnt lgkmcnt(0)
	s_barrier
	s_setprio 1
	s_waitcnt lgkmcnt(0)
	v_mfma_f32_16x16x32_bf16 v[62:65], v[110:113], v[162:165], v[62:65]
	v_mfma_f32_16x16x32_bf16 v[58:61], v[122:125], v[162:165], v[58:61]
	v_mfma_f32_16x16x32_bf16 v[46:49], v[110:113], v[170:173], v[46:49]
	v_mfma_f32_16x16x32_bf16 v[42:45], v[122:125], v[170:173], v[42:45]
	v_mfma_f32_16x16x32_bf16 v[30:33], v[110:113], v[178:181], v[30:33]
	v_mfma_f32_16x16x32_bf16 v[26:29], v[122:125], v[178:181], v[26:29]
	v_mfma_f32_16x16x32_bf16 v[14:17], v[110:113], v[186:189], v[14:17]
	v_mfma_f32_16x16x32_bf16 v[10:13], v[122:125], v[186:189], v[10:13]
	v_mfma_f32_16x16x32_bf16 v[62:65], v[118:121], v[166:169], v[62:65]
	v_mfma_f32_16x16x32_bf16 v[58:61], v[134:137], v[166:169], v[58:61]
	v_mfma_f32_16x16x32_bf16 v[46:49], v[118:121], v[174:177], v[46:49]
	v_mfma_f32_16x16x32_bf16 v[42:45], v[134:137], v[174:177], v[42:45]
	v_mfma_f32_16x16x32_bf16 v[30:33], v[118:121], v[182:185], v[30:33]
	v_mfma_f32_16x16x32_bf16 v[26:29], v[134:137], v[182:185], v[26:29]
	v_mfma_f32_16x16x32_bf16 v[14:17], v[118:121], v[210:213], v[14:17]
	v_mfma_f32_16x16x32_bf16 v[10:13], v[134:137], v[210:213], v[10:13]
	v_mfma_f32_16x16x32_bf16 v[54:57], v[138:141], v[162:165], v[54:57]
	v_mfma_f32_16x16x32_bf16 v[50:53], v[146:149], v[162:165], v[50:53]
	v_mfma_f32_16x16x32_bf16 v[38:41], v[138:141], v[170:173], v[38:41]
	v_mfma_f32_16x16x32_bf16 v[34:37], v[146:149], v[170:173], v[34:37]
	v_mfma_f32_16x16x32_bf16 v[22:25], v[138:141], v[178:181], v[22:25]
	v_mfma_f32_16x16x32_bf16 v[18:21], v[146:149], v[178:181], v[18:21]
	v_mfma_f32_16x16x32_bf16 v[6:9], v[138:141], v[186:189], v[6:9]
	v_mfma_f32_16x16x32_bf16 v[2:5], v[146:149], v[186:189], v[2:5]
	v_mfma_f32_16x16x32_bf16 v[54:57], v[142:145], v[166:169], v[54:57]
	v_mfma_f32_16x16x32_bf16 v[50:53], v[154:157], v[166:169], v[50:53]
	v_mfma_f32_16x16x32_bf16 v[38:41], v[142:145], v[174:177], v[38:41]
	v_mfma_f32_16x16x32_bf16 v[34:37], v[154:157], v[174:177], v[34:37]
	v_mfma_f32_16x16x32_bf16 v[22:25], v[142:145], v[182:185], v[22:25]
	v_mfma_f32_16x16x32_bf16 v[18:21], v[154:157], v[182:185], v[18:21]
	v_mfma_f32_16x16x32_bf16 v[6:9], v[142:145], v[210:213], v[6:9]
	v_mfma_f32_16x16x32_bf16 v[2:5], v[154:157], v[210:213], v[2:5]
	s_setprio 0
	s_barrier
	s_add_i32 s53, 0, 0x18000
	s_add_i32 s54, 0, 0x1c000
	v_add_u32_e32 v134, s53, v1
	v_add_u32_e32 v154, s54, v1
	ds_read_b128 v[110:113], v134
	ds_read_b128 v[118:121], v134 offset:1024
	ds_read_b128 v[122:125], v134 offset:2048
	ds_read_b128 v[134:137], v134 offset:3072
	ds_read_b128 v[138:141], v154
	ds_read_b128 v[142:145], v154 offset:1024
	ds_read_b128 v[146:149], v154 offset:2048
	ds_read_b128 v[154:157], v154 offset:3072
	s_add_u32 s18, s24, 0xb0000
	s_addc_u32 s19, s25, 0
	s_mov_b32 m0, s37
	v_lshl_add_u64 v[222:223], s[18:19], 0, v[190:191]
	ds_read_b128 v[162:165], v214 offset:32768
	ds_read_b128 v[166:169], v214 offset:33792
	ds_read_b128 v[170:173], v214 offset:34816
	ds_read_b128 v[174:177], v214 offset:35840
	ds_read_b128 v[178:181], v214 offset:36864
	ds_read_b128 v[182:185], v214 offset:37888
	ds_read_b128 v[186:189], v214 offset:38912
	ds_read_b128 v[210:213], v214 offset:39936
	global_load_lds_dwordx4 v[222:223], off
	v_lshl_add_u64 v[222:223], s[18:19], 0, v[194:195]
	s_mov_b32 m0, s38
	s_nop 0
	global_load_lds_dwordx4 v[222:223], off
	s_waitcnt vmcnt(8)
	s_waitcnt lgkmcnt(0)
	s_barrier
	s_setprio 1
	s_waitcnt lgkmcnt(0)
	v_mfma_f32_16x16x32_bf16 v[158:161], v[110:113], v[162:165], v[158:161]
	v_mfma_f32_16x16x32_bf16 v[150:153], v[122:125], v[162:165], v[150:153]
	v_mfma_f32_16x16x32_bf16 v[114:117], v[110:113], v[170:173], v[114:117]
	v_mfma_f32_16x16x32_bf16 v[106:109], v[122:125], v[170:173], v[106:109]
	v_mfma_f32_16x16x32_bf16 v[94:97], v[110:113], v[178:181], v[94:97]
	v_mfma_f32_16x16x32_bf16 v[90:93], v[122:125], v[178:181], v[90:93]
	v_mfma_f32_16x16x32_bf16 v[78:81], v[110:113], v[186:189], v[78:81]
	v_mfma_f32_16x16x32_bf16 v[74:77], v[122:125], v[186:189], v[74:77]
	v_mfma_f32_16x16x32_bf16 v[158:161], v[118:121], v[166:169], v[158:161]
	v_mfma_f32_16x16x32_bf16 v[150:153], v[134:137], v[166:169], v[150:153]
	v_mfma_f32_16x16x32_bf16 v[114:117], v[118:121], v[174:177], v[114:117]
	v_mfma_f32_16x16x32_bf16 v[106:109], v[134:137], v[174:177], v[106:109]
	v_mfma_f32_16x16x32_bf16 v[94:97], v[118:121], v[182:185], v[94:97]
	v_mfma_f32_16x16x32_bf16 v[90:93], v[134:137], v[182:185], v[90:93]
	v_mfma_f32_16x16x32_bf16 v[78:81], v[118:121], v[210:213], v[78:81]
	v_mfma_f32_16x16x32_bf16 v[74:77], v[134:137], v[210:213], v[74:77]
	v_mfma_f32_16x16x32_bf16 v[130:133], v[138:141], v[162:165], v[130:133]
	v_mfma_f32_16x16x32_bf16 v[126:129], v[146:149], v[162:165], v[126:129]
	v_mfma_f32_16x16x32_bf16 v[102:105], v[138:141], v[170:173], v[102:105]
	v_mfma_f32_16x16x32_bf16 v[98:101], v[146:149], v[170:173], v[98:101]
	v_mfma_f32_16x16x32_bf16 v[86:89], v[138:141], v[178:181], v[86:89]
	v_mfma_f32_16x16x32_bf16 v[82:85], v[146:149], v[178:181], v[82:85]
	v_mfma_f32_16x16x32_bf16 v[70:73], v[138:141], v[186:189], v[70:73]
	v_mfma_f32_16x16x32_bf16 v[66:69], v[146:149], v[186:189], v[66:69]
	v_mfma_f32_16x16x32_bf16 v[130:133], v[142:145], v[166:169], v[130:133]
	v_mfma_f32_16x16x32_bf16 v[126:129], v[154:157], v[166:169], v[126:129]
	v_mfma_f32_16x16x32_bf16 v[102:105], v[142:145], v[174:177], v[102:105]
	v_mfma_f32_16x16x32_bf16 v[98:101], v[154:157], v[174:177], v[98:101]
	v_mfma_f32_16x16x32_bf16 v[86:89], v[142:145], v[182:185], v[86:89]
	v_mfma_f32_16x16x32_bf16 v[82:85], v[154:157], v[182:185], v[82:85]
	v_mfma_f32_16x16x32_bf16 v[70:73], v[142:145], v[210:213], v[70:73]
	v_mfma_f32_16x16x32_bf16 v[66:69], v[154:157], v[210:213], v[66:69]
	s_setprio 0
	s_barrier
	s_add_i32 s18, s53, s34
	v_lshl_add_u64 v[196:197], v[196:197], 0, s[94:95]
	s_mov_b32 m0, s18
	ds_read_b128 v[162:165], v214 offset:49152
	ds_read_b128 v[166:169], v214 offset:50176
	ds_read_b128 v[170:173], v214 offset:51200
	ds_read_b128 v[174:177], v214 offset:52224
	ds_read_b128 v[178:181], v214 offset:53248
	ds_read_b128 v[182:185], v214 offset:54272
	ds_read_b128 v[186:189], v214 offset:55296
	ds_read_b128 v[210:213], v214 offset:56320
	global_load_lds_dwordx4 v[196:197], off
	s_add_i32 m0, s18, 0x2000
	s_add_u32 s18, s22, 0xb0080
	v_lshl_add_u64 v[196:197], v[198:199], 0, s[94:95]
	s_addc_u32 s19, s23, 0
	s_add_i32 s22, s54, s34
	global_load_lds_dwordx4 v[196:197], off
	v_lshl_add_u64 v[196:197], s[18:19], 0, v[192:193]
	s_mov_b32 m0, s22
	s_nop 0
	global_load_lds_dwordx4 v[196:197], off
	v_lshl_add_u64 v[196:197], s[18:19], 0, v[204:205]
	s_add_i32 m0, s22, 0x2000
	s_nop 0
	global_load_lds_dwordx4 v[196:197], off
	v_lshl_add_u64 v[196:197], v[216:217], 0, s[94:95]
	s_mov_b32 m0, s41
	s_nop 0
	global_load_lds_dwordx4 v[196:197], off
	v_lshl_add_u64 v[196:197], v[220:221], 0, s[94:95]
	s_mov_b32 m0, s42
	s_nop 0
	global_load_lds_dwordx4 v[196:197], off
	s_waitcnt vmcnt(8)
	s_waitcnt lgkmcnt(0)
	s_barrier
	s_setprio 1
	s_waitcnt lgkmcnt(0)
	v_mfma_f32_16x16x32_bf16 v[62:65], v[110:113], v[162:165], v[62:65]
	v_mfma_f32_16x16x32_bf16 v[58:61], v[122:125], v[162:165], v[58:61]
	v_mfma_f32_16x16x32_bf16 v[46:49], v[110:113], v[170:173], v[46:49]
	v_mfma_f32_16x16x32_bf16 v[42:45], v[122:125], v[170:173], v[42:45]
	v_mfma_f32_16x16x32_bf16 v[30:33], v[110:113], v[178:181], v[30:33]
	v_mfma_f32_16x16x32_bf16 v[26:29], v[122:125], v[178:181], v[26:29]
	v_mfma_f32_16x16x32_bf16 v[14:17], v[110:113], v[186:189], v[14:17]
	v_mfma_f32_16x16x32_bf16 v[10:13], v[122:125], v[186:189], v[10:13]
	v_mfma_f32_16x16x32_bf16 v[62:65], v[118:121], v[166:169], v[62:65]
	v_mfma_f32_16x16x32_bf16 v[58:61], v[134:137], v[166:169], v[58:61]
	v_mfma_f32_16x16x32_bf16 v[46:49], v[118:121], v[174:177], v[46:49]
	v_mfma_f32_16x16x32_bf16 v[42:45], v[134:137], v[174:177], v[42:45]
	v_mfma_f32_16x16x32_bf16 v[30:33], v[118:121], v[182:185], v[30:33]
	v_mfma_f32_16x16x32_bf16 v[26:29], v[134:137], v[182:185], v[26:29]
	v_mfma_f32_16x16x32_bf16 v[14:17], v[118:121], v[210:213], v[14:17]
	v_mfma_f32_16x16x32_bf16 v[10:13], v[134:137], v[210:213], v[10:13]
	v_mfma_f32_16x16x32_bf16 v[54:57], v[138:141], v[162:165], v[54:57]
	v_mfma_f32_16x16x32_bf16 v[50:53], v[146:149], v[162:165], v[50:53]
	v_mfma_f32_16x16x32_bf16 v[38:41], v[138:141], v[170:173], v[38:41]
	v_mfma_f32_16x16x32_bf16 v[34:37], v[146:149], v[170:173], v[34:37]
	v_mfma_f32_16x16x32_bf16 v[22:25], v[138:141], v[178:181], v[22:25]
	v_mfma_f32_16x16x32_bf16 v[18:21], v[146:149], v[178:181], v[18:21]
	v_mfma_f32_16x16x32_bf16 v[6:9], v[138:141], v[186:189], v[6:9]
	v_mfma_f32_16x16x32_bf16 v[2:5], v[146:149], v[186:189], v[2:5]
	v_mfma_f32_16x16x32_bf16 v[54:57], v[142:145], v[166:169], v[54:57]
	v_mfma_f32_16x16x32_bf16 v[50:53], v[154:157], v[166:169], v[50:53]
	v_mfma_f32_16x16x32_bf16 v[38:41], v[142:145], v[174:177], v[38:41]
	v_mfma_f32_16x16x32_bf16 v[34:37], v[154:157], v[174:177], v[34:37]
	v_mfma_f32_16x16x32_bf16 v[22:25], v[142:145], v[182:185], v[22:25]
	v_mfma_f32_16x16x32_bf16 v[18:21], v[154:157], v[182:185], v[18:21]
	v_mfma_f32_16x16x32_bf16 v[6:9], v[142:145], v[210:213], v[6:9]
	v_mfma_f32_16x16x32_bf16 v[2:5], v[154:157], v[210:213], v[2:5]
	s_setprio 0
	s_barrier
	s_add_i32 s52, s52, 2
	s_add_u32 s50, s50, 0x100
	s_addc_u32 s51, s51, 0
	s_cmp_gt_u32 s52, 41
	s_mov_b64 s[18:19], s[20:21]
	s_cbranch_scc0 .LBB0_1263
	s_and_b64 vcc, exec, s[14:15]
	s_cbranch_vccz .LBB0_1266
	s_barrier
